# K-loops: no per-segment priority flips; trailing (younger) half at s_setprio 1 for the whole K-loop (static priority), merged waits, on top of P0 item pipeline
# baseline (speedup 1.0000x reference)
.LBB0_445:
	s_ashr_i32 s45, s44, 31
	s_lshl_b64 s[46:47], s[44:45], 21
	s_add_u32 s46, s29, s46
	s_addc_u32 s47, s31, s47
	s_and_b64 s[48:49], s[0:1], exec
	s_cselect_b32 s3, s47, s5
	s_cselect_b32 s8, s46, s4
	s_ashr_i32 s39, s38, 31
	s_lshl_b64 s[48:49], s[38:39], 21
	s_add_u32 s48, s25, s48
	s_addc_u32 s49, s27, s49
	s_and_b64 s[52:53], s[0:1], exec
	s_cselect_b32 s39, s49, s51
	s_cselect_b32 s45, s48, s50
	s_add_u32 s4, s4, 0x100080
	s_addc_u32 s5, s5, 0
	s_add_u32 s63, s50, 0x100
	v_mov_b32_e32 v2, 0
	s_addc_u32 s65, s51, 0
	s_mov_b32 s68, -2
	v_mov_b32_e32 v3, v2
	s_waitcnt lgkmcnt(0)
	v_mov_b32_e32 v4, v2
	v_mov_b32_e32 v5, v2
	v_mov_b32_e32 v6, v2
	v_mov_b32_e32 v7, v2
	v_mov_b32_e32 v8, v2
	v_mov_b32_e32 v9, v2
	v_mov_b32_e32 v18, v2
	v_mov_b32_e32 v19, v2
	v_mov_b32_e32 v20, v2
	v_mov_b32_e32 v21, v2
	v_mov_b32_e32 v22, v2
	v_mov_b32_e32 v23, v2
	v_mov_b32_e32 v24, v2
	v_mov_b32_e32 v25, v2
	v_mov_b32_e32 v34, v2
	v_mov_b32_e32 v35, v2
	v_mov_b32_e32 v36, v2
	v_mov_b32_e32 v37, v2
	v_mov_b32_e32 v38, v2
	v_mov_b32_e32 v39, v2
	v_mov_b32_e32 v40, v2
	v_mov_b32_e32 v41, v2
	s_waitcnt vmcnt(0)
	v_mov_b32_e32 v50, v2
	v_mov_b32_e32 v51, v2
	v_mov_b32_e32 v52, v2
	v_mov_b32_e32 v53, v2
	v_mov_b32_e32 v54, v2
	v_mov_b32_e32 v55, v2
	v_mov_b32_e32 v56, v2
	v_mov_b32_e32 v57, v2
	v_mov_b32_e32 v10, v2
	v_mov_b32_e32 v11, v2
	v_mov_b32_e32 v12, v2
	v_mov_b32_e32 v13, v2
	v_mov_b32_e32 v14, v2
	v_mov_b32_e32 v15, v2
	v_mov_b32_e32 v16, v2
	v_mov_b32_e32 v17, v2
	v_mov_b32_e32 v26, v2
	v_mov_b32_e32 v27, v2
	v_mov_b32_e32 v28, v2
	v_mov_b32_e32 v29, v2
	v_mov_b32_e32 v30, v2
	v_mov_b32_e32 v31, v2
	v_mov_b32_e32 v32, v2
	v_mov_b32_e32 v33, v2
	v_mov_b32_e32 v42, v2
	v_mov_b32_e32 v43, v2
	v_mov_b32_e32 v44, v2
	v_mov_b32_e32 v45, v2
	v_mov_b32_e32 v46, v2
	v_mov_b32_e32 v47, v2
	v_mov_b32_e32 v48, v2
	v_mov_b32_e32 v49, v2
	v_mov_b32_e32 v58, v2
	v_mov_b32_e32 v59, v2
	v_mov_b32_e32 v60, v2
	v_mov_b32_e32 v61, v2
	v_mov_b32_e32 v62, v2
	v_mov_b32_e32 v63, v2
	v_mov_b32_e32 v64, v2
	v_mov_b32_e32 v65, v2
	v_mov_b32_e32 v66, v2
	v_mov_b32_e32 v67, v2
	v_mov_b32_e32 v68, v2
	v_mov_b32_e32 v69, v2
	v_mov_b32_e32 v70, v2
	v_mov_b32_e32 v71, v2
	v_mov_b32_e32 v72, v2
	v_mov_b32_e32 v73, v2
	v_mov_b32_e32 v82, v2
	v_mov_b32_e32 v83, v2
	v_mov_b32_e32 v84, v2
	v_mov_b32_e32 v85, v2
	v_mov_b32_e32 v86, v2
	v_mov_b32_e32 v87, v2
	v_mov_b32_e32 v88, v2
	v_mov_b32_e32 v89, v2
	v_mov_b32_e32 v98, v2
	v_mov_b32_e32 v99, v2
	v_mov_b32_e32 v100, v2
	v_mov_b32_e32 v101, v2
	v_mov_b32_e32 v102, v2
	v_mov_b32_e32 v103, v2
	v_mov_b32_e32 v104, v2
	v_mov_b32_e32 v105, v2
	v_mov_b32_e32 v114, v2
	v_mov_b32_e32 v115, v2
	v_mov_b32_e32 v116, v2
	v_mov_b32_e32 v117, v2
	v_mov_b32_e32 v118, v2
	v_mov_b32_e32 v119, v2
	v_mov_b32_e32 v120, v2
	v_mov_b32_e32 v121, v2
	v_mov_b32_e32 v74, v2
	v_mov_b32_e32 v75, v2
	v_mov_b32_e32 v76, v2
	v_mov_b32_e32 v77, v2
	v_mov_b32_e32 v78, v2
	v_mov_b32_e32 v79, v2
	v_mov_b32_e32 v80, v2
	v_mov_b32_e32 v81, v2
	v_mov_b32_e32 v90, v2
	v_mov_b32_e32 v91, v2
	v_mov_b32_e32 v92, v2
	v_mov_b32_e32 v93, v2
	v_mov_b32_e32 v94, v2
	v_mov_b32_e32 v95, v2
	v_mov_b32_e32 v96, v2
	v_mov_b32_e32 v97, v2
	v_mov_b32_e32 v106, v2
	v_mov_b32_e32 v107, v2
	v_mov_b32_e32 v108, v2
	v_mov_b32_e32 v109, v2
	v_mov_b32_e32 v110, v2
	v_mov_b32_e32 v111, v2
	v_mov_b32_e32 v112, v2
	v_mov_b32_e32 v113, v2
	v_mov_b32_e32 v122, v2
	v_mov_b32_e32 v123, v2
	v_mov_b32_e32 v124, v2
	v_mov_b32_e32 v125, v2
	v_mov_b32_e32 v126, v2
	v_mov_b32_e32 v127, v2
	v_mov_b32_e32 v128, v2
	v_mov_b32_e32 v129, v2
	s_and_b64 vcc, exec, s[20:21]
	s_cbranch_vccnz .Lsp_lead_7
	s_setprio 1
.Lsp_lead_7:
.LBB0_446:
	ds_read_b128 v[148:151], v165
	ds_read_b128 v[174:177], v165 offset:1024
	ds_read_b128 v[180:183], v165 offset:2048
	ds_read_b128 v[184:187], v165 offset:3072
	ds_read_b128 v[188:191], v169
	ds_read_b128 v[192:195], v169 offset:1024
	ds_read_b128 v[196:199], v169 offset:2048
	ds_read_b128 v[200:203], v169 offset:3072
	s_add_u32 s50, s4, 0xfff00080
	s_addc_u32 s51, s5, -1
	s_cmp_eq_u32 s68, 60
	s_cselect_b32 s53, s3, s51
	s_cselect_b32 s52, s8, s50
	s_cselect_b32 s51, s39, s65
	s_cselect_b32 s50, s45, s63
	v_lshl_add_u64 v[154:155], s[4:5], 0, v[140:141]
	s_add_i32 m0, s7, 0xc000
	ds_read_b128 v[204:207], v173
	ds_read_b128 v[208:211], v173 offset:1024
	ds_read_b128 v[212:215], v173 offset:2048
	ds_read_b128 v[216:219], v173 offset:3072
	ds_read_b128 v[220:223], v173 offset:4096
	ds_read_b128 v[224:227], v173 offset:5120
	ds_read_b128 v[228:231], v173 offset:6144
	ds_read_b128 v[236:239], v173 offset:7168
	global_load_lds_dwordx4 v[154:155], off
	v_lshl_add_u64 v[154:155], s[4:5], 0, v[142:143]
	s_add_i32 m0, s7, 0xe000
	s_nop 0
	global_load_lds_dwordx4 v[154:155], off
	s_waitcnt vmcnt(8) lgkmcnt(0)
	s_barrier
	v_mfma_f32_16x16x32_bf16 v[126:129], v[148:151], v[204:207], v[126:129]
	v_mfma_f32_16x16x32_bf16 v[122:125], v[180:183], v[204:207], v[122:125]
	v_mfma_f32_16x16x32_bf16 v[110:113], v[148:151], v[212:215], v[110:113]
	v_mfma_f32_16x16x32_bf16 v[106:109], v[180:183], v[212:215], v[106:109]
	v_mfma_f32_16x16x32_bf16 v[94:97], v[148:151], v[220:223], v[94:97]
	v_mfma_f32_16x16x32_bf16 v[90:93], v[180:183], v[220:223], v[90:93]
	v_mfma_f32_16x16x32_bf16 v[78:81], v[148:151], v[228:231], v[78:81]
	v_mfma_f32_16x16x32_bf16 v[74:77], v[180:183], v[228:231], v[74:77]
	v_mfma_f32_16x16x32_bf16 v[126:129], v[174:177], v[208:211], v[126:129]
	v_mfma_f32_16x16x32_bf16 v[122:125], v[184:187], v[208:211], v[122:125]
	v_mfma_f32_16x16x32_bf16 v[110:113], v[174:177], v[216:219], v[110:113]
	v_mfma_f32_16x16x32_bf16 v[106:109], v[184:187], v[216:219], v[106:109]
	v_mfma_f32_16x16x32_bf16 v[94:97], v[174:177], v[224:227], v[94:97]
	v_mfma_f32_16x16x32_bf16 v[90:93], v[184:187], v[224:227], v[90:93]
	v_mfma_f32_16x16x32_bf16 v[78:81], v[174:177], v[236:239], v[78:81]
	v_mfma_f32_16x16x32_bf16 v[74:77], v[184:187], v[236:239], v[74:77]
	v_mfma_f32_16x16x32_bf16 v[118:121], v[188:191], v[204:207], v[118:121]
	v_mfma_f32_16x16x32_bf16 v[114:117], v[196:199], v[204:207], v[114:117]
	v_mfma_f32_16x16x32_bf16 v[102:105], v[188:191], v[212:215], v[102:105]
	v_mfma_f32_16x16x32_bf16 v[98:101], v[196:199], v[212:215], v[98:101]
	v_mfma_f32_16x16x32_bf16 v[86:89], v[188:191], v[220:223], v[86:89]
	v_mfma_f32_16x16x32_bf16 v[82:85], v[196:199], v[220:223], v[82:85]
	v_mfma_f32_16x16x32_bf16 v[70:73], v[188:191], v[228:231], v[70:73]
	v_mfma_f32_16x16x32_bf16 v[66:69], v[196:199], v[228:231], v[66:69]
	v_mfma_f32_16x16x32_bf16 v[118:121], v[192:195], v[208:211], v[118:121]
	v_mfma_f32_16x16x32_bf16 v[114:117], v[200:203], v[208:211], v[114:117]
	v_mfma_f32_16x16x32_bf16 v[102:105], v[192:195], v[216:219], v[102:105]
	v_mfma_f32_16x16x32_bf16 v[98:101], v[200:203], v[216:219], v[98:101]
	v_mfma_f32_16x16x32_bf16 v[86:89], v[192:195], v[224:227], v[86:89]
	v_mfma_f32_16x16x32_bf16 v[82:85], v[200:203], v[224:227], v[82:85]
	v_mfma_f32_16x16x32_bf16 v[70:73], v[192:195], v[236:239], v[70:73]
	v_mfma_f32_16x16x32_bf16 v[66:69], v[200:203], v[236:239], v[66:69]
	s_barrier
	s_add_i32 s69, s59, s35
	v_lshl_add_u64 v[154:155], s[50:51], 0, v[132:133]
	s_mov_b32 m0, s69
	ds_read_b128 v[204:207], v173 offset:16384
	ds_read_b128 v[208:211], v173 offset:17408
	ds_read_b128 v[212:215], v173 offset:18432
	ds_read_b128 v[216:219], v173 offset:19456
	ds_read_b128 v[220:223], v173 offset:20480
	ds_read_b128 v[224:227], v173 offset:21504
	ds_read_b128 v[228:231], v173 offset:22528
	ds_read_b128 v[236:239], v173 offset:23552
	global_load_lds_dwordx4 v[154:155], off
	s_add_i32 m0, s69, 0x2000
	s_add_u32 s70, s50, 0x100000
	v_lshl_add_u64 v[158:159], s[50:51], 0, v[136:137]
	s_addc_u32 s71, s51, 0
	s_add_i32 s69, s60, s35
	global_load_lds_dwordx4 v[158:159], off
	v_lshl_add_u64 v[162:163], s[70:71], 0, v[132:133]
	s_mov_b32 m0, s69
	v_lshl_add_u64 v[166:167], s[52:53], 0, v[134:135]
	global_load_lds_dwordx4 v[162:163], off
	v_lshl_add_u64 v[162:163], s[70:71], 0, v[136:137]
	s_add_i32 m0, s69, 0x2000
	s_nop 0
	global_load_lds_dwordx4 v[162:163], off
	v_lshl_add_u64 v[162:163], s[52:53], 0, v[130:131]
	s_mov_b32 m0, s7
	s_nop 0
	global_load_lds_dwordx4 v[162:163], off
	s_mov_b32 m0, s37
	s_nop 0
	global_load_lds_dwordx4 v[166:167], off
	s_waitcnt vmcnt(8) lgkmcnt(0)
	s_barrier
	v_mfma_f32_16x16x32_bf16 v[62:65], v[148:151], v[204:207], v[62:65]
	v_mfma_f32_16x16x32_bf16 v[58:61], v[180:183], v[204:207], v[58:61]
	v_mfma_f32_16x16x32_bf16 v[46:49], v[148:151], v[212:215], v[46:49]
	v_mfma_f32_16x16x32_bf16 v[42:45], v[180:183], v[212:215], v[42:45]
	v_mfma_f32_16x16x32_bf16 v[30:33], v[148:151], v[220:223], v[30:33]
	v_mfma_f32_16x16x32_bf16 v[26:29], v[180:183], v[220:223], v[26:29]
	v_mfma_f32_16x16x32_bf16 v[14:17], v[148:151], v[228:231], v[14:17]
	v_mfma_f32_16x16x32_bf16 v[10:13], v[180:183], v[228:231], v[10:13]
	v_mfma_f32_16x16x32_bf16 v[62:65], v[174:177], v[208:211], v[62:65]
	v_mfma_f32_16x16x32_bf16 v[58:61], v[184:187], v[208:211], v[58:61]
	v_mfma_f32_16x16x32_bf16 v[46:49], v[174:177], v[216:219], v[46:49]
	v_mfma_f32_16x16x32_bf16 v[42:45], v[184:187], v[216:219], v[42:45]
	v_mfma_f32_16x16x32_bf16 v[30:33], v[174:177], v[224:227], v[30:33]
	v_mfma_f32_16x16x32_bf16 v[26:29], v[184:187], v[224:227], v[26:29]
	v_mfma_f32_16x16x32_bf16 v[14:17], v[174:177], v[236:239], v[14:17]
	v_mfma_f32_16x16x32_bf16 v[10:13], v[184:187], v[236:239], v[10:13]
	v_mfma_f32_16x16x32_bf16 v[54:57], v[188:191], v[204:207], v[54:57]
	v_mfma_f32_16x16x32_bf16 v[50:53], v[196:199], v[204:207], v[50:53]
	v_mfma_f32_16x16x32_bf16 v[38:41], v[188:191], v[212:215], v[38:41]
	v_mfma_f32_16x16x32_bf16 v[34:37], v[196:199], v[212:215], v[34:37]
	v_mfma_f32_16x16x32_bf16 v[22:25], v[188:191], v[220:223], v[22:25]
	v_mfma_f32_16x16x32_bf16 v[18:21], v[196:199], v[220:223], v[18:21]
	v_mfma_f32_16x16x32_bf16 v[6:9], v[188:191], v[228:231], v[6:9]
	v_mfma_f32_16x16x32_bf16 v[2:5], v[196:199], v[228:231], v[2:5]
	v_mfma_f32_16x16x32_bf16 v[54:57], v[192:195], v[208:211], v[54:57]
	v_mfma_f32_16x16x32_bf16 v[50:53], v[200:203], v[208:211], v[50:53]
	v_mfma_f32_16x16x32_bf16 v[38:41], v[192:195], v[216:219], v[38:41]
	v_mfma_f32_16x16x32_bf16 v[34:37], v[200:203], v[216:219], v[34:37]
	v_mfma_f32_16x16x32_bf16 v[22:25], v[192:195], v[224:227], v[22:25]
	v_mfma_f32_16x16x32_bf16 v[18:21], v[200:203], v[224:227], v[18:21]
	v_mfma_f32_16x16x32_bf16 v[6:9], v[192:195], v[236:239], v[6:9]
	v_mfma_f32_16x16x32_bf16 v[2:5], v[200:203], v[236:239], v[2:5]
	s_barrier
	s_add_i32 s69, 0, 0x18000
	v_add_u32_e32 v139, s69, v161
	s_add_i32 s70, 0, 0x1c000
	ds_read_b128 v[148:151], v139
	ds_read_b128 v[174:177], v139 offset:1024
	ds_read_b128 v[180:183], v139 offset:2048
	ds_read_b128 v[184:187], v139 offset:3072
	v_add_u32_e32 v139, s70, v161
	ds_read_b128 v[188:191], v139
	ds_read_b128 v[192:195], v139 offset:1024
	ds_read_b128 v[196:199], v139 offset:2048
	ds_read_b128 v[200:203], v139 offset:3072
	s_add_u32 s52, s52, 0x100000
	s_addc_u32 s53, s53, 0
	s_mov_b32 m0, s41
	v_lshl_add_u64 v[170:171], s[52:53], 0, v[130:131]
	ds_read_b128 v[204:207], v173 offset:32768
	ds_read_b128 v[208:211], v173 offset:33792
	ds_read_b128 v[212:215], v173 offset:34816
	ds_read_b128 v[216:219], v173 offset:35840
	ds_read_b128 v[220:223], v173 offset:36864
	ds_read_b128 v[224:227], v173 offset:37888
	ds_read_b128 v[228:231], v173 offset:38912
	ds_read_b128 v[236:239], v173 offset:39936
	global_load_lds_dwordx4 v[170:171], off
	v_lshl_add_u64 v[170:171], s[52:53], 0, v[134:135]
	s_mov_b32 m0, s43
	s_nop 0
	global_load_lds_dwordx4 v[170:171], off
	s_waitcnt vmcnt(8) lgkmcnt(0)
	s_barrier
	v_mfma_f32_16x16x32_bf16 v[126:129], v[148:151], v[204:207], v[126:129]
	v_mfma_f32_16x16x32_bf16 v[122:125], v[180:183], v[204:207], v[122:125]
	v_mfma_f32_16x16x32_bf16 v[110:113], v[148:151], v[212:215], v[110:113]
	v_mfma_f32_16x16x32_bf16 v[106:109], v[180:183], v[212:215], v[106:109]
	v_mfma_f32_16x16x32_bf16 v[94:97], v[148:151], v[220:223], v[94:97]
	v_mfma_f32_16x16x32_bf16 v[90:93], v[180:183], v[220:223], v[90:93]
	v_mfma_f32_16x16x32_bf16 v[78:81], v[148:151], v[228:231], v[78:81]
	v_mfma_f32_16x16x32_bf16 v[74:77], v[180:183], v[228:231], v[74:77]
	v_mfma_f32_16x16x32_bf16 v[126:129], v[174:177], v[208:211], v[126:129]
	v_mfma_f32_16x16x32_bf16 v[122:125], v[184:187], v[208:211], v[122:125]
	v_mfma_f32_16x16x32_bf16 v[110:113], v[174:177], v[216:219], v[110:113]
	v_mfma_f32_16x16x32_bf16 v[106:109], v[184:187], v[216:219], v[106:109]
	v_mfma_f32_16x16x32_bf16 v[94:97], v[174:177], v[224:227], v[94:97]
	v_mfma_f32_16x16x32_bf16 v[90:93], v[184:187], v[224:227], v[90:93]
	v_mfma_f32_16x16x32_bf16 v[78:81], v[174:177], v[236:239], v[78:81]
	v_mfma_f32_16x16x32_bf16 v[74:77], v[184:187], v[236:239], v[74:77]
	v_mfma_f32_16x16x32_bf16 v[118:121], v[188:191], v[204:207], v[118:121]
	v_mfma_f32_16x16x32_bf16 v[114:117], v[196:199], v[204:207], v[114:117]
	v_mfma_f32_16x16x32_bf16 v[102:105], v[188:191], v[212:215], v[102:105]
	v_mfma_f32_16x16x32_bf16 v[98:101], v[196:199], v[212:215], v[98:101]
	v_mfma_f32_16x16x32_bf16 v[86:89], v[188:191], v[220:223], v[86:89]
	v_mfma_f32_16x16x32_bf16 v[82:85], v[196:199], v[220:223], v[82:85]
	v_mfma_f32_16x16x32_bf16 v[70:73], v[188:191], v[228:231], v[70:73]
	v_mfma_f32_16x16x32_bf16 v[66:69], v[196:199], v[228:231], v[66:69]
	v_mfma_f32_16x16x32_bf16 v[118:121], v[192:195], v[208:211], v[118:121]
	v_mfma_f32_16x16x32_bf16 v[114:117], v[200:203], v[208:211], v[114:117]
	v_mfma_f32_16x16x32_bf16 v[102:105], v[192:195], v[216:219], v[102:105]
	v_mfma_f32_16x16x32_bf16 v[98:101], v[200:203], v[216:219], v[98:101]
	v_mfma_f32_16x16x32_bf16 v[86:89], v[192:195], v[224:227], v[86:89]
	v_mfma_f32_16x16x32_bf16 v[82:85], v[200:203], v[224:227], v[82:85]
	v_mfma_f32_16x16x32_bf16 v[70:73], v[192:195], v[236:239], v[70:73]
	v_mfma_f32_16x16x32_bf16 v[66:69], v[200:203], v[236:239], v[66:69]
	s_barrier
	s_add_i32 s52, s69, s35
	v_lshl_add_u64 v[154:155], v[154:155], 0, s[16:17]
	s_mov_b32 m0, s52
	ds_read_b128 v[204:207], v173 offset:49152
	ds_read_b128 v[208:211], v173 offset:50176
	ds_read_b128 v[212:215], v173 offset:51200
	ds_read_b128 v[216:219], v173 offset:52224
	ds_read_b128 v[220:223], v173 offset:53248
	ds_read_b128 v[224:227], v173 offset:54272
	ds_read_b128 v[228:231], v173 offset:55296
	ds_read_b128 v[236:239], v173 offset:56320
	global_load_lds_dwordx4 v[154:155], off
	s_add_i32 m0, s52, 0x2000
	s_add_u32 s50, s50, 0x100080
	v_lshl_add_u64 v[154:155], v[158:159], 0, s[16:17]
	s_addc_u32 s51, s51, 0
	s_add_i32 s52, s70, s35
	global_load_lds_dwordx4 v[154:155], off
	v_lshl_add_u64 v[154:155], s[50:51], 0, v[132:133]
	s_mov_b32 m0, s52
	s_nop 0
	global_load_lds_dwordx4 v[154:155], off
	v_lshl_add_u64 v[154:155], s[50:51], 0, v[136:137]
	s_add_i32 m0, s52, 0x2000
	s_nop 0
	global_load_lds_dwordx4 v[154:155], off
	v_lshl_add_u64 v[154:155], v[162:163], 0, s[16:17]
	s_mov_b32 m0, s57
	s_nop 0
	global_load_lds_dwordx4 v[154:155], off
	v_lshl_add_u64 v[154:155], v[166:167], 0, s[16:17]
	s_mov_b32 m0, s58
	s_nop 0
	global_load_lds_dwordx4 v[154:155], off
	s_waitcnt vmcnt(8) lgkmcnt(0)
	s_barrier
	v_mfma_f32_16x16x32_bf16 v[62:65], v[148:151], v[204:207], v[62:65]
	v_mfma_f32_16x16x32_bf16 v[58:61], v[180:183], v[204:207], v[58:61]
	v_mfma_f32_16x16x32_bf16 v[46:49], v[148:151], v[212:215], v[46:49]
	v_mfma_f32_16x16x32_bf16 v[42:45], v[180:183], v[212:215], v[42:45]
	v_mfma_f32_16x16x32_bf16 v[30:33], v[148:151], v[220:223], v[30:33]
	v_mfma_f32_16x16x32_bf16 v[26:29], v[180:183], v[220:223], v[26:29]
	v_mfma_f32_16x16x32_bf16 v[14:17], v[148:151], v[228:231], v[14:17]
	v_mfma_f32_16x16x32_bf16 v[10:13], v[180:183], v[228:231], v[10:13]
	v_mfma_f32_16x16x32_bf16 v[62:65], v[174:177], v[208:211], v[62:65]
	v_mfma_f32_16x16x32_bf16 v[58:61], v[184:187], v[208:211], v[58:61]
	v_mfma_f32_16x16x32_bf16 v[46:49], v[174:177], v[216:219], v[46:49]
	v_mfma_f32_16x16x32_bf16 v[42:45], v[184:187], v[216:219], v[42:45]
	v_mfma_f32_16x16x32_bf16 v[30:33], v[174:177], v[224:227], v[30:33]
	v_mfma_f32_16x16x32_bf16 v[26:29], v[184:187], v[224:227], v[26:29]
	v_mfma_f32_16x16x32_bf16 v[14:17], v[174:177], v[236:239], v[14:17]
	v_mfma_f32_16x16x32_bf16 v[10:13], v[184:187], v[236:239], v[10:13]
	v_mfma_f32_16x16x32_bf16 v[54:57], v[188:191], v[204:207], v[54:57]
	v_mfma_f32_16x16x32_bf16 v[50:53], v[196:199], v[204:207], v[50:53]
	v_mfma_f32_16x16x32_bf16 v[38:41], v[188:191], v[212:215], v[38:41]
	v_mfma_f32_16x16x32_bf16 v[34:37], v[196:199], v[212:215], v[34:37]
	v_mfma_f32_16x16x32_bf16 v[22:25], v[188:191], v[220:223], v[22:25]
	v_mfma_f32_16x16x32_bf16 v[18:21], v[196:199], v[220:223], v[18:21]
	v_mfma_f32_16x16x32_bf16 v[6:9], v[188:191], v[228:231], v[6:9]
	v_mfma_f32_16x16x32_bf16 v[2:5], v[196:199], v[228:231], v[2:5]
	v_mfma_f32_16x16x32_bf16 v[54:57], v[192:195], v[208:211], v[54:57]
	v_mfma_f32_16x16x32_bf16 v[50:53], v[200:203], v[208:211], v[50:53]
	v_mfma_f32_16x16x32_bf16 v[38:41], v[192:195], v[216:219], v[38:41]
	v_mfma_f32_16x16x32_bf16 v[34:37], v[200:203], v[216:219], v[34:37]
	v_mfma_f32_16x16x32_bf16 v[22:25], v[192:195], v[224:227], v[22:25]
	v_mfma_f32_16x16x32_bf16 v[18:21], v[200:203], v[224:227], v[18:21]
	v_mfma_f32_16x16x32_bf16 v[6:9], v[192:195], v[236:239], v[6:9]
	v_mfma_f32_16x16x32_bf16 v[2:5], v[200:203], v[236:239], v[2:5]
	s_barrier
	s_add_i32 s68, s68, 2
	s_add_u32 s4, s4, 0x100
	s_addc_u32 s5, s5, 0
	s_add_u32 s63, s63, 0x100
	s_addc_u32 s65, s65, 0
	s_cmp_gt_u32 s68, 61
	s_cbranch_scc0 .LBB0_446
	s_setprio 0
	s_and_b64 vcc, exec, s[20:21]
	s_cbranch_vccz .LBB0_449
	s_barrier

.LBB0_667:
	s_ashr_i32 s25, s24, 31
	s_lshl_b64 s[26:27], s[24:25], 21
	s_add_u32 s26, s45, s26
	s_addc_u32 s27, s46, s27
	s_and_b64 s[28:29], s[0:1], exec
	s_cselect_b32 s25, s27, s35
	s_cselect_b32 s61, s26, s34
	s_ashr_i32 s23, s22, 31
	s_lshl_b64 s[28:29], s[22:23], 21
	s_add_u32 s28, s43, s28
	s_addc_u32 s29, s44, s29
	s_and_b64 s[38:39], s[0:1], exec
	s_cselect_b32 s23, s29, s37
	s_cselect_b32 s62, s28, s36
	s_add_u32 s34, s34, 0x100080
	s_addc_u32 s35, s35, 0
	s_add_u32 s63, s36, 0x100
	v_mov_b32_e32 v2, 0
	s_addc_u32 s65, s37, 0
	s_mov_b32 s68, -2
	v_mov_b32_e32 v3, v2
	v_mov_b32_e32 v4, v2
	v_mov_b32_e32 v5, v2
	v_mov_b32_e32 v6, v2
	v_mov_b32_e32 v7, v2
	v_mov_b32_e32 v8, v2
	v_mov_b32_e32 v9, v2
	v_mov_b32_e32 v14, v2
	v_mov_b32_e32 v15, v2
	v_mov_b32_e32 v16, v2
	v_mov_b32_e32 v17, v2
	v_mov_b32_e32 v22, v2
	v_mov_b32_e32 v23, v2
	v_mov_b32_e32 v24, v2
	v_mov_b32_e32 v25, v2
	v_mov_b32_e32 v30, v2
	v_mov_b32_e32 v31, v2
	v_mov_b32_e32 v32, v2
	v_mov_b32_e32 v33, v2
	v_mov_b32_e32 v38, v2
	v_mov_b32_e32 v39, v2
	v_mov_b32_e32 v40, v2
	v_mov_b32_e32 v41, v2
	v_mov_b32_e32 v46, v2
	v_mov_b32_e32 v47, v2
	v_mov_b32_e32 v48, v2
	v_mov_b32_e32 v49, v2
	v_mov_b32_e32 v54, v2
	v_mov_b32_e32 v55, v2
	v_mov_b32_e32 v56, v2
	v_mov_b32_e32 v57, v2
	v_mov_b32_e32 v10, v2
	v_mov_b32_e32 v11, v2
	v_mov_b32_e32 v12, v2
	v_mov_b32_e32 v13, v2
	v_mov_b32_e32 v18, v2
	v_mov_b32_e32 v19, v2
	v_mov_b32_e32 v20, v2
	v_mov_b32_e32 v21, v2
	v_mov_b32_e32 v26, v2
	v_mov_b32_e32 v27, v2
	v_mov_b32_e32 v28, v2
	v_mov_b32_e32 v29, v2
	v_mov_b32_e32 v34, v2
	v_mov_b32_e32 v35, v2
	v_mov_b32_e32 v36, v2
	v_mov_b32_e32 v37, v2
	v_mov_b32_e32 v42, v2
	v_mov_b32_e32 v43, v2
	v_mov_b32_e32 v44, v2
	v_mov_b32_e32 v45, v2
	v_mov_b32_e32 v50, v2
	v_mov_b32_e32 v51, v2
	v_mov_b32_e32 v52, v2
	v_mov_b32_e32 v53, v2
	v_mov_b32_e32 v58, v2
	v_mov_b32_e32 v59, v2
	v_mov_b32_e32 v60, v2
	v_mov_b32_e32 v61, v2
	v_mov_b32_e32 v62, v2
	v_mov_b32_e32 v63, v2
	v_mov_b32_e32 v64, v2
	v_mov_b32_e32 v65, v2
	v_mov_b32_e32 v66, v2
	v_mov_b32_e32 v67, v2
	v_mov_b32_e32 v68, v2
	v_mov_b32_e32 v69, v2
	v_mov_b32_e32 v70, v2
	v_mov_b32_e32 v71, v2
	v_mov_b32_e32 v72, v2
	v_mov_b32_e32 v73, v2
	v_mov_b32_e32 v78, v2
	v_mov_b32_e32 v79, v2
	v_mov_b32_e32 v80, v2
	v_mov_b32_e32 v81, v2
	v_mov_b32_e32 v86, v2
	v_mov_b32_e32 v87, v2
	v_mov_b32_e32 v88, v2
	v_mov_b32_e32 v89, v2
	v_mov_b32_e32 v94, v2
	v_mov_b32_e32 v95, v2
	v_mov_b32_e32 v96, v2
	v_mov_b32_e32 v97, v2
	v_mov_b32_e32 v102, v2
	v_mov_b32_e32 v103, v2
	v_mov_b32_e32 v104, v2
	v_mov_b32_e32 v105, v2
	v_mov_b32_e32 v110, v2
	v_mov_b32_e32 v111, v2
	v_mov_b32_e32 v112, v2
	v_mov_b32_e32 v113, v2
	v_mov_b32_e32 v118, v2
	v_mov_b32_e32 v119, v2
	v_mov_b32_e32 v120, v2
	v_mov_b32_e32 v121, v2
	v_mov_b32_e32 v74, v2
	v_mov_b32_e32 v75, v2
	v_mov_b32_e32 v76, v2
	v_mov_b32_e32 v77, v2
	v_mov_b32_e32 v82, v2
	v_mov_b32_e32 v83, v2
	v_mov_b32_e32 v84, v2
	v_mov_b32_e32 v85, v2
	v_mov_b32_e32 v90, v2
	v_mov_b32_e32 v91, v2
	v_mov_b32_e32 v92, v2
	v_mov_b32_e32 v93, v2
	v_mov_b32_e32 v98, v2
	v_mov_b32_e32 v99, v2
	v_mov_b32_e32 v100, v2
	v_mov_b32_e32 v101, v2
	v_mov_b32_e32 v106, v2
	v_mov_b32_e32 v107, v2
	v_mov_b32_e32 v108, v2
	v_mov_b32_e32 v109, v2
	v_mov_b32_e32 v114, v2
	v_mov_b32_e32 v115, v2
	v_mov_b32_e32 v116, v2
	v_mov_b32_e32 v117, v2
	v_mov_b32_e32 v122, v2
	v_mov_b32_e32 v123, v2
	v_mov_b32_e32 v124, v2
	v_mov_b32_e32 v125, v2
	v_mov_b32_e32 v126, v2
	v_mov_b32_e32 v127, v2
	v_mov_b32_e32 v128, v2
	v_mov_b32_e32 v129, v2
	s_and_b64 vcc, exec, s[12:13]
	s_cbranch_vccnz .Lsp_lead_6
	s_setprio 1
.Lsp_lead_6:
.LBB0_668:
	ds_read_b128 v[154:157], v151
	ds_read_b128 v[158:161], v151 offset:1024
	ds_read_b128 v[162:165], v151 offset:2048
	ds_read_b128 v[166:169], v151 offset:3072
	ds_read_b128 v[170:173], v152
	ds_read_b128 v[174:177], v152 offset:1024
	ds_read_b128 v[178:181], v152 offset:2048
	ds_read_b128 v[182:185], v152 offset:3072
	s_add_u32 s36, s34, 0xfff00080
	s_addc_u32 s37, s35, -1
	s_cmp_eq_u32 s68, 60
	s_cselect_b32 s39, s25, s37
	s_cselect_b32 s38, s61, s36
	s_cselect_b32 s37, s23, s65
	s_cselect_b32 s36, s62, s63
	v_lshl_add_u64 v[148:149], s[34:35], 0, v[140:141]
	s_add_i32 m0, s31, 0xc000
	ds_read_b128 v[186:189], v153
	ds_read_b128 v[190:193], v153 offset:1024
	ds_read_b128 v[194:197], v153 offset:2048
	ds_read_b128 v[198:201], v153 offset:3072
	ds_read_b128 v[202:205], v153 offset:4096
	ds_read_b128 v[206:209], v153 offset:5120
	ds_read_b128 v[210:213], v153 offset:6144
	ds_read_b128 v[214:217], v153 offset:7168
	global_load_lds_dwordx4 v[148:149], off
	v_lshl_add_u64 v[148:149], s[34:35], 0, v[142:143]
	s_add_i32 m0, s31, 0xe000
	s_nop 0
	global_load_lds_dwordx4 v[148:149], off
	s_waitcnt vmcnt(8) lgkmcnt(0)
	s_barrier
	v_mfma_f32_16x16x32_bf16 v[126:129], v[154:157], v[186:189], v[126:129]
	v_mfma_f32_16x16x32_bf16 v[122:125], v[162:165], v[186:189], v[122:125]
	v_mfma_f32_16x16x32_bf16 v[114:117], v[154:157], v[194:197], v[114:117]
	v_mfma_f32_16x16x32_bf16 v[106:109], v[162:165], v[194:197], v[106:109]
	v_mfma_f32_16x16x32_bf16 v[98:101], v[154:157], v[202:205], v[98:101]
	v_mfma_f32_16x16x32_bf16 v[90:93], v[162:165], v[202:205], v[90:93]
	v_mfma_f32_16x16x32_bf16 v[82:85], v[154:157], v[210:213], v[82:85]
	v_mfma_f32_16x16x32_bf16 v[74:77], v[162:165], v[210:213], v[74:77]
	v_mfma_f32_16x16x32_bf16 v[126:129], v[158:161], v[190:193], v[126:129]
	v_mfma_f32_16x16x32_bf16 v[122:125], v[166:169], v[190:193], v[122:125]
	v_mfma_f32_16x16x32_bf16 v[114:117], v[158:161], v[198:201], v[114:117]
	v_mfma_f32_16x16x32_bf16 v[106:109], v[166:169], v[198:201], v[106:109]
	v_mfma_f32_16x16x32_bf16 v[98:101], v[158:161], v[206:209], v[98:101]
	v_mfma_f32_16x16x32_bf16 v[90:93], v[166:169], v[206:209], v[90:93]
	v_mfma_f32_16x16x32_bf16 v[82:85], v[158:161], v[214:217], v[82:85]
	v_mfma_f32_16x16x32_bf16 v[74:77], v[166:169], v[214:217], v[74:77]
	v_mfma_f32_16x16x32_bf16 v[118:121], v[170:173], v[186:189], v[118:121]
	v_mfma_f32_16x16x32_bf16 v[110:113], v[178:181], v[186:189], v[110:113]
	v_mfma_f32_16x16x32_bf16 v[102:105], v[170:173], v[194:197], v[102:105]
	v_mfma_f32_16x16x32_bf16 v[94:97], v[178:181], v[194:197], v[94:97]
	v_mfma_f32_16x16x32_bf16 v[86:89], v[170:173], v[202:205], v[86:89]
	v_mfma_f32_16x16x32_bf16 v[78:81], v[178:181], v[202:205], v[78:81]
	v_mfma_f32_16x16x32_bf16 v[70:73], v[170:173], v[210:213], v[70:73]
	v_mfma_f32_16x16x32_bf16 v[66:69], v[178:181], v[210:213], v[66:69]
	v_mfma_f32_16x16x32_bf16 v[118:121], v[174:177], v[190:193], v[118:121]
	v_mfma_f32_16x16x32_bf16 v[110:113], v[182:185], v[190:193], v[110:113]
	v_mfma_f32_16x16x32_bf16 v[102:105], v[174:177], v[198:201], v[102:105]
	v_mfma_f32_16x16x32_bf16 v[94:97], v[182:185], v[198:201], v[94:97]
	v_mfma_f32_16x16x32_bf16 v[86:89], v[174:177], v[206:209], v[86:89]
	v_mfma_f32_16x16x32_bf16 v[78:81], v[182:185], v[206:209], v[78:81]
	v_mfma_f32_16x16x32_bf16 v[70:73], v[174:177], v[214:217], v[70:73]
	v_mfma_f32_16x16x32_bf16 v[66:69], v[182:185], v[214:217], v[66:69]
	s_barrier
	s_add_i32 s69, s54, s47
	v_lshl_add_u64 v[148:149], s[36:37], 0, v[136:137]
	s_mov_b32 m0, s69
	ds_read_b128 v[186:189], v153 offset:16384
	ds_read_b128 v[190:193], v153 offset:17408
	ds_read_b128 v[194:197], v153 offset:18432
	ds_read_b128 v[198:201], v153 offset:19456
	ds_read_b128 v[202:205], v153 offset:20480
	ds_read_b128 v[206:209], v153 offset:21504
	ds_read_b128 v[210:213], v153 offset:22528
	ds_read_b128 v[214:217], v153 offset:23552
	global_load_lds_dwordx4 v[148:149], off
	s_add_i32 m0, s69, 0x2000
	s_add_u32 s70, s36, 0x100000
	v_lshl_add_u64 v[218:219], s[36:37], 0, v[132:133]
	s_addc_u32 s71, s37, 0
	s_add_i32 s69, s55, s47
	global_load_lds_dwordx4 v[218:219], off
	v_lshl_add_u64 v[220:221], s[70:71], 0, v[136:137]
	s_mov_b32 m0, s69
	v_lshl_add_u64 v[222:223], s[38:39], 0, v[134:135]
	global_load_lds_dwordx4 v[220:221], off
	v_lshl_add_u64 v[220:221], s[70:71], 0, v[132:133]
	s_add_i32 m0, s69, 0x2000
	s_nop 0
	global_load_lds_dwordx4 v[220:221], off
	v_lshl_add_u64 v[220:221], s[38:39], 0, v[138:139]
	s_mov_b32 m0, s31
	s_nop 0
	global_load_lds_dwordx4 v[220:221], off
	s_mov_b32 m0, s48
	s_nop 0
	global_load_lds_dwordx4 v[222:223], off
	s_waitcnt vmcnt(8) lgkmcnt(0)
	s_barrier
	v_mfma_f32_16x16x32_bf16 v[62:65], v[154:157], v[186:189], v[62:65]
	v_mfma_f32_16x16x32_bf16 v[58:61], v[162:165], v[186:189], v[58:61]
	v_mfma_f32_16x16x32_bf16 v[50:53], v[154:157], v[194:197], v[50:53]
	v_mfma_f32_16x16x32_bf16 v[42:45], v[162:165], v[194:197], v[42:45]
	v_mfma_f32_16x16x32_bf16 v[34:37], v[154:157], v[202:205], v[34:37]
	v_mfma_f32_16x16x32_bf16 v[26:29], v[162:165], v[202:205], v[26:29]
	v_mfma_f32_16x16x32_bf16 v[18:21], v[154:157], v[210:213], v[18:21]
	v_mfma_f32_16x16x32_bf16 v[10:13], v[162:165], v[210:213], v[10:13]
	v_mfma_f32_16x16x32_bf16 v[62:65], v[158:161], v[190:193], v[62:65]
	v_mfma_f32_16x16x32_bf16 v[58:61], v[166:169], v[190:193], v[58:61]
	v_mfma_f32_16x16x32_bf16 v[50:53], v[158:161], v[198:201], v[50:53]
	v_mfma_f32_16x16x32_bf16 v[42:45], v[166:169], v[198:201], v[42:45]
	v_mfma_f32_16x16x32_bf16 v[34:37], v[158:161], v[206:209], v[34:37]
	v_mfma_f32_16x16x32_bf16 v[26:29], v[166:169], v[206:209], v[26:29]
	v_mfma_f32_16x16x32_bf16 v[18:21], v[158:161], v[214:217], v[18:21]
	v_mfma_f32_16x16x32_bf16 v[10:13], v[166:169], v[214:217], v[10:13]
	v_mfma_f32_16x16x32_bf16 v[54:57], v[170:173], v[186:189], v[54:57]
	v_mfma_f32_16x16x32_bf16 v[46:49], v[178:181], v[186:189], v[46:49]
	v_mfma_f32_16x16x32_bf16 v[38:41], v[170:173], v[194:197], v[38:41]
	v_mfma_f32_16x16x32_bf16 v[30:33], v[178:181], v[194:197], v[30:33]
	v_mfma_f32_16x16x32_bf16 v[22:25], v[170:173], v[202:205], v[22:25]
	v_mfma_f32_16x16x32_bf16 v[14:17], v[178:181], v[202:205], v[14:17]
	v_mfma_f32_16x16x32_bf16 v[6:9], v[170:173], v[210:213], v[6:9]
	v_mfma_f32_16x16x32_bf16 v[2:5], v[178:181], v[210:213], v[2:5]
	v_mfma_f32_16x16x32_bf16 v[54:57], v[174:177], v[190:193], v[54:57]
	v_mfma_f32_16x16x32_bf16 v[46:49], v[182:185], v[190:193], v[46:49]
	v_mfma_f32_16x16x32_bf16 v[38:41], v[174:177], v[198:201], v[38:41]
	v_mfma_f32_16x16x32_bf16 v[30:33], v[182:185], v[198:201], v[30:33]
	v_mfma_f32_16x16x32_bf16 v[22:25], v[174:177], v[206:209], v[22:25]
	v_mfma_f32_16x16x32_bf16 v[14:17], v[182:185], v[206:209], v[14:17]
	v_mfma_f32_16x16x32_bf16 v[6:9], v[174:177], v[214:217], v[6:9]
	v_mfma_f32_16x16x32_bf16 v[2:5], v[182:185], v[214:217], v[2:5]
	s_barrier
	s_add_i32 s69, 0, 0x18000
	s_add_i32 s70, 0, 0x1c000
	v_add_u32_e32 v166, s69, v131
	v_add_u32_e32 v182, s70, v131
	ds_read_b128 v[154:157], v166
	ds_read_b128 v[158:161], v166 offset:1024
	ds_read_b128 v[162:165], v166 offset:2048
	ds_read_b128 v[166:169], v166 offset:3072
	ds_read_b128 v[170:173], v182
	ds_read_b128 v[174:177], v182 offset:1024
	ds_read_b128 v[178:181], v182 offset:2048
	ds_read_b128 v[182:185], v182 offset:3072
	s_add_u32 s38, s38, 0x100000
	s_addc_u32 s39, s39, 0
	s_mov_b32 m0, s49
	v_lshl_add_u64 v[224:225], s[38:39], 0, v[138:139]
	ds_read_b128 v[186:189], v153 offset:32768
	ds_read_b128 v[190:193], v153 offset:33792
	ds_read_b128 v[194:197], v153 offset:34816
	ds_read_b128 v[198:201], v153 offset:35840
	ds_read_b128 v[202:205], v153 offset:36864
	ds_read_b128 v[206:209], v153 offset:37888
	ds_read_b128 v[210:213], v153 offset:38912
	ds_read_b128 v[214:217], v153 offset:39936
	global_load_lds_dwordx4 v[224:225], off
	v_lshl_add_u64 v[224:225], s[38:39], 0, v[134:135]
	s_mov_b32 m0, s50
	s_nop 0
	global_load_lds_dwordx4 v[224:225], off
	s_waitcnt vmcnt(8) lgkmcnt(0)
	s_barrier
	v_mfma_f32_16x16x32_bf16 v[126:129], v[154:157], v[186:189], v[126:129]
	v_mfma_f32_16x16x32_bf16 v[122:125], v[162:165], v[186:189], v[122:125]
	v_mfma_f32_16x16x32_bf16 v[114:117], v[154:157], v[194:197], v[114:117]
	v_mfma_f32_16x16x32_bf16 v[106:109], v[162:165], v[194:197], v[106:109]
	v_mfma_f32_16x16x32_bf16 v[98:101], v[154:157], v[202:205], v[98:101]
	v_mfma_f32_16x16x32_bf16 v[90:93], v[162:165], v[202:205], v[90:93]
	v_mfma_f32_16x16x32_bf16 v[82:85], v[154:157], v[210:213], v[82:85]
	v_mfma_f32_16x16x32_bf16 v[74:77], v[162:165], v[210:213], v[74:77]
	v_mfma_f32_16x16x32_bf16 v[126:129], v[158:161], v[190:193], v[126:129]
	v_mfma_f32_16x16x32_bf16 v[122:125], v[166:169], v[190:193], v[122:125]
	v_mfma_f32_16x16x32_bf16 v[114:117], v[158:161], v[198:201], v[114:117]
	v_mfma_f32_16x16x32_bf16 v[106:109], v[166:169], v[198:201], v[106:109]
	v_mfma_f32_16x16x32_bf16 v[98:101], v[158:161], v[206:209], v[98:101]
	v_mfma_f32_16x16x32_bf16 v[90:93], v[166:169], v[206:209], v[90:93]
	v_mfma_f32_16x16x32_bf16 v[82:85], v[158:161], v[214:217], v[82:85]
	v_mfma_f32_16x16x32_bf16 v[74:77], v[166:169], v[214:217], v[74:77]
	v_mfma_f32_16x16x32_bf16 v[118:121], v[170:173], v[186:189], v[118:121]
	v_mfma_f32_16x16x32_bf16 v[110:113], v[178:181], v[186:189], v[110:113]
	v_mfma_f32_16x16x32_bf16 v[102:105], v[170:173], v[194:197], v[102:105]
	v_mfma_f32_16x16x32_bf16 v[94:97], v[178:181], v[194:197], v[94:97]
	v_mfma_f32_16x16x32_bf16 v[86:89], v[170:173], v[202:205], v[86:89]
	v_mfma_f32_16x16x32_bf16 v[78:81], v[178:181], v[202:205], v[78:81]
	v_mfma_f32_16x16x32_bf16 v[70:73], v[170:173], v[210:213], v[70:73]
	v_mfma_f32_16x16x32_bf16 v[66:69], v[178:181], v[210:213], v[66:69]
	v_mfma_f32_16x16x32_bf16 v[118:121], v[174:177], v[190:193], v[118:121]
	v_mfma_f32_16x16x32_bf16 v[110:113], v[182:185], v[190:193], v[110:113]
	v_mfma_f32_16x16x32_bf16 v[102:105], v[174:177], v[198:201], v[102:105]
	v_mfma_f32_16x16x32_bf16 v[94:97], v[182:185], v[198:201], v[94:97]
	v_mfma_f32_16x16x32_bf16 v[86:89], v[174:177], v[206:209], v[86:89]
	v_mfma_f32_16x16x32_bf16 v[78:81], v[182:185], v[206:209], v[78:81]
	v_mfma_f32_16x16x32_bf16 v[70:73], v[174:177], v[214:217], v[70:73]
	v_mfma_f32_16x16x32_bf16 v[66:69], v[182:185], v[214:217], v[66:69]
	s_barrier
	s_add_i32 s38, s69, s47
	v_lshl_add_u64 v[148:149], v[148:149], 0, s[8:9]
	s_mov_b32 m0, s38
	ds_read_b128 v[186:189], v153 offset:49152
	ds_read_b128 v[190:193], v153 offset:50176
	ds_read_b128 v[194:197], v153 offset:51200
	ds_read_b128 v[198:201], v153 offset:52224
	ds_read_b128 v[202:205], v153 offset:53248
	ds_read_b128 v[206:209], v153 offset:54272
	ds_read_b128 v[210:213], v153 offset:55296
	ds_read_b128 v[214:217], v153 offset:56320
	global_load_lds_dwordx4 v[148:149], off
	s_add_i32 m0, s38, 0x2000
	s_add_u32 s36, s36, 0x100080
	v_lshl_add_u64 v[148:149], v[218:219], 0, s[8:9]
	s_addc_u32 s37, s37, 0
	s_add_i32 s38, s70, s47
	global_load_lds_dwordx4 v[148:149], off
	v_lshl_add_u64 v[148:149], s[36:37], 0, v[136:137]
	s_mov_b32 m0, s38
	s_nop 0
	global_load_lds_dwordx4 v[148:149], off
	v_lshl_add_u64 v[148:149], s[36:37], 0, v[132:133]
	s_add_i32 m0, s38, 0x2000
	s_nop 0
	global_load_lds_dwordx4 v[148:149], off
	v_lshl_add_u64 v[148:149], v[220:221], 0, s[8:9]
	s_mov_b32 m0, s52
	s_nop 0
	global_load_lds_dwordx4 v[148:149], off
	v_lshl_add_u64 v[148:149], v[222:223], 0, s[8:9]
	s_mov_b32 m0, s53
	s_nop 0
	global_load_lds_dwordx4 v[148:149], off
	s_waitcnt vmcnt(8) lgkmcnt(0)
	s_barrier
	v_mfma_f32_16x16x32_bf16 v[62:65], v[154:157], v[186:189], v[62:65]
	v_mfma_f32_16x16x32_bf16 v[58:61], v[162:165], v[186:189], v[58:61]
	v_mfma_f32_16x16x32_bf16 v[50:53], v[154:157], v[194:197], v[50:53]
	v_mfma_f32_16x16x32_bf16 v[42:45], v[162:165], v[194:197], v[42:45]
	v_mfma_f32_16x16x32_bf16 v[34:37], v[154:157], v[202:205], v[34:37]
	v_mfma_f32_16x16x32_bf16 v[26:29], v[162:165], v[202:205], v[26:29]
	v_mfma_f32_16x16x32_bf16 v[18:21], v[154:157], v[210:213], v[18:21]
	v_mfma_f32_16x16x32_bf16 v[10:13], v[162:165], v[210:213], v[10:13]
	v_mfma_f32_16x16x32_bf16 v[62:65], v[158:161], v[190:193], v[62:65]
	v_mfma_f32_16x16x32_bf16 v[58:61], v[166:169], v[190:193], v[58:61]
	v_mfma_f32_16x16x32_bf16 v[50:53], v[158:161], v[198:201], v[50:53]
	v_mfma_f32_16x16x32_bf16 v[42:45], v[166:169], v[198:201], v[42:45]
	v_mfma_f32_16x16x32_bf16 v[34:37], v[158:161], v[206:209], v[34:37]
	v_mfma_f32_16x16x32_bf16 v[26:29], v[166:169], v[206:209], v[26:29]
	v_mfma_f32_16x16x32_bf16 v[18:21], v[158:161], v[214:217], v[18:21]
	v_mfma_f32_16x16x32_bf16 v[10:13], v[166:169], v[214:217], v[10:13]
	v_mfma_f32_16x16x32_bf16 v[54:57], v[170:173], v[186:189], v[54:57]
	v_mfma_f32_16x16x32_bf16 v[46:49], v[178:181], v[186:189], v[46:49]
	v_mfma_f32_16x16x32_bf16 v[38:41], v[170:173], v[194:197], v[38:41]
	v_mfma_f32_16x16x32_bf16 v[30:33], v[178:181], v[194:197], v[30:33]
	v_mfma_f32_16x16x32_bf16 v[22:25], v[170:173], v[202:205], v[22:25]
	v_mfma_f32_16x16x32_bf16 v[14:17], v[178:181], v[202:205], v[14:17]
	v_mfma_f32_16x16x32_bf16 v[6:9], v[170:173], v[210:213], v[6:9]
	v_mfma_f32_16x16x32_bf16 v[2:5], v[178:181], v[210:213], v[2:5]
	v_mfma_f32_16x16x32_bf16 v[54:57], v[174:177], v[190:193], v[54:57]
	v_mfma_f32_16x16x32_bf16 v[46:49], v[182:185], v[190:193], v[46:49]
	v_mfma_f32_16x16x32_bf16 v[38:41], v[174:177], v[198:201], v[38:41]
	v_mfma_f32_16x16x32_bf16 v[30:33], v[182:185], v[198:201], v[30:33]
	v_mfma_f32_16x16x32_bf16 v[22:25], v[174:177], v[206:209], v[22:25]
	v_mfma_f32_16x16x32_bf16 v[14:17], v[182:185], v[206:209], v[14:17]
	v_mfma_f32_16x16x32_bf16 v[6:9], v[174:177], v[214:217], v[6:9]
	v_mfma_f32_16x16x32_bf16 v[2:5], v[182:185], v[214:217], v[2:5]
	s_barrier
	s_add_i32 s68, s68, 2
	s_add_u32 s34, s34, 0x100
	s_addc_u32 s35, s35, 0
	s_add_u32 s63, s63, 0x100
	s_addc_u32 s65, s65, 0
	s_cmp_gt_u32 s68, 61
	s_cbranch_scc0 .LBB0_668
	s_setprio 0
	s_and_b64 vcc, exec, s[12:13]
	s_cbranch_vccz .LBB0_671
	s_barrier

.LBB0_844:
	s_ashr_i32 s49, s48, 31
	s_lshl_b64 s[50:51], s[48:49], 20
	s_add_u32 s50, s43, s50
	s_addc_u32 s51, s62, s51
	s_and_b64 s[52:53], s[0:1], exec
	s_cselect_b32 s49, s51, s3
	s_cselect_b32 s88, s50, s2
	s_ashr_i32 s47, s46, 31
	s_lshl_b64 s[52:53], s[46:47], 20
	s_add_u32 s52, s8, s52
	s_addc_u32 s53, s9, s53
	s_and_b64 s[58:59], s[0:1], exec
	s_cselect_b32 s47, s53, s57
	s_cselect_b32 s89, s52, s56
	s_add_u32 s90, s56, 0x100
	v_mov_b32_e32 v34, 0
	s_addc_u32 s91, s57, 0
	s_mov_b32 s92, -2
	v_mov_b32_e32 v35, v34
	v_mov_b32_e32 v36, v34
	v_mov_b32_e32 v37, v34
	v_mov_b32_e32 v38, v34
	v_mov_b32_e32 v39, v34
	v_mov_b32_e32 v40, v34
	v_mov_b32_e32 v41, v34
	v_mov_b32_e32 v46, v34
	v_mov_b32_e32 v47, v34
	v_mov_b32_e32 v48, v34
	v_mov_b32_e32 v49, v34
	v_mov_b32_e32 v54, v34
	v_mov_b32_e32 v55, v34
	v_mov_b32_e32 v56, v34
	v_mov_b32_e32 v57, v34
	v_mov_b32_e32 v2, v34
	v_mov_b32_e32 v3, v34
	v_mov_b32_e32 v4, v34
	v_mov_b32_e32 v5, v34
	v_mov_b32_e32 v42, v34
	v_mov_b32_e32 v43, v34
	v_mov_b32_e32 v44, v34
	v_mov_b32_e32 v45, v34
	v_mov_b32_e32 v6, v34
	v_mov_b32_e32 v7, v34
	v_mov_b32_e32 v8, v34
	v_mov_b32_e32 v9, v34
	v_mov_b32_e32 v50, v34
	v_mov_b32_e32 v51, v34
	v_mov_b32_e32 v52, v34
	v_mov_b32_e32 v53, v34
	v_mov_b32_e32 v82, v34
	v_mov_b32_e32 v83, v34
	v_mov_b32_e32 v84, v34
	v_mov_b32_e32 v85, v34
	v_mov_b32_e32 v86, v34
	v_mov_b32_e32 v87, v34
	v_mov_b32_e32 v88, v34
	v_mov_b32_e32 v89, v34
	v_mov_b32_e32 v106, v34
	v_mov_b32_e32 v107, v34
	v_mov_b32_e32 v108, v34
	v_mov_b32_e32 v109, v34
	v_mov_b32_e32 v114, v34
	v_mov_b32_e32 v115, v34
	v_mov_b32_e32 v116, v34
	v_mov_b32_e32 v117, v34
	v_mov_b32_e32 v10, v34
	v_mov_b32_e32 v11, v34
	v_mov_b32_e32 v12, v34
	v_mov_b32_e32 v13, v34
	v_mov_b32_e32 v58, v34
	v_mov_b32_e32 v59, v34
	v_mov_b32_e32 v60, v34
	v_mov_b32_e32 v61, v34
	v_mov_b32_e32 v14, v34
	v_mov_b32_e32 v15, v34
	v_mov_b32_e32 v16, v34
	v_mov_b32_e32 v17, v34
	v_mov_b32_e32 v62, v34
	v_mov_b32_e32 v63, v34
	v_mov_b32_e32 v64, v34
	v_mov_b32_e32 v65, v34
	v_mov_b32_e32 v18, v34
	v_mov_b32_e32 v19, v34
	v_mov_b32_e32 v20, v34
	v_mov_b32_e32 v21, v34
	v_mov_b32_e32 v66, v34
	v_mov_b32_e32 v67, v34
	v_mov_b32_e32 v68, v34
	v_mov_b32_e32 v69, v34
	v_mov_b32_e32 v22, v34
	v_mov_b32_e32 v23, v34
	v_mov_b32_e32 v24, v34
	v_mov_b32_e32 v25, v34
	v_mov_b32_e32 v70, v34
	v_mov_b32_e32 v71, v34
	v_mov_b32_e32 v72, v34
	v_mov_b32_e32 v73, v34
	v_mov_b32_e32 v90, v34
	v_mov_b32_e32 v91, v34
	v_mov_b32_e32 v92, v34
	v_mov_b32_e32 v93, v34
	v_mov_b32_e32 v94, v34
	v_mov_b32_e32 v95, v34
	v_mov_b32_e32 v96, v34
	v_mov_b32_e32 v97, v34
	v_mov_b32_e32 v98, v34
	v_mov_b32_e32 v99, v34
	v_mov_b32_e32 v100, v34
	v_mov_b32_e32 v101, v34
	v_mov_b32_e32 v102, v34
	v_mov_b32_e32 v103, v34
	v_mov_b32_e32 v104, v34
	v_mov_b32_e32 v105, v34
	v_mov_b32_e32 v26, v34
	v_mov_b32_e32 v27, v34
	v_mov_b32_e32 v28, v34
	v_mov_b32_e32 v29, v34
	v_mov_b32_e32 v74, v34
	v_mov_b32_e32 v75, v34
	v_mov_b32_e32 v76, v34
	v_mov_b32_e32 v77, v34
	v_mov_b32_e32 v30, v34
	v_mov_b32_e32 v31, v34
	v_mov_b32_e32 v32, v34
	v_mov_b32_e32 v33, v34
	v_mov_b32_e32 v78, v34
	v_mov_b32_e32 v79, v34
	v_mov_b32_e32 v80, v34
	v_mov_b32_e32 v81, v34
	v_mov_b32_e32 v110, v34
	v_mov_b32_e32 v111, v34
	v_mov_b32_e32 v112, v34
	v_mov_b32_e32 v113, v34
	v_mov_b32_e32 v118, v34
	v_mov_b32_e32 v119, v34
	v_mov_b32_e32 v120, v34
	v_mov_b32_e32 v121, v34
	v_mov_b32_e32 v122, v34
	v_mov_b32_e32 v123, v34
	v_mov_b32_e32 v124, v34
	v_mov_b32_e32 v125, v34
	v_mov_b32_e32 v126, v34
	v_mov_b32_e32 v127, v34
	v_mov_b32_e32 v128, v34
	v_mov_b32_e32 v129, v34
	s_and_b64 vcc, exec, s[38:39]
	s_cbranch_vccnz .Lsp_lead_5
	s_setprio 1
.Lsp_lead_5:
.LBB0_845:
	ds_read_b128 v[130:133], v238
	ds_read_b128 v[134:137], v238 offset:1024
	ds_read_b128 v[138:141], v238 offset:2048
	ds_read_b128 v[142:145], v238 offset:3072
	ds_read_b128 v[146:149], v239
	ds_read_b128 v[150:153], v239 offset:1024
	ds_read_b128 v[154:157], v239 offset:2048
	ds_read_b128 v[158:161], v239 offset:3072
	s_add_u32 s56, s2, 0x100
	s_addc_u32 s57, s3, 0
	s_cmp_eq_u32 s92, 28
	s_cselect_b32 s61, s49, s57
	s_cselect_b32 s60, s88, s56
	s_cselect_b32 s59, s47, s91
	s_cselect_b32 s58, s89, s90
	v_lshl_add_u64 v[194:195], s[2:3], 0, v[210:211]
	s_add_i32 m0, s55, 0xc000
	ds_read_b128 v[162:165], v240
	ds_read_b128 v[166:169], v240 offset:1024
	ds_read_b128 v[170:173], v240 offset:2048
	ds_read_b128 v[174:177], v240 offset:3072
	ds_read_b128 v[178:181], v240 offset:4096
	ds_read_b128 v[182:185], v240 offset:5120
	ds_read_b128 v[186:189], v240 offset:6144
	ds_read_b128 v[190:193], v240 offset:7168
	global_load_lds_dwordx4 v[194:195], off
	v_lshl_add_u64 v[194:195], s[2:3], 0, v[212:213]
	s_add_i32 m0, s55, 0xe000
	s_nop 0
	global_load_lds_dwordx4 v[194:195], off
	s_waitcnt vmcnt(8) lgkmcnt(0)
	s_barrier
	v_mfma_i32_16x16x64_i8 v[126:129], v[130:133], v[162:165], v[126:129]
	v_mfma_i32_16x16x64_i8 v[122:125], v[138:141], v[162:165], v[122:125]
	v_mfma_i32_16x16x64_i8 v[118:121], v[130:133], v[170:173], v[118:121]
	v_mfma_i32_16x16x64_i8 v[110:113], v[138:141], v[170:173], v[110:113]
	v_mfma_i32_16x16x64_i8 v[78:81], v[130:133], v[178:181], v[78:81]
	v_mfma_i32_16x16x64_i8 v[30:33], v[138:141], v[178:181], v[30:33]
	v_mfma_i32_16x16x64_i8 v[74:77], v[130:133], v[186:189], v[74:77]
	v_mfma_i32_16x16x64_i8 v[26:29], v[138:141], v[186:189], v[26:29]
	v_mfma_i32_16x16x64_i8 v[126:129], v[134:137], v[166:169], v[126:129]
	v_mfma_i32_16x16x64_i8 v[122:125], v[142:145], v[166:169], v[122:125]
	v_mfma_i32_16x16x64_i8 v[118:121], v[134:137], v[174:177], v[118:121]
	v_mfma_i32_16x16x64_i8 v[110:113], v[142:145], v[174:177], v[110:113]
	v_mfma_i32_16x16x64_i8 v[78:81], v[134:137], v[182:185], v[78:81]
	v_mfma_i32_16x16x64_i8 v[30:33], v[142:145], v[182:185], v[30:33]
	v_mfma_i32_16x16x64_i8 v[74:77], v[134:137], v[190:193], v[74:77]
	v_mfma_i32_16x16x64_i8 v[26:29], v[142:145], v[190:193], v[26:29]
	v_mfma_i32_16x16x64_i8 v[102:105], v[146:149], v[162:165], v[102:105]
	v_mfma_i32_16x16x64_i8 v[98:101], v[154:157], v[162:165], v[98:101]
	v_mfma_i32_16x16x64_i8 v[94:97], v[146:149], v[170:173], v[94:97]
	v_mfma_i32_16x16x64_i8 v[90:93], v[154:157], v[170:173], v[90:93]
	v_mfma_i32_16x16x64_i8 v[70:73], v[146:149], v[178:181], v[70:73]
	v_mfma_i32_16x16x64_i8 v[22:25], v[154:157], v[178:181], v[22:25]
	v_mfma_i32_16x16x64_i8 v[66:69], v[146:149], v[186:189], v[66:69]
	v_mfma_i32_16x16x64_i8 v[18:21], v[154:157], v[186:189], v[18:21]
	v_mfma_i32_16x16x64_i8 v[102:105], v[150:153], v[166:169], v[102:105]
	v_mfma_i32_16x16x64_i8 v[98:101], v[158:161], v[166:169], v[98:101]
	v_mfma_i32_16x16x64_i8 v[94:97], v[150:153], v[174:177], v[94:97]
	v_mfma_i32_16x16x64_i8 v[90:93], v[158:161], v[174:177], v[90:93]
	v_mfma_i32_16x16x64_i8 v[70:73], v[150:153], v[182:185], v[70:73]
	v_mfma_i32_16x16x64_i8 v[22:25], v[158:161], v[182:185], v[22:25]
	v_mfma_i32_16x16x64_i8 v[66:69], v[150:153], v[190:193], v[66:69]
	v_mfma_i32_16x16x64_i8 v[18:21], v[158:161], v[190:193], v[18:21]
	s_barrier
	s_add_i32 s2, s84, s65
	v_lshl_add_u64 v[194:195], s[58:59], 0, v[206:207]
	s_mov_b32 m0, s2
	ds_read_b128 v[162:165], v240 offset:16384
	ds_read_b128 v[166:169], v240 offset:17408
	ds_read_b128 v[170:173], v240 offset:18432
	ds_read_b128 v[174:177], v240 offset:19456
	ds_read_b128 v[178:181], v240 offset:20480
	ds_read_b128 v[182:185], v240 offset:21504
	ds_read_b128 v[186:189], v240 offset:22528
	ds_read_b128 v[190:193], v240 offset:23552
	global_load_lds_dwordx4 v[194:195], off
	s_add_i32 m0, s2, 0x2000
	s_add_u32 s2, s58, 0x80000
	v_lshl_add_u64 v[196:197], s[58:59], 0, v[202:203]
	s_addc_u32 s3, s59, 0
	s_add_i32 s93, s85, s65
	global_load_lds_dwordx4 v[196:197], off
	v_lshl_add_u64 v[198:199], s[2:3], 0, v[206:207]
	s_mov_b32 m0, s93
	v_lshl_add_u64 v[200:201], s[60:61], 0, v[204:205]
	global_load_lds_dwordx4 v[198:199], off
	v_lshl_add_u64 v[198:199], s[2:3], 0, v[202:203]
	s_add_i32 m0, s93, 0x2000
	s_nop 0
	global_load_lds_dwordx4 v[198:199], off
	v_lshl_add_u64 v[198:199], s[60:61], 0, v[208:209]
	s_mov_b32 m0, s55
	s_nop 0
	global_load_lds_dwordx4 v[198:199], off
	s_mov_b32 m0, s69
	s_nop 0
	global_load_lds_dwordx4 v[200:201], off
	s_waitcnt vmcnt(8) lgkmcnt(0)
	s_barrier
	v_mfma_i32_16x16x64_i8 v[62:65], v[130:133], v[162:165], v[62:65]
	v_mfma_i32_16x16x64_i8 v[14:17], v[138:141], v[162:165], v[14:17]
	v_mfma_i32_16x16x64_i8 v[58:61], v[130:133], v[170:173], v[58:61]
	v_mfma_i32_16x16x64_i8 v[10:13], v[138:141], v[170:173], v[10:13]
	v_mfma_i32_16x16x64_i8 v[114:117], v[130:133], v[178:181], v[114:117]
	v_mfma_i32_16x16x64_i8 v[106:109], v[138:141], v[178:181], v[106:109]
	v_mfma_i32_16x16x64_i8 v[86:89], v[130:133], v[186:189], v[86:89]
	v_mfma_i32_16x16x64_i8 v[82:85], v[138:141], v[186:189], v[82:85]
	v_mfma_i32_16x16x64_i8 v[62:65], v[134:137], v[166:169], v[62:65]
	v_mfma_i32_16x16x64_i8 v[14:17], v[142:145], v[166:169], v[14:17]
	v_mfma_i32_16x16x64_i8 v[58:61], v[134:137], v[174:177], v[58:61]
	v_mfma_i32_16x16x64_i8 v[10:13], v[142:145], v[174:177], v[10:13]
	v_mfma_i32_16x16x64_i8 v[114:117], v[134:137], v[182:185], v[114:117]
	v_mfma_i32_16x16x64_i8 v[106:109], v[142:145], v[182:185], v[106:109]
	v_mfma_i32_16x16x64_i8 v[86:89], v[134:137], v[190:193], v[86:89]
	v_mfma_i32_16x16x64_i8 v[82:85], v[142:145], v[190:193], v[82:85]
	v_mfma_i32_16x16x64_i8 v[50:53], v[146:149], v[162:165], v[50:53]
	v_mfma_i32_16x16x64_i8 v[6:9], v[154:157], v[162:165], v[6:9]
	v_mfma_i32_16x16x64_i8 v[42:45], v[146:149], v[170:173], v[42:45]
	v_mfma_i32_16x16x64_i8 v[2:5], v[154:157], v[170:173], v[2:5]
	v_mfma_i32_16x16x64_i8 v[54:57], v[146:149], v[178:181], v[54:57]
	v_mfma_i32_16x16x64_i8 v[46:49], v[154:157], v[178:181], v[46:49]
	v_mfma_i32_16x16x64_i8 v[38:41], v[146:149], v[186:189], v[38:41]
	v_mfma_i32_16x16x64_i8 v[34:37], v[154:157], v[186:189], v[34:37]
	v_mfma_i32_16x16x64_i8 v[50:53], v[150:153], v[166:169], v[50:53]
	v_mfma_i32_16x16x64_i8 v[6:9], v[158:161], v[166:169], v[6:9]
	v_mfma_i32_16x16x64_i8 v[42:45], v[150:153], v[174:177], v[42:45]
	v_mfma_i32_16x16x64_i8 v[2:5], v[158:161], v[174:177], v[2:5]
	v_mfma_i32_16x16x64_i8 v[54:57], v[150:153], v[182:185], v[54:57]
	v_mfma_i32_16x16x64_i8 v[46:49], v[158:161], v[182:185], v[46:49]
	v_mfma_i32_16x16x64_i8 v[38:41], v[150:153], v[190:193], v[38:41]
	v_mfma_i32_16x16x64_i8 v[34:37], v[158:161], v[190:193], v[34:37]
	s_barrier
	s_add_i32 s93, 0, 0x18000
	s_add_i32 s94, 0, 0x1c000
	v_add_u32_e32 v142, s93, v237
	v_add_u32_e32 v158, s94, v237
	ds_read_b128 v[130:133], v142
	ds_read_b128 v[134:137], v142 offset:1024
	ds_read_b128 v[138:141], v142 offset:2048
	ds_read_b128 v[142:145], v142 offset:3072
	ds_read_b128 v[146:149], v158
	ds_read_b128 v[150:153], v158 offset:1024
	ds_read_b128 v[154:157], v158 offset:2048
	ds_read_b128 v[158:161], v158 offset:3072
	s_add_u32 s2, s60, 0x4000
	s_addc_u32 s3, s61, 0
	s_mov_b32 m0, s70
	v_lshl_add_u64 v[220:221], s[2:3], 0, v[208:209]
	ds_read_b128 v[162:165], v240 offset:32768
	ds_read_b128 v[166:169], v240 offset:33792
	ds_read_b128 v[170:173], v240 offset:34816
	ds_read_b128 v[174:177], v240 offset:35840
	ds_read_b128 v[178:181], v240 offset:36864
	ds_read_b128 v[182:185], v240 offset:37888
	ds_read_b128 v[186:189], v240 offset:38912
	ds_read_b128 v[190:193], v240 offset:39936
	global_load_lds_dwordx4 v[220:221], off
	v_lshl_add_u64 v[220:221], s[2:3], 0, v[204:205]
	s_mov_b32 m0, s71
	s_nop 0
	global_load_lds_dwordx4 v[220:221], off
	s_waitcnt vmcnt(8) lgkmcnt(0)
	s_barrier
	v_mfma_i32_16x16x64_i8 v[126:129], v[130:133], v[162:165], v[126:129]
	v_mfma_i32_16x16x64_i8 v[122:125], v[138:141], v[162:165], v[122:125]
	v_mfma_i32_16x16x64_i8 v[118:121], v[130:133], v[170:173], v[118:121]
	v_mfma_i32_16x16x64_i8 v[110:113], v[138:141], v[170:173], v[110:113]
	v_mfma_i32_16x16x64_i8 v[78:81], v[130:133], v[178:181], v[78:81]
	v_mfma_i32_16x16x64_i8 v[30:33], v[138:141], v[178:181], v[30:33]
	v_mfma_i32_16x16x64_i8 v[74:77], v[130:133], v[186:189], v[74:77]
	v_mfma_i32_16x16x64_i8 v[26:29], v[138:141], v[186:189], v[26:29]
	v_mfma_i32_16x16x64_i8 v[126:129], v[134:137], v[166:169], v[126:129]
	v_mfma_i32_16x16x64_i8 v[122:125], v[142:145], v[166:169], v[122:125]
	v_mfma_i32_16x16x64_i8 v[118:121], v[134:137], v[174:177], v[118:121]
	v_mfma_i32_16x16x64_i8 v[110:113], v[142:145], v[174:177], v[110:113]
	v_mfma_i32_16x16x64_i8 v[78:81], v[134:137], v[182:185], v[78:81]
	v_mfma_i32_16x16x64_i8 v[30:33], v[142:145], v[182:185], v[30:33]
	v_mfma_i32_16x16x64_i8 v[74:77], v[134:137], v[190:193], v[74:77]
	v_mfma_i32_16x16x64_i8 v[26:29], v[142:145], v[190:193], v[26:29]
	v_mfma_i32_16x16x64_i8 v[102:105], v[146:149], v[162:165], v[102:105]
	v_mfma_i32_16x16x64_i8 v[98:101], v[154:157], v[162:165], v[98:101]
	v_mfma_i32_16x16x64_i8 v[94:97], v[146:149], v[170:173], v[94:97]
	v_mfma_i32_16x16x64_i8 v[90:93], v[154:157], v[170:173], v[90:93]
	v_mfma_i32_16x16x64_i8 v[70:73], v[146:149], v[178:181], v[70:73]
	v_mfma_i32_16x16x64_i8 v[22:25], v[154:157], v[178:181], v[22:25]
	v_mfma_i32_16x16x64_i8 v[66:69], v[146:149], v[186:189], v[66:69]
	v_mfma_i32_16x16x64_i8 v[18:21], v[154:157], v[186:189], v[18:21]
	v_mfma_i32_16x16x64_i8 v[102:105], v[150:153], v[166:169], v[102:105]
	v_mfma_i32_16x16x64_i8 v[98:101], v[158:161], v[166:169], v[98:101]
	v_mfma_i32_16x16x64_i8 v[94:97], v[150:153], v[174:177], v[94:97]
	v_mfma_i32_16x16x64_i8 v[90:93], v[158:161], v[174:177], v[90:93]
	v_mfma_i32_16x16x64_i8 v[70:73], v[150:153], v[182:185], v[70:73]
	v_mfma_i32_16x16x64_i8 v[22:25], v[158:161], v[182:185], v[22:25]
	v_mfma_i32_16x16x64_i8 v[66:69], v[150:153], v[190:193], v[66:69]
	v_mfma_i32_16x16x64_i8 v[18:21], v[158:161], v[190:193], v[18:21]
	s_barrier
	s_add_i32 s2, s93, s65
	v_lshl_add_u64 v[194:195], v[194:195], 0, s[36:37]
	s_mov_b32 m0, s2
	ds_read_b128 v[162:165], v240 offset:49152
	ds_read_b128 v[166:169], v240 offset:50176
	ds_read_b128 v[170:173], v240 offset:51200
	ds_read_b128 v[174:177], v240 offset:52224
	ds_read_b128 v[178:181], v240 offset:53248
	ds_read_b128 v[182:185], v240 offset:54272
	ds_read_b128 v[186:189], v240 offset:55296
	ds_read_b128 v[190:193], v240 offset:56320
	global_load_lds_dwordx4 v[194:195], off
	s_add_i32 m0, s2, 0x2000
	s_add_u32 s2, s58, 0x80080
	v_lshl_add_u64 v[194:195], v[196:197], 0, s[36:37]
	s_addc_u32 s3, s59, 0
	s_add_i32 s58, s94, s65
	global_load_lds_dwordx4 v[194:195], off
	v_lshl_add_u64 v[194:195], s[2:3], 0, v[206:207]
	s_mov_b32 m0, s58
	s_nop 0
	global_load_lds_dwordx4 v[194:195], off
	v_lshl_add_u64 v[194:195], s[2:3], 0, v[202:203]
	s_add_i32 m0, s58, 0x2000
	s_nop 0
	global_load_lds_dwordx4 v[194:195], off
	v_lshl_add_u64 v[194:195], v[198:199], 0, s[36:37]
	s_mov_b32 m0, s78
	s_nop 0
	global_load_lds_dwordx4 v[194:195], off
	v_lshl_add_u64 v[194:195], v[200:201], 0, s[36:37]
	s_mov_b32 m0, s79
	s_nop 0
	global_load_lds_dwordx4 v[194:195], off
	s_waitcnt vmcnt(8) lgkmcnt(0)
	s_barrier
	v_mfma_i32_16x16x64_i8 v[62:65], v[130:133], v[162:165], v[62:65]
	v_mfma_i32_16x16x64_i8 v[14:17], v[138:141], v[162:165], v[14:17]
	v_mfma_i32_16x16x64_i8 v[58:61], v[130:133], v[170:173], v[58:61]
	v_mfma_i32_16x16x64_i8 v[10:13], v[138:141], v[170:173], v[10:13]
	v_mfma_i32_16x16x64_i8 v[114:117], v[130:133], v[178:181], v[114:117]
	v_mfma_i32_16x16x64_i8 v[106:109], v[138:141], v[178:181], v[106:109]
	v_mfma_i32_16x16x64_i8 v[86:89], v[130:133], v[186:189], v[86:89]
	v_mfma_i32_16x16x64_i8 v[82:85], v[138:141], v[186:189], v[82:85]
	v_mfma_i32_16x16x64_i8 v[62:65], v[134:137], v[166:169], v[62:65]
	v_mfma_i32_16x16x64_i8 v[14:17], v[142:145], v[166:169], v[14:17]
	v_mfma_i32_16x16x64_i8 v[58:61], v[134:137], v[174:177], v[58:61]
	v_mfma_i32_16x16x64_i8 v[10:13], v[142:145], v[174:177], v[10:13]
	v_mfma_i32_16x16x64_i8 v[114:117], v[134:137], v[182:185], v[114:117]
	v_mfma_i32_16x16x64_i8 v[106:109], v[142:145], v[182:185], v[106:109]
	v_mfma_i32_16x16x64_i8 v[86:89], v[134:137], v[190:193], v[86:89]
	v_mfma_i32_16x16x64_i8 v[82:85], v[142:145], v[190:193], v[82:85]
	v_mfma_i32_16x16x64_i8 v[50:53], v[146:149], v[162:165], v[50:53]
	v_mfma_i32_16x16x64_i8 v[6:9], v[154:157], v[162:165], v[6:9]
	v_mfma_i32_16x16x64_i8 v[42:45], v[146:149], v[170:173], v[42:45]
	v_mfma_i32_16x16x64_i8 v[2:5], v[154:157], v[170:173], v[2:5]
	v_mfma_i32_16x16x64_i8 v[54:57], v[146:149], v[178:181], v[54:57]
	v_mfma_i32_16x16x64_i8 v[46:49], v[154:157], v[178:181], v[46:49]
	v_mfma_i32_16x16x64_i8 v[38:41], v[146:149], v[186:189], v[38:41]
	v_mfma_i32_16x16x64_i8 v[34:37], v[154:157], v[186:189], v[34:37]
	v_mfma_i32_16x16x64_i8 v[50:53], v[150:153], v[166:169], v[50:53]
	v_mfma_i32_16x16x64_i8 v[6:9], v[158:161], v[166:169], v[6:9]
	v_mfma_i32_16x16x64_i8 v[42:45], v[150:153], v[174:177], v[42:45]
	v_mfma_i32_16x16x64_i8 v[2:5], v[158:161], v[174:177], v[2:5]
	v_mfma_i32_16x16x64_i8 v[54:57], v[150:153], v[182:185], v[54:57]
	v_mfma_i32_16x16x64_i8 v[46:49], v[158:161], v[182:185], v[46:49]
	v_mfma_i32_16x16x64_i8 v[38:41], v[150:153], v[190:193], v[38:41]
	v_mfma_i32_16x16x64_i8 v[34:37], v[158:161], v[190:193], v[34:37]
	s_barrier
	s_add_i32 s92, s92, 2
	s_add_u32 s90, s90, 0x100
	s_addc_u32 s91, s91, 0
	s_cmp_gt_u32 s92, 29
	s_mov_b64 s[2:3], s[56:57]
	s_cbranch_scc0 .LBB0_845
	s_setprio 0
	s_and_b64 vcc, exec, s[38:39]
	s_cbranch_vccz .LBB0_848
	s_barrier

.LBB0_1098:
	s_add_u32 s70, s30, 0x100
	v_mov_b32_e32 v2, 0
	s_addc_u32 s71, s31, 0
	s_mov_b32 s72, -2
	v_mov_b32_e32 v3, v2
	v_mov_b32_e32 v4, v2
	v_mov_b32_e32 v5, v2
	v_mov_b32_e32 v6, v2
	v_mov_b32_e32 v7, v2
	v_mov_b32_e32 v8, v2
	v_mov_b32_e32 v9, v2
	v_mov_b32_e32 v18, v2
	v_mov_b32_e32 v19, v2
	v_mov_b32_e32 v20, v2
	v_mov_b32_e32 v21, v2
	v_mov_b32_e32 v22, v2
	v_mov_b32_e32 v23, v2
	v_mov_b32_e32 v24, v2
	v_mov_b32_e32 v25, v2
	v_mov_b32_e32 v34, v2
	v_mov_b32_e32 v35, v2
	v_mov_b32_e32 v36, v2
	v_mov_b32_e32 v37, v2
	v_mov_b32_e32 v38, v2
	v_mov_b32_e32 v39, v2
	v_mov_b32_e32 v40, v2
	v_mov_b32_e32 v41, v2
	v_mov_b32_e32 v50, v2
	v_mov_b32_e32 v51, v2
	v_mov_b32_e32 v52, v2
	v_mov_b32_e32 v53, v2
	v_mov_b32_e32 v54, v2
	v_mov_b32_e32 v55, v2
	v_mov_b32_e32 v56, v2
	v_mov_b32_e32 v57, v2
	v_mov_b32_e32 v10, v2
	v_mov_b32_e32 v11, v2
	v_mov_b32_e32 v12, v2
	v_mov_b32_e32 v13, v2
	v_mov_b32_e32 v14, v2
	v_mov_b32_e32 v15, v2
	v_mov_b32_e32 v16, v2
	v_mov_b32_e32 v17, v2
	v_mov_b32_e32 v26, v2
	v_mov_b32_e32 v27, v2
	v_mov_b32_e32 v28, v2
	v_mov_b32_e32 v29, v2
	v_mov_b32_e32 v30, v2
	v_mov_b32_e32 v31, v2
	v_mov_b32_e32 v32, v2
	v_mov_b32_e32 v33, v2
	v_mov_b32_e32 v42, v2
	v_mov_b32_e32 v43, v2
	v_mov_b32_e32 v44, v2
	v_mov_b32_e32 v45, v2
	v_mov_b32_e32 v46, v2
	v_mov_b32_e32 v47, v2
	v_mov_b32_e32 v48, v2
	v_mov_b32_e32 v49, v2
	v_mov_b32_e32 v58, v2
	v_mov_b32_e32 v59, v2
	v_mov_b32_e32 v60, v2
	v_mov_b32_e32 v61, v2
	v_mov_b32_e32 v62, v2
	v_mov_b32_e32 v63, v2
	v_mov_b32_e32 v64, v2
	v_mov_b32_e32 v65, v2
	v_mov_b32_e32 v66, v2
	v_mov_b32_e32 v67, v2
	v_mov_b32_e32 v68, v2
	v_mov_b32_e32 v69, v2
	v_mov_b32_e32 v70, v2
	v_mov_b32_e32 v71, v2
	v_mov_b32_e32 v72, v2
	v_mov_b32_e32 v73, v2
	v_mov_b32_e32 v82, v2
	v_mov_b32_e32 v83, v2
	v_mov_b32_e32 v84, v2
	v_mov_b32_e32 v85, v2
	v_mov_b32_e32 v86, v2
	v_mov_b32_e32 v87, v2
	v_mov_b32_e32 v88, v2
	v_mov_b32_e32 v89, v2
	v_mov_b32_e32 v98, v2
	v_mov_b32_e32 v99, v2
	v_mov_b32_e32 v100, v2
	v_mov_b32_e32 v101, v2
	v_mov_b32_e32 v102, v2
	v_mov_b32_e32 v103, v2
	v_mov_b32_e32 v104, v2
	v_mov_b32_e32 v105, v2
	v_mov_b32_e32 v114, v2
	v_mov_b32_e32 v115, v2
	v_mov_b32_e32 v116, v2
	v_mov_b32_e32 v117, v2
	v_mov_b32_e32 v118, v2
	v_mov_b32_e32 v119, v2
	v_mov_b32_e32 v120, v2
	v_mov_b32_e32 v121, v2
	v_mov_b32_e32 v74, v2
	v_mov_b32_e32 v75, v2
	v_mov_b32_e32 v76, v2
	v_mov_b32_e32 v77, v2
	v_mov_b32_e32 v78, v2
	v_mov_b32_e32 v79, v2
	v_mov_b32_e32 v80, v2
	v_mov_b32_e32 v81, v2
	v_mov_b32_e32 v90, v2
	v_mov_b32_e32 v91, v2
	v_mov_b32_e32 v92, v2
	v_mov_b32_e32 v93, v2
	v_mov_b32_e32 v94, v2
	v_mov_b32_e32 v95, v2
	v_mov_b32_e32 v96, v2
	v_mov_b32_e32 v97, v2
	v_mov_b32_e32 v106, v2
	v_mov_b32_e32 v107, v2
	v_mov_b32_e32 v108, v2
	v_mov_b32_e32 v109, v2
	v_mov_b32_e32 v110, v2
	v_mov_b32_e32 v111, v2
	v_mov_b32_e32 v112, v2
	v_mov_b32_e32 v113, v2
	v_mov_b32_e32 v122, v2
	v_mov_b32_e32 v123, v2
	v_mov_b32_e32 v124, v2
	v_mov_b32_e32 v125, v2
	v_mov_b32_e32 v126, v2
	v_mov_b32_e32 v127, v2
	v_mov_b32_e32 v128, v2
	v_mov_b32_e32 v129, v2
	s_and_b64 vcc, exec, s[16:17]
	s_cbranch_vccnz .Lsp_lead_4
	s_setprio 1
.Lsp_lead_4:
.LBB0_1099:
	ds_read_b128 v[130:133], v167
	ds_read_b128 v[134:137], v167 offset:1024
	ds_read_b128 v[138:141], v167 offset:2048
	ds_read_b128 v[142:145], v167 offset:3072
	ds_read_b128 v[170:173], v168
	ds_read_b128 v[174:177], v168 offset:1024
	ds_read_b128 v[178:181], v168 offset:2048
	ds_read_b128 v[182:185], v168 offset:3072
	s_add_u32 s30, s28, 0x100
	s_addc_u32 s31, s29, 0
	s_cmpk_eq_i32 s72, 0x52
	s_cselect_b32 s37, s3, s31
	s_cselect_b32 s36, s2, s30
	s_cselect_b32 s35, s27, s71
	s_cselect_b32 s34, s26, s70
	v_lshl_add_u64 v[162:163], s[28:29], 0, v[154:155]
	s_add_i32 m0, s47, 0xc000
	ds_read_b128 v[186:189], v169
	ds_read_b128 v[190:193], v169 offset:1024
	ds_read_b128 v[194:197], v169 offset:2048
	ds_read_b128 v[198:201], v169 offset:3072
	ds_read_b128 v[202:205], v169 offset:4096
	ds_read_b128 v[206:209], v169 offset:5120
	ds_read_b128 v[210:213], v169 offset:6144
	ds_read_b128 v[214:217], v169 offset:7168
	global_load_lds_dwordx4 v[162:163], off
	v_lshl_add_u64 v[162:163], s[28:29], 0, v[156:157]
	s_add_i32 m0, s47, 0xe000
	s_nop 0
	global_load_lds_dwordx4 v[162:163], off
	s_waitcnt vmcnt(8) lgkmcnt(0)
	s_barrier
	v_mfma_i32_16x16x64_i8 v[126:129], v[130:133], v[186:189], v[126:129]
	v_mfma_i32_16x16x64_i8 v[122:125], v[138:141], v[186:189], v[122:125]
	v_mfma_i32_16x16x64_i8 v[110:113], v[130:133], v[194:197], v[110:113]
	v_mfma_i32_16x16x64_i8 v[106:109], v[138:141], v[194:197], v[106:109]
	v_mfma_i32_16x16x64_i8 v[94:97], v[130:133], v[202:205], v[94:97]
	v_mfma_i32_16x16x64_i8 v[90:93], v[138:141], v[202:205], v[90:93]
	v_mfma_i32_16x16x64_i8 v[78:81], v[130:133], v[210:213], v[78:81]
	v_mfma_i32_16x16x64_i8 v[74:77], v[138:141], v[210:213], v[74:77]
	v_mfma_i32_16x16x64_i8 v[126:129], v[134:137], v[190:193], v[126:129]
	v_mfma_i32_16x16x64_i8 v[122:125], v[142:145], v[190:193], v[122:125]
	v_mfma_i32_16x16x64_i8 v[110:113], v[134:137], v[198:201], v[110:113]
	v_mfma_i32_16x16x64_i8 v[106:109], v[142:145], v[198:201], v[106:109]
	v_mfma_i32_16x16x64_i8 v[94:97], v[134:137], v[206:209], v[94:97]
	v_mfma_i32_16x16x64_i8 v[90:93], v[142:145], v[206:209], v[90:93]
	v_mfma_i32_16x16x64_i8 v[78:81], v[134:137], v[214:217], v[78:81]
	v_mfma_i32_16x16x64_i8 v[74:77], v[142:145], v[214:217], v[74:77]
	v_mfma_i32_16x16x64_i8 v[118:121], v[170:173], v[186:189], v[118:121]
	v_mfma_i32_16x16x64_i8 v[114:117], v[178:181], v[186:189], v[114:117]
	v_mfma_i32_16x16x64_i8 v[102:105], v[170:173], v[194:197], v[102:105]
	v_mfma_i32_16x16x64_i8 v[98:101], v[178:181], v[194:197], v[98:101]
	v_mfma_i32_16x16x64_i8 v[86:89], v[170:173], v[202:205], v[86:89]
	v_mfma_i32_16x16x64_i8 v[82:85], v[178:181], v[202:205], v[82:85]
	v_mfma_i32_16x16x64_i8 v[70:73], v[170:173], v[210:213], v[70:73]
	v_mfma_i32_16x16x64_i8 v[66:69], v[178:181], v[210:213], v[66:69]
	v_mfma_i32_16x16x64_i8 v[118:121], v[174:177], v[190:193], v[118:121]
	v_mfma_i32_16x16x64_i8 v[114:117], v[182:185], v[190:193], v[114:117]
	v_mfma_i32_16x16x64_i8 v[102:105], v[174:177], v[198:201], v[102:105]
	v_mfma_i32_16x16x64_i8 v[98:101], v[182:185], v[198:201], v[98:101]
	v_mfma_i32_16x16x64_i8 v[86:89], v[174:177], v[206:209], v[86:89]
	v_mfma_i32_16x16x64_i8 v[82:85], v[182:185], v[206:209], v[82:85]
	v_mfma_i32_16x16x64_i8 v[70:73], v[174:177], v[214:217], v[70:73]
	v_mfma_i32_16x16x64_i8 v[66:69], v[182:185], v[214:217], v[66:69]
	s_barrier
	s_add_i32 s28, s56, s46
	v_lshl_add_u64 v[162:163], s[34:35], 0, v[150:151]
	s_mov_b32 m0, s28
	ds_read_b128 v[186:189], v169 offset:16384
	ds_read_b128 v[190:193], v169 offset:17408
	ds_read_b128 v[194:197], v169 offset:18432
	ds_read_b128 v[198:201], v169 offset:19456
	ds_read_b128 v[202:205], v169 offset:20480
	ds_read_b128 v[206:209], v169 offset:21504
	ds_read_b128 v[210:213], v169 offset:22528
	ds_read_b128 v[214:217], v169 offset:23552
	global_load_lds_dwordx4 v[162:163], off
	s_add_i32 m0, s28, 0x2000
	s_add_u32 s28, s34, 0x158000
	v_lshl_add_u64 v[218:219], s[34:35], 0, v[146:147]
	s_addc_u32 s29, s35, 0
	s_add_i32 s73, s57, s46
	global_load_lds_dwordx4 v[218:219], off
	v_lshl_add_u64 v[220:221], s[28:29], 0, v[150:151]
	s_mov_b32 m0, s73
	v_lshl_add_u64 v[222:223], s[36:37], 0, v[148:149]
	global_load_lds_dwordx4 v[220:221], off
	v_lshl_add_u64 v[220:221], s[28:29], 0, v[146:147]
	s_add_i32 m0, s73, 0x2000
	s_nop 0
	global_load_lds_dwordx4 v[220:221], off
	v_lshl_add_u64 v[220:221], s[36:37], 0, v[152:153]
	s_mov_b32 m0, s47
	s_nop 0
	global_load_lds_dwordx4 v[220:221], off
	s_mov_b32 m0, s48
	s_nop 0
	global_load_lds_dwordx4 v[222:223], off
	s_waitcnt vmcnt(8) lgkmcnt(0)
	s_barrier
	v_mfma_i32_16x16x64_i8 v[62:65], v[130:133], v[186:189], v[62:65]
	v_mfma_i32_16x16x64_i8 v[58:61], v[138:141], v[186:189], v[58:61]
	v_mfma_i32_16x16x64_i8 v[46:49], v[130:133], v[194:197], v[46:49]
	v_mfma_i32_16x16x64_i8 v[42:45], v[138:141], v[194:197], v[42:45]
	v_mfma_i32_16x16x64_i8 v[30:33], v[130:133], v[202:205], v[30:33]
	v_mfma_i32_16x16x64_i8 v[26:29], v[138:141], v[202:205], v[26:29]
	v_mfma_i32_16x16x64_i8 v[14:17], v[130:133], v[210:213], v[14:17]
	v_mfma_i32_16x16x64_i8 v[10:13], v[138:141], v[210:213], v[10:13]
	v_mfma_i32_16x16x64_i8 v[62:65], v[134:137], v[190:193], v[62:65]
	v_mfma_i32_16x16x64_i8 v[58:61], v[142:145], v[190:193], v[58:61]
	v_mfma_i32_16x16x64_i8 v[46:49], v[134:137], v[198:201], v[46:49]
	v_mfma_i32_16x16x64_i8 v[42:45], v[142:145], v[198:201], v[42:45]
	v_mfma_i32_16x16x64_i8 v[30:33], v[134:137], v[206:209], v[30:33]
	v_mfma_i32_16x16x64_i8 v[26:29], v[142:145], v[206:209], v[26:29]
	v_mfma_i32_16x16x64_i8 v[14:17], v[134:137], v[214:217], v[14:17]
	v_mfma_i32_16x16x64_i8 v[10:13], v[142:145], v[214:217], v[10:13]
	v_mfma_i32_16x16x64_i8 v[54:57], v[170:173], v[186:189], v[54:57]
	v_mfma_i32_16x16x64_i8 v[50:53], v[178:181], v[186:189], v[50:53]
	v_mfma_i32_16x16x64_i8 v[38:41], v[170:173], v[194:197], v[38:41]
	v_mfma_i32_16x16x64_i8 v[34:37], v[178:181], v[194:197], v[34:37]
	v_mfma_i32_16x16x64_i8 v[22:25], v[170:173], v[202:205], v[22:25]
	v_mfma_i32_16x16x64_i8 v[18:21], v[178:181], v[202:205], v[18:21]
	v_mfma_i32_16x16x64_i8 v[6:9], v[170:173], v[210:213], v[6:9]
	v_mfma_i32_16x16x64_i8 v[2:5], v[178:181], v[210:213], v[2:5]
	v_mfma_i32_16x16x64_i8 v[54:57], v[174:177], v[190:193], v[54:57]
	v_mfma_i32_16x16x64_i8 v[50:53], v[182:185], v[190:193], v[50:53]
	v_mfma_i32_16x16x64_i8 v[38:41], v[174:177], v[198:201], v[38:41]
	v_mfma_i32_16x16x64_i8 v[34:37], v[182:185], v[198:201], v[34:37]
	v_mfma_i32_16x16x64_i8 v[22:25], v[174:177], v[206:209], v[22:25]
	v_mfma_i32_16x16x64_i8 v[18:21], v[182:185], v[206:209], v[18:21]
	v_mfma_i32_16x16x64_i8 v[6:9], v[174:177], v[214:217], v[6:9]
	v_mfma_i32_16x16x64_i8 v[2:5], v[182:185], v[214:217], v[2:5]
	s_barrier
	s_add_i32 s73, 0, 0x18000
	s_add_i32 s74, 0, 0x1c000
	v_add_u32_e32 v142, s73, v166
	v_add_u32_e32 v182, s74, v166
	ds_read_b128 v[130:133], v142
	ds_read_b128 v[134:137], v142 offset:1024
	ds_read_b128 v[138:141], v142 offset:2048
	ds_read_b128 v[142:145], v142 offset:3072
	ds_read_b128 v[170:173], v182
	ds_read_b128 v[174:177], v182 offset:1024
	ds_read_b128 v[178:181], v182 offset:2048
	ds_read_b128 v[182:185], v182 offset:3072
	s_add_u32 s28, s36, 0x158000
	s_addc_u32 s29, s37, 0
	s_mov_b32 m0, s49
	v_lshl_add_u64 v[224:225], s[28:29], 0, v[152:153]
	ds_read_b128 v[186:189], v169 offset:32768
	ds_read_b128 v[190:193], v169 offset:33792
	ds_read_b128 v[194:197], v169 offset:34816
	ds_read_b128 v[198:201], v169 offset:35840
	ds_read_b128 v[202:205], v169 offset:36864
	ds_read_b128 v[206:209], v169 offset:37888
	ds_read_b128 v[210:213], v169 offset:38912
	ds_read_b128 v[214:217], v169 offset:39936
	global_load_lds_dwordx4 v[224:225], off
	v_lshl_add_u64 v[224:225], s[28:29], 0, v[148:149]
	s_mov_b32 m0, s50
	s_nop 0
	global_load_lds_dwordx4 v[224:225], off
	s_waitcnt vmcnt(8) lgkmcnt(0)
	s_barrier
	v_mfma_i32_16x16x64_i8 v[126:129], v[130:133], v[186:189], v[126:129]
	v_mfma_i32_16x16x64_i8 v[122:125], v[138:141], v[186:189], v[122:125]
	v_mfma_i32_16x16x64_i8 v[110:113], v[130:133], v[194:197], v[110:113]
	v_mfma_i32_16x16x64_i8 v[106:109], v[138:141], v[194:197], v[106:109]
	v_mfma_i32_16x16x64_i8 v[94:97], v[130:133], v[202:205], v[94:97]
	v_mfma_i32_16x16x64_i8 v[90:93], v[138:141], v[202:205], v[90:93]
	v_mfma_i32_16x16x64_i8 v[78:81], v[130:133], v[210:213], v[78:81]
	v_mfma_i32_16x16x64_i8 v[74:77], v[138:141], v[210:213], v[74:77]
	v_mfma_i32_16x16x64_i8 v[126:129], v[134:137], v[190:193], v[126:129]
	v_mfma_i32_16x16x64_i8 v[122:125], v[142:145], v[190:193], v[122:125]
	v_mfma_i32_16x16x64_i8 v[110:113], v[134:137], v[198:201], v[110:113]
	v_mfma_i32_16x16x64_i8 v[106:109], v[142:145], v[198:201], v[106:109]
	v_mfma_i32_16x16x64_i8 v[94:97], v[134:137], v[206:209], v[94:97]
	v_mfma_i32_16x16x64_i8 v[90:93], v[142:145], v[206:209], v[90:93]
	v_mfma_i32_16x16x64_i8 v[78:81], v[134:137], v[214:217], v[78:81]
	v_mfma_i32_16x16x64_i8 v[74:77], v[142:145], v[214:217], v[74:77]
	v_mfma_i32_16x16x64_i8 v[118:121], v[170:173], v[186:189], v[118:121]
	v_mfma_i32_16x16x64_i8 v[114:117], v[178:181], v[186:189], v[114:117]
	v_mfma_i32_16x16x64_i8 v[102:105], v[170:173], v[194:197], v[102:105]
	v_mfma_i32_16x16x64_i8 v[98:101], v[178:181], v[194:197], v[98:101]
	v_mfma_i32_16x16x64_i8 v[86:89], v[170:173], v[202:205], v[86:89]
	v_mfma_i32_16x16x64_i8 v[82:85], v[178:181], v[202:205], v[82:85]
	v_mfma_i32_16x16x64_i8 v[70:73], v[170:173], v[210:213], v[70:73]
	v_mfma_i32_16x16x64_i8 v[66:69], v[178:181], v[210:213], v[66:69]
	v_mfma_i32_16x16x64_i8 v[118:121], v[174:177], v[190:193], v[118:121]
	v_mfma_i32_16x16x64_i8 v[114:117], v[182:185], v[190:193], v[114:117]
	v_mfma_i32_16x16x64_i8 v[102:105], v[174:177], v[198:201], v[102:105]
	v_mfma_i32_16x16x64_i8 v[98:101], v[182:185], v[198:201], v[98:101]
	v_mfma_i32_16x16x64_i8 v[86:89], v[174:177], v[206:209], v[86:89]
	v_mfma_i32_16x16x64_i8 v[82:85], v[182:185], v[206:209], v[82:85]
	v_mfma_i32_16x16x64_i8 v[70:73], v[174:177], v[214:217], v[70:73]
	v_mfma_i32_16x16x64_i8 v[66:69], v[182:185], v[214:217], v[66:69]
	s_barrier
	s_add_i32 s28, s73, s46
	v_lshl_add_u64 v[162:163], v[162:163], 0, s[14:15]
	s_mov_b32 m0, s28
	ds_read_b128 v[186:189], v169 offset:49152
	ds_read_b128 v[190:193], v169 offset:50176
	ds_read_b128 v[194:197], v169 offset:51200
	ds_read_b128 v[198:201], v169 offset:52224
	ds_read_b128 v[202:205], v169 offset:53248
	ds_read_b128 v[206:209], v169 offset:54272
	ds_read_b128 v[210:213], v169 offset:55296
	ds_read_b128 v[214:217], v169 offset:56320
	global_load_lds_dwordx4 v[162:163], off
	s_add_i32 m0, s28, 0x2000
	s_add_u32 s28, s34, 0x158080
	v_lshl_add_u64 v[162:163], v[218:219], 0, s[14:15]
	s_addc_u32 s29, s35, 0
	s_add_i32 s34, s74, s46
	global_load_lds_dwordx4 v[162:163], off
	v_lshl_add_u64 v[162:163], s[28:29], 0, v[150:151]
	s_mov_b32 m0, s34
	s_nop 0
	global_load_lds_dwordx4 v[162:163], off
	v_lshl_add_u64 v[162:163], s[28:29], 0, v[146:147]
	s_add_i32 m0, s34, 0x2000
	s_nop 0
	global_load_lds_dwordx4 v[162:163], off
	v_lshl_add_u64 v[162:163], v[220:221], 0, s[14:15]
	s_mov_b32 m0, s54
	s_nop 0
	global_load_lds_dwordx4 v[162:163], off
	v_lshl_add_u64 v[162:163], v[222:223], 0, s[14:15]
	s_mov_b32 m0, s55
	s_nop 0
	global_load_lds_dwordx4 v[162:163], off
	s_waitcnt vmcnt(8) lgkmcnt(0)
	s_barrier
	v_mfma_i32_16x16x64_i8 v[62:65], v[130:133], v[186:189], v[62:65]
	v_mfma_i32_16x16x64_i8 v[58:61], v[138:141], v[186:189], v[58:61]
	v_mfma_i32_16x16x64_i8 v[46:49], v[130:133], v[194:197], v[46:49]
	v_mfma_i32_16x16x64_i8 v[42:45], v[138:141], v[194:197], v[42:45]
	v_mfma_i32_16x16x64_i8 v[30:33], v[130:133], v[202:205], v[30:33]
	v_mfma_i32_16x16x64_i8 v[26:29], v[138:141], v[202:205], v[26:29]
	v_mfma_i32_16x16x64_i8 v[14:17], v[130:133], v[210:213], v[14:17]
	v_mfma_i32_16x16x64_i8 v[10:13], v[138:141], v[210:213], v[10:13]
	v_mfma_i32_16x16x64_i8 v[62:65], v[134:137], v[190:193], v[62:65]
	v_mfma_i32_16x16x64_i8 v[58:61], v[142:145], v[190:193], v[58:61]
	v_mfma_i32_16x16x64_i8 v[46:49], v[134:137], v[198:201], v[46:49]
	v_mfma_i32_16x16x64_i8 v[42:45], v[142:145], v[198:201], v[42:45]
	v_mfma_i32_16x16x64_i8 v[30:33], v[134:137], v[206:209], v[30:33]
	v_mfma_i32_16x16x64_i8 v[26:29], v[142:145], v[206:209], v[26:29]
	v_mfma_i32_16x16x64_i8 v[14:17], v[134:137], v[214:217], v[14:17]
	v_mfma_i32_16x16x64_i8 v[10:13], v[142:145], v[214:217], v[10:13]
	v_mfma_i32_16x16x64_i8 v[54:57], v[170:173], v[186:189], v[54:57]
	v_mfma_i32_16x16x64_i8 v[50:53], v[178:181], v[186:189], v[50:53]
	v_mfma_i32_16x16x64_i8 v[38:41], v[170:173], v[194:197], v[38:41]
	v_mfma_i32_16x16x64_i8 v[34:37], v[178:181], v[194:197], v[34:37]
	v_mfma_i32_16x16x64_i8 v[22:25], v[170:173], v[202:205], v[22:25]
	v_mfma_i32_16x16x64_i8 v[18:21], v[178:181], v[202:205], v[18:21]
	v_mfma_i32_16x16x64_i8 v[6:9], v[170:173], v[210:213], v[6:9]
	v_mfma_i32_16x16x64_i8 v[2:5], v[178:181], v[210:213], v[2:5]
	v_mfma_i32_16x16x64_i8 v[54:57], v[174:177], v[190:193], v[54:57]
	v_mfma_i32_16x16x64_i8 v[50:53], v[182:185], v[190:193], v[50:53]
	v_mfma_i32_16x16x64_i8 v[38:41], v[174:177], v[198:201], v[38:41]
	v_mfma_i32_16x16x64_i8 v[34:37], v[182:185], v[198:201], v[34:37]
	v_mfma_i32_16x16x64_i8 v[22:25], v[174:177], v[206:209], v[22:25]
	v_mfma_i32_16x16x64_i8 v[18:21], v[182:185], v[206:209], v[18:21]
	v_mfma_i32_16x16x64_i8 v[6:9], v[174:177], v[214:217], v[6:9]
	v_mfma_i32_16x16x64_i8 v[2:5], v[182:185], v[214:217], v[2:5]
	s_barrier
	s_add_i32 s72, s72, 2
	s_add_u32 s70, s70, 0x100
	s_addc_u32 s71, s71, 0
	s_cmpk_gt_u32 s72, 0x53
	s_mov_b64 s[28:29], s[30:31]
	s_cbranch_scc0 .LBB0_1099
	s_setprio 0
	s_and_b64 vcc, exec, s[16:17]
	s_cbranch_vccz .LBB0_1102
	s_barrier

.LBB0_1245:
	s_ashr_i32 s23, s22, 31
	s_lshl_b64 s[24:25], s[22:23], 21
	s_add_u32 s24, s39, s24
	s_addc_u32 s25, s41, s25
	s_and_b64 s[26:27], s[0:1], exec
	s_cselect_b32 s3, s25, s29
	s_cselect_b32 s23, s24, s28
	s_ashr_i32 s17, s16, 31
	s_lshl_b64 s[26:27], s[16:17], 21
	s_add_u32 s26, s37, s26
	s_addc_u32 s27, s38, s27
	s_and_b64 s[34:35], s[0:1], exec
	s_cselect_b32 s17, s27, s31
	s_cselect_b32 s62, s26, s30
	s_add_u32 s28, s28, 0x100080
	s_addc_u32 s29, s29, 0
	s_add_u32 s63, s30, 0x100
	v_mov_b32_e32 v2, 0
	s_addc_u32 s65, s31, 0
	s_mov_b32 s68, -2
	v_mov_b32_e32 v3, v2
	v_mov_b32_e32 v4, v2
	v_mov_b32_e32 v5, v2
	v_mov_b32_e32 v6, v2
	v_mov_b32_e32 v7, v2
	v_mov_b32_e32 v8, v2
	v_mov_b32_e32 v9, v2
	v_mov_b32_e32 v18, v2
	v_mov_b32_e32 v19, v2
	v_mov_b32_e32 v20, v2
	v_mov_b32_e32 v21, v2
	v_mov_b32_e32 v22, v2
	v_mov_b32_e32 v23, v2
	v_mov_b32_e32 v24, v2
	v_mov_b32_e32 v25, v2
	v_mov_b32_e32 v34, v2
	v_mov_b32_e32 v35, v2
	v_mov_b32_e32 v36, v2
	v_mov_b32_e32 v37, v2
	v_mov_b32_e32 v38, v2
	v_mov_b32_e32 v39, v2
	v_mov_b32_e32 v40, v2
	v_mov_b32_e32 v41, v2
	v_mov_b32_e32 v50, v2
	v_mov_b32_e32 v51, v2
	v_mov_b32_e32 v52, v2
	v_mov_b32_e32 v53, v2
	v_mov_b32_e32 v54, v2
	v_mov_b32_e32 v55, v2
	v_mov_b32_e32 v56, v2
	v_mov_b32_e32 v57, v2
	v_mov_b32_e32 v10, v2
	v_mov_b32_e32 v11, v2
	v_mov_b32_e32 v12, v2
	v_mov_b32_e32 v13, v2
	v_mov_b32_e32 v14, v2
	v_mov_b32_e32 v15, v2
	v_mov_b32_e32 v16, v2
	v_mov_b32_e32 v17, v2
	v_mov_b32_e32 v26, v2
	v_mov_b32_e32 v27, v2
	v_mov_b32_e32 v28, v2
	v_mov_b32_e32 v29, v2
	v_mov_b32_e32 v30, v2
	v_mov_b32_e32 v31, v2
	v_mov_b32_e32 v32, v2
	v_mov_b32_e32 v33, v2
	v_mov_b32_e32 v42, v2
	v_mov_b32_e32 v43, v2
	v_mov_b32_e32 v44, v2
	v_mov_b32_e32 v45, v2
	v_mov_b32_e32 v46, v2
	v_mov_b32_e32 v47, v2
	v_mov_b32_e32 v48, v2
	v_mov_b32_e32 v49, v2
	v_mov_b32_e32 v58, v2
	v_mov_b32_e32 v59, v2
	v_mov_b32_e32 v60, v2
	v_mov_b32_e32 v61, v2
	v_mov_b32_e32 v62, v2
	v_mov_b32_e32 v63, v2
	v_mov_b32_e32 v64, v2
	v_mov_b32_e32 v65, v2
	v_mov_b32_e32 v66, v2
	v_mov_b32_e32 v67, v2
	v_mov_b32_e32 v68, v2
	v_mov_b32_e32 v69, v2
	v_mov_b32_e32 v70, v2
	v_mov_b32_e32 v71, v2
	v_mov_b32_e32 v72, v2
	v_mov_b32_e32 v73, v2
	v_mov_b32_e32 v78, v2
	v_mov_b32_e32 v79, v2
	v_mov_b32_e32 v80, v2
	v_mov_b32_e32 v81, v2
	v_mov_b32_e32 v86, v2
	v_mov_b32_e32 v87, v2
	v_mov_b32_e32 v88, v2
	v_mov_b32_e32 v89, v2
	v_mov_b32_e32 v94, v2
	v_mov_b32_e32 v95, v2
	v_mov_b32_e32 v96, v2
	v_mov_b32_e32 v97, v2
	v_mov_b32_e32 v102, v2
	v_mov_b32_e32 v103, v2
	v_mov_b32_e32 v104, v2
	v_mov_b32_e32 v105, v2
	v_mov_b32_e32 v106, v2
	v_mov_b32_e32 v107, v2
	v_mov_b32_e32 v108, v2
	v_mov_b32_e32 v109, v2
	v_mov_b32_e32 v114, v2
	v_mov_b32_e32 v115, v2
	v_mov_b32_e32 v116, v2
	v_mov_b32_e32 v117, v2
	v_mov_b32_e32 v74, v2
	v_mov_b32_e32 v75, v2
	v_mov_b32_e32 v76, v2
	v_mov_b32_e32 v77, v2
	v_mov_b32_e32 v82, v2
	v_mov_b32_e32 v83, v2
	v_mov_b32_e32 v84, v2
	v_mov_b32_e32 v85, v2
	v_mov_b32_e32 v90, v2
	v_mov_b32_e32 v91, v2
	v_mov_b32_e32 v92, v2
	v_mov_b32_e32 v93, v2
	v_mov_b32_e32 v98, v2
	v_mov_b32_e32 v99, v2
	v_mov_b32_e32 v100, v2
	v_mov_b32_e32 v101, v2
	v_mov_b32_e32 v110, v2
	v_mov_b32_e32 v111, v2
	v_mov_b32_e32 v112, v2
	v_mov_b32_e32 v113, v2
	v_mov_b32_e32 v118, v2
	v_mov_b32_e32 v119, v2
	v_mov_b32_e32 v120, v2
	v_mov_b32_e32 v121, v2
	v_mov_b32_e32 v122, v2
	v_mov_b32_e32 v123, v2
	v_mov_b32_e32 v124, v2
	v_mov_b32_e32 v125, v2
	v_mov_b32_e32 v126, v2
	v_mov_b32_e32 v127, v2
	v_mov_b32_e32 v128, v2
	v_mov_b32_e32 v129, v2
	s_and_b64 vcc, exec, s[14:15]
	s_cbranch_vccnz .Lsp_lead_3
	s_setprio 1
.Lsp_lead_3:
.LBB0_1246:
	ds_read_b128 v[130:133], v193
	ds_read_b128 v[134:137], v193 offset:1024
	ds_read_b128 v[138:141], v193 offset:2048
	ds_read_b128 v[142:145], v193 offset:3072
	ds_read_b128 v[162:165], v194
	ds_read_b128 v[166:169], v194 offset:1024
	ds_read_b128 v[170:173], v194 offset:2048
	ds_read_b128 v[174:177], v194 offset:3072
	s_add_u32 s30, s28, 0xfff00080
	s_addc_u32 s31, s29, -1
	s_cmp_eq_u32 s68, 60
	s_cselect_b32 s35, s3, s31
	s_cselect_b32 s34, s23, s30
	s_cselect_b32 s31, s17, s65
	s_cselect_b32 s30, s62, s63
	v_lshl_add_u64 v[216:217], s[28:29], 0, v[154:155]
	s_add_i32 m0, s45, 0xc000
	ds_read_b128 v[178:181], v195
	ds_read_b128 v[182:185], v195 offset:1024
	ds_read_b128 v[186:189], v195 offset:2048
	ds_read_b128 v[196:199], v195 offset:3072
	ds_read_b128 v[200:203], v195 offset:4096
	ds_read_b128 v[204:207], v195 offset:5120
	ds_read_b128 v[208:211], v195 offset:6144
	ds_read_b128 v[212:215], v195 offset:7168
	global_load_lds_dwordx4 v[216:217], off
	v_lshl_add_u64 v[216:217], s[28:29], 0, v[156:157]
	s_add_i32 m0, s45, 0xe000
	s_nop 0
	global_load_lds_dwordx4 v[216:217], off
	s_waitcnt vmcnt(8) lgkmcnt(0)
	s_barrier
	v_mfma_f32_16x16x32_bf16 v[126:129], v[130:133], v[178:181], v[126:129]
	v_mfma_f32_16x16x32_bf16 v[122:125], v[138:141], v[178:181], v[122:125]
	v_mfma_f32_16x16x32_bf16 v[118:121], v[130:133], v[186:189], v[118:121]
	v_mfma_f32_16x16x32_bf16 v[110:113], v[138:141], v[186:189], v[110:113]
	v_mfma_f32_16x16x32_bf16 v[98:101], v[130:133], v[200:203], v[98:101]
	v_mfma_f32_16x16x32_bf16 v[90:93], v[138:141], v[200:203], v[90:93]
	v_mfma_f32_16x16x32_bf16 v[82:85], v[130:133], v[208:211], v[82:85]
	v_mfma_f32_16x16x32_bf16 v[74:77], v[138:141], v[208:211], v[74:77]
	v_mfma_f32_16x16x32_bf16 v[126:129], v[134:137], v[182:185], v[126:129]
	v_mfma_f32_16x16x32_bf16 v[122:125], v[142:145], v[182:185], v[122:125]
	v_mfma_f32_16x16x32_bf16 v[118:121], v[134:137], v[196:199], v[118:121]
	v_mfma_f32_16x16x32_bf16 v[110:113], v[142:145], v[196:199], v[110:113]
	v_mfma_f32_16x16x32_bf16 v[98:101], v[134:137], v[204:207], v[98:101]
	v_mfma_f32_16x16x32_bf16 v[90:93], v[142:145], v[204:207], v[90:93]
	v_mfma_f32_16x16x32_bf16 v[82:85], v[134:137], v[212:215], v[82:85]
	v_mfma_f32_16x16x32_bf16 v[74:77], v[142:145], v[212:215], v[74:77]
	v_mfma_f32_16x16x32_bf16 v[114:117], v[162:165], v[178:181], v[114:117]
	v_mfma_f32_16x16x32_bf16 v[106:109], v[170:173], v[178:181], v[106:109]
	v_mfma_f32_16x16x32_bf16 v[102:105], v[162:165], v[186:189], v[102:105]
	v_mfma_f32_16x16x32_bf16 v[94:97], v[170:173], v[186:189], v[94:97]
	v_mfma_f32_16x16x32_bf16 v[86:89], v[162:165], v[200:203], v[86:89]
	v_mfma_f32_16x16x32_bf16 v[78:81], v[170:173], v[200:203], v[78:81]
	v_mfma_f32_16x16x32_bf16 v[70:73], v[162:165], v[208:211], v[70:73]
	v_mfma_f32_16x16x32_bf16 v[66:69], v[170:173], v[208:211], v[66:69]
	v_mfma_f32_16x16x32_bf16 v[114:117], v[166:169], v[182:185], v[114:117]
	v_mfma_f32_16x16x32_bf16 v[106:109], v[174:177], v[182:185], v[106:109]
	v_mfma_f32_16x16x32_bf16 v[102:105], v[166:169], v[196:199], v[102:105]
	v_mfma_f32_16x16x32_bf16 v[94:97], v[174:177], v[196:199], v[94:97]
	v_mfma_f32_16x16x32_bf16 v[86:89], v[166:169], v[204:207], v[86:89]
	v_mfma_f32_16x16x32_bf16 v[78:81], v[174:177], v[204:207], v[78:81]
	v_mfma_f32_16x16x32_bf16 v[70:73], v[166:169], v[212:215], v[70:73]
	v_mfma_f32_16x16x32_bf16 v[66:69], v[174:177], v[212:215], v[66:69]
	s_barrier
	s_add_i32 s69, s58, s44
	v_lshl_add_u64 v[216:217], s[30:31], 0, v[148:149]
	s_mov_b32 m0, s69
	ds_read_b128 v[178:181], v195 offset:16384
	ds_read_b128 v[182:185], v195 offset:17408
	ds_read_b128 v[186:189], v195 offset:18432
	ds_read_b128 v[196:199], v195 offset:19456
	ds_read_b128 v[200:203], v195 offset:20480
	ds_read_b128 v[204:207], v195 offset:21504
	ds_read_b128 v[208:211], v195 offset:22528
	ds_read_b128 v[212:215], v195 offset:23552
	global_load_lds_dwordx4 v[216:217], off
	s_add_i32 m0, s69, 0x2000
	s_add_u32 s70, s30, 0x100000
	v_lshl_add_u64 v[218:219], s[30:31], 0, v[152:153]
	s_addc_u32 s71, s31, 0
	s_add_i32 s69, s59, s44
	global_load_lds_dwordx4 v[218:219], off
	v_lshl_add_u64 v[220:221], s[70:71], 0, v[148:149]
	s_mov_b32 m0, s69
	v_lshl_add_u64 v[222:223], s[34:35], 0, v[150:151]
	global_load_lds_dwordx4 v[220:221], off
	v_lshl_add_u64 v[220:221], s[70:71], 0, v[152:153]
	s_add_i32 m0, s69, 0x2000
	s_nop 0
	global_load_lds_dwordx4 v[220:221], off
	v_lshl_add_u64 v[220:221], s[34:35], 0, v[146:147]
	s_mov_b32 m0, s45
	s_nop 0
	global_load_lds_dwordx4 v[220:221], off
	s_mov_b32 m0, s46
	s_nop 0
	global_load_lds_dwordx4 v[222:223], off
	s_waitcnt vmcnt(8) lgkmcnt(0)
	s_barrier
	v_mfma_f32_16x16x32_bf16 v[62:65], v[130:133], v[178:181], v[62:65]
	v_mfma_f32_16x16x32_bf16 v[58:61], v[138:141], v[178:181], v[58:61]
	v_mfma_f32_16x16x32_bf16 v[46:49], v[130:133], v[186:189], v[46:49]
	v_mfma_f32_16x16x32_bf16 v[42:45], v[138:141], v[186:189], v[42:45]
	v_mfma_f32_16x16x32_bf16 v[30:33], v[130:133], v[200:203], v[30:33]
	v_mfma_f32_16x16x32_bf16 v[26:29], v[138:141], v[200:203], v[26:29]
	v_mfma_f32_16x16x32_bf16 v[14:17], v[130:133], v[208:211], v[14:17]
	v_mfma_f32_16x16x32_bf16 v[10:13], v[138:141], v[208:211], v[10:13]
	v_mfma_f32_16x16x32_bf16 v[62:65], v[134:137], v[182:185], v[62:65]
	v_mfma_f32_16x16x32_bf16 v[58:61], v[142:145], v[182:185], v[58:61]
	v_mfma_f32_16x16x32_bf16 v[46:49], v[134:137], v[196:199], v[46:49]
	v_mfma_f32_16x16x32_bf16 v[42:45], v[142:145], v[196:199], v[42:45]
	v_mfma_f32_16x16x32_bf16 v[30:33], v[134:137], v[204:207], v[30:33]
	v_mfma_f32_16x16x32_bf16 v[26:29], v[142:145], v[204:207], v[26:29]
	v_mfma_f32_16x16x32_bf16 v[14:17], v[134:137], v[212:215], v[14:17]
	v_mfma_f32_16x16x32_bf16 v[10:13], v[142:145], v[212:215], v[10:13]
	v_mfma_f32_16x16x32_bf16 v[54:57], v[162:165], v[178:181], v[54:57]
	v_mfma_f32_16x16x32_bf16 v[50:53], v[170:173], v[178:181], v[50:53]
	v_mfma_f32_16x16x32_bf16 v[38:41], v[162:165], v[186:189], v[38:41]
	v_mfma_f32_16x16x32_bf16 v[34:37], v[170:173], v[186:189], v[34:37]
	v_mfma_f32_16x16x32_bf16 v[22:25], v[162:165], v[200:203], v[22:25]
	v_mfma_f32_16x16x32_bf16 v[18:21], v[170:173], v[200:203], v[18:21]
	v_mfma_f32_16x16x32_bf16 v[6:9], v[162:165], v[208:211], v[6:9]
	v_mfma_f32_16x16x32_bf16 v[2:5], v[170:173], v[208:211], v[2:5]
	v_mfma_f32_16x16x32_bf16 v[54:57], v[166:169], v[182:185], v[54:57]
	v_mfma_f32_16x16x32_bf16 v[50:53], v[174:177], v[182:185], v[50:53]
	v_mfma_f32_16x16x32_bf16 v[38:41], v[166:169], v[196:199], v[38:41]
	v_mfma_f32_16x16x32_bf16 v[34:37], v[174:177], v[196:199], v[34:37]
	v_mfma_f32_16x16x32_bf16 v[22:25], v[166:169], v[204:207], v[22:25]
	v_mfma_f32_16x16x32_bf16 v[18:21], v[174:177], v[204:207], v[18:21]
	v_mfma_f32_16x16x32_bf16 v[6:9], v[166:169], v[212:215], v[6:9]
	v_mfma_f32_16x16x32_bf16 v[2:5], v[174:177], v[212:215], v[2:5]
	s_barrier
	s_add_i32 s69, 0, 0x18000
	s_add_i32 s70, 0, 0x1c000
	v_add_u32_e32 v142, s69, v192
	v_add_u32_e32 v174, s70, v192
	ds_read_b128 v[130:133], v142
	ds_read_b128 v[134:137], v142 offset:1024
	ds_read_b128 v[138:141], v142 offset:2048
	ds_read_b128 v[142:145], v142 offset:3072
	ds_read_b128 v[162:165], v174
	ds_read_b128 v[166:169], v174 offset:1024
	ds_read_b128 v[170:173], v174 offset:2048
	ds_read_b128 v[174:177], v174 offset:3072
	s_add_u32 s34, s34, 0x100000
	s_addc_u32 s35, s35, 0
	s_mov_b32 m0, s47
	v_lshl_add_u64 v[224:225], s[34:35], 0, v[146:147]
	ds_read_b128 v[178:181], v195 offset:32768
	ds_read_b128 v[182:185], v195 offset:33792
	ds_read_b128 v[186:189], v195 offset:34816
	ds_read_b128 v[196:199], v195 offset:35840
	ds_read_b128 v[200:203], v195 offset:36864
	ds_read_b128 v[204:207], v195 offset:37888
	ds_read_b128 v[208:211], v195 offset:38912
	ds_read_b128 v[212:215], v195 offset:39936
	global_load_lds_dwordx4 v[224:225], off
	v_lshl_add_u64 v[224:225], s[34:35], 0, v[150:151]
	s_mov_b32 m0, s48
	s_nop 0
	global_load_lds_dwordx4 v[224:225], off
	s_waitcnt vmcnt(8) lgkmcnt(0)
	s_barrier
	v_mfma_f32_16x16x32_bf16 v[126:129], v[130:133], v[178:181], v[126:129]
	v_mfma_f32_16x16x32_bf16 v[122:125], v[138:141], v[178:181], v[122:125]
	v_mfma_f32_16x16x32_bf16 v[118:121], v[130:133], v[186:189], v[118:121]
	v_mfma_f32_16x16x32_bf16 v[110:113], v[138:141], v[186:189], v[110:113]
	v_mfma_f32_16x16x32_bf16 v[98:101], v[130:133], v[200:203], v[98:101]
	v_mfma_f32_16x16x32_bf16 v[90:93], v[138:141], v[200:203], v[90:93]
	v_mfma_f32_16x16x32_bf16 v[82:85], v[130:133], v[208:211], v[82:85]
	v_mfma_f32_16x16x32_bf16 v[74:77], v[138:141], v[208:211], v[74:77]
	v_mfma_f32_16x16x32_bf16 v[126:129], v[134:137], v[182:185], v[126:129]
	v_mfma_f32_16x16x32_bf16 v[122:125], v[142:145], v[182:185], v[122:125]
	v_mfma_f32_16x16x32_bf16 v[118:121], v[134:137], v[196:199], v[118:121]
	v_mfma_f32_16x16x32_bf16 v[110:113], v[142:145], v[196:199], v[110:113]
	v_mfma_f32_16x16x32_bf16 v[98:101], v[134:137], v[204:207], v[98:101]
	v_mfma_f32_16x16x32_bf16 v[90:93], v[142:145], v[204:207], v[90:93]
	v_mfma_f32_16x16x32_bf16 v[82:85], v[134:137], v[212:215], v[82:85]
	v_mfma_f32_16x16x32_bf16 v[74:77], v[142:145], v[212:215], v[74:77]
	v_mfma_f32_16x16x32_bf16 v[114:117], v[162:165], v[178:181], v[114:117]
	v_mfma_f32_16x16x32_bf16 v[106:109], v[170:173], v[178:181], v[106:109]
	v_mfma_f32_16x16x32_bf16 v[102:105], v[162:165], v[186:189], v[102:105]
	v_mfma_f32_16x16x32_bf16 v[94:97], v[170:173], v[186:189], v[94:97]
	v_mfma_f32_16x16x32_bf16 v[86:89], v[162:165], v[200:203], v[86:89]
	v_mfma_f32_16x16x32_bf16 v[78:81], v[170:173], v[200:203], v[78:81]
	v_mfma_f32_16x16x32_bf16 v[70:73], v[162:165], v[208:211], v[70:73]
	v_mfma_f32_16x16x32_bf16 v[66:69], v[170:173], v[208:211], v[66:69]
	v_mfma_f32_16x16x32_bf16 v[114:117], v[166:169], v[182:185], v[114:117]
	v_mfma_f32_16x16x32_bf16 v[106:109], v[174:177], v[182:185], v[106:109]
	v_mfma_f32_16x16x32_bf16 v[102:105], v[166:169], v[196:199], v[102:105]
	v_mfma_f32_16x16x32_bf16 v[94:97], v[174:177], v[196:199], v[94:97]
	v_mfma_f32_16x16x32_bf16 v[86:89], v[166:169], v[204:207], v[86:89]
	v_mfma_f32_16x16x32_bf16 v[78:81], v[174:177], v[204:207], v[78:81]
	v_mfma_f32_16x16x32_bf16 v[70:73], v[166:169], v[212:215], v[70:73]
	v_mfma_f32_16x16x32_bf16 v[66:69], v[174:177], v[212:215], v[66:69]
	s_barrier
	s_add_i32 s34, s69, s44
	v_lshl_add_u64 v[216:217], v[216:217], 0, s[12:13]
	s_mov_b32 m0, s34
	ds_read_b128 v[178:181], v195 offset:49152
	ds_read_b128 v[182:185], v195 offset:50176
	ds_read_b128 v[186:189], v195 offset:51200
	ds_read_b128 v[196:199], v195 offset:52224
	ds_read_b128 v[200:203], v195 offset:53248
	ds_read_b128 v[204:207], v195 offset:54272
	ds_read_b128 v[208:211], v195 offset:55296
	ds_read_b128 v[212:215], v195 offset:56320
	global_load_lds_dwordx4 v[216:217], off
	s_add_i32 m0, s34, 0x2000
	s_add_u32 s30, s30, 0x100080
	v_lshl_add_u64 v[216:217], v[218:219], 0, s[12:13]
	s_addc_u32 s31, s31, 0
	s_add_i32 s34, s70, s44
	global_load_lds_dwordx4 v[216:217], off
	v_lshl_add_u64 v[216:217], s[30:31], 0, v[148:149]
	s_mov_b32 m0, s34
	s_nop 0
	global_load_lds_dwordx4 v[216:217], off
	v_lshl_add_u64 v[216:217], s[30:31], 0, v[152:153]
	s_add_i32 m0, s34, 0x2000
	s_nop 0
	global_load_lds_dwordx4 v[216:217], off
	v_lshl_add_u64 v[216:217], v[220:221], 0, s[12:13]
	s_mov_b32 m0, s55
	s_nop 0
	global_load_lds_dwordx4 v[216:217], off
	v_lshl_add_u64 v[216:217], v[222:223], 0, s[12:13]
	s_mov_b32 m0, s56
	s_nop 0
	global_load_lds_dwordx4 v[216:217], off
	s_waitcnt vmcnt(8) lgkmcnt(0)
	s_barrier
	v_mfma_f32_16x16x32_bf16 v[62:65], v[130:133], v[178:181], v[62:65]
	v_mfma_f32_16x16x32_bf16 v[58:61], v[138:141], v[178:181], v[58:61]
	v_mfma_f32_16x16x32_bf16 v[46:49], v[130:133], v[186:189], v[46:49]
	v_mfma_f32_16x16x32_bf16 v[42:45], v[138:141], v[186:189], v[42:45]
	v_mfma_f32_16x16x32_bf16 v[30:33], v[130:133], v[200:203], v[30:33]
	v_mfma_f32_16x16x32_bf16 v[26:29], v[138:141], v[200:203], v[26:29]
	v_mfma_f32_16x16x32_bf16 v[14:17], v[130:133], v[208:211], v[14:17]
	v_mfma_f32_16x16x32_bf16 v[10:13], v[138:141], v[208:211], v[10:13]
	v_mfma_f32_16x16x32_bf16 v[62:65], v[134:137], v[182:185], v[62:65]
	v_mfma_f32_16x16x32_bf16 v[58:61], v[142:145], v[182:185], v[58:61]
	v_mfma_f32_16x16x32_bf16 v[46:49], v[134:137], v[196:199], v[46:49]
	v_mfma_f32_16x16x32_bf16 v[42:45], v[142:145], v[196:199], v[42:45]
	v_mfma_f32_16x16x32_bf16 v[30:33], v[134:137], v[204:207], v[30:33]
	v_mfma_f32_16x16x32_bf16 v[26:29], v[142:145], v[204:207], v[26:29]
	v_mfma_f32_16x16x32_bf16 v[14:17], v[134:137], v[212:215], v[14:17]
	v_mfma_f32_16x16x32_bf16 v[10:13], v[142:145], v[212:215], v[10:13]
	v_mfma_f32_16x16x32_bf16 v[54:57], v[162:165], v[178:181], v[54:57]
	v_mfma_f32_16x16x32_bf16 v[50:53], v[170:173], v[178:181], v[50:53]
	v_mfma_f32_16x16x32_bf16 v[38:41], v[162:165], v[186:189], v[38:41]
	v_mfma_f32_16x16x32_bf16 v[34:37], v[170:173], v[186:189], v[34:37]
	v_mfma_f32_16x16x32_bf16 v[22:25], v[162:165], v[200:203], v[22:25]
	v_mfma_f32_16x16x32_bf16 v[18:21], v[170:173], v[200:203], v[18:21]
	v_mfma_f32_16x16x32_bf16 v[6:9], v[162:165], v[208:211], v[6:9]
	v_mfma_f32_16x16x32_bf16 v[2:5], v[170:173], v[208:211], v[2:5]
	v_mfma_f32_16x16x32_bf16 v[54:57], v[166:169], v[182:185], v[54:57]
	v_mfma_f32_16x16x32_bf16 v[50:53], v[174:177], v[182:185], v[50:53]
	v_mfma_f32_16x16x32_bf16 v[38:41], v[166:169], v[196:199], v[38:41]
	v_mfma_f32_16x16x32_bf16 v[34:37], v[174:177], v[196:199], v[34:37]
	v_mfma_f32_16x16x32_bf16 v[22:25], v[166:169], v[204:207], v[22:25]
	v_mfma_f32_16x16x32_bf16 v[18:21], v[174:177], v[204:207], v[18:21]
	v_mfma_f32_16x16x32_bf16 v[6:9], v[166:169], v[212:215], v[6:9]
	v_mfma_f32_16x16x32_bf16 v[2:5], v[174:177], v[212:215], v[2:5]
	s_barrier
	s_add_i32 s68, s68, 2
	s_add_u32 s28, s28, 0x100
	s_addc_u32 s29, s29, 0
	s_add_u32 s63, s63, 0x100
	s_addc_u32 s65, s65, 0
	s_cmp_gt_u32 s68, 61
	s_cbranch_scc0 .LBB0_1246
	s_setprio 0
	s_and_b64 vcc, exec, s[14:15]
	s_cbranch_vccz .LBB0_1249
	s_barrier

.LBB0_1520:
	s_ashr_i32 s29, s28, 31
	s_lshl_b64 s[30:31], s[28:29], 21
	s_add_u32 s30, s48, s30
	s_addc_u32 s31, s49, s31
	s_and_b64 s[34:35], s[0:1], exec
	s_cselect_b32 s29, s31, s3
	s_cselect_b32 s65, s30, s2
	s_ashr_i32 s27, s26, 31
	s_lshl_b64 s[34:35], s[26:27], 21
	s_add_u32 s34, s46, s34
	s_addc_u32 s35, s47, s35
	s_and_b64 s[44:45], s[0:1], exec
	s_cselect_b32 s27, s35, s39
	s_cselect_b32 s66, s34, s38
	s_add_u32 s2, s2, 0x100080
	s_addc_u32 s3, s3, 0
	s_add_u32 s67, s38, 0x100
	v_mov_b32_e32 v2, 0
	s_addc_u32 s68, s39, 0
	s_mov_b32 s69, -2
	v_mov_b32_e32 v3, v2
	v_mov_b32_e32 v4, v2
	v_mov_b32_e32 v5, v2
	v_mov_b32_e32 v6, v2
	v_mov_b32_e32 v7, v2
	v_mov_b32_e32 v8, v2
	v_mov_b32_e32 v9, v2
	v_mov_b32_e32 v14, v2
	v_mov_b32_e32 v15, v2
	v_mov_b32_e32 v16, v2
	v_mov_b32_e32 v17, v2
	v_mov_b32_e32 v22, v2
	v_mov_b32_e32 v23, v2
	v_mov_b32_e32 v24, v2
	v_mov_b32_e32 v25, v2
	v_mov_b32_e32 v30, v2
	v_mov_b32_e32 v31, v2
	v_mov_b32_e32 v32, v2
	v_mov_b32_e32 v33, v2
	v_mov_b32_e32 v38, v2
	v_mov_b32_e32 v39, v2
	v_mov_b32_e32 v40, v2
	v_mov_b32_e32 v41, v2
	v_mov_b32_e32 v46, v2
	v_mov_b32_e32 v47, v2
	v_mov_b32_e32 v48, v2
	v_mov_b32_e32 v49, v2
	v_mov_b32_e32 v54, v2
	v_mov_b32_e32 v55, v2
	v_mov_b32_e32 v56, v2
	v_mov_b32_e32 v57, v2
	v_mov_b32_e32 v10, v2
	v_mov_b32_e32 v11, v2
	v_mov_b32_e32 v12, v2
	v_mov_b32_e32 v13, v2
	v_mov_b32_e32 v18, v2
	v_mov_b32_e32 v19, v2
	v_mov_b32_e32 v20, v2
	v_mov_b32_e32 v21, v2
	v_mov_b32_e32 v26, v2
	v_mov_b32_e32 v27, v2
	v_mov_b32_e32 v28, v2
	v_mov_b32_e32 v29, v2
	v_mov_b32_e32 v34, v2
	v_mov_b32_e32 v35, v2
	v_mov_b32_e32 v36, v2
	v_mov_b32_e32 v37, v2
	v_mov_b32_e32 v42, v2
	v_mov_b32_e32 v43, v2
	v_mov_b32_e32 v44, v2
	v_mov_b32_e32 v45, v2
	v_mov_b32_e32 v50, v2
	v_mov_b32_e32 v51, v2
	v_mov_b32_e32 v52, v2
	v_mov_b32_e32 v53, v2
	v_mov_b32_e32 v58, v2
	v_mov_b32_e32 v59, v2
	v_mov_b32_e32 v60, v2
	v_mov_b32_e32 v61, v2
	v_mov_b32_e32 v62, v2
	v_mov_b32_e32 v63, v2
	v_mov_b32_e32 v64, v2
	v_mov_b32_e32 v65, v2
	v_mov_b32_e32 v66, v2
	v_mov_b32_e32 v67, v2
	v_mov_b32_e32 v68, v2
	v_mov_b32_e32 v69, v2
	v_mov_b32_e32 v70, v2
	v_mov_b32_e32 v71, v2
	v_mov_b32_e32 v72, v2
	v_mov_b32_e32 v73, v2
	v_mov_b32_e32 v78, v2
	v_mov_b32_e32 v79, v2
	v_mov_b32_e32 v80, v2
	v_mov_b32_e32 v81, v2
	v_mov_b32_e32 v86, v2
	v_mov_b32_e32 v87, v2
	v_mov_b32_e32 v88, v2
	v_mov_b32_e32 v89, v2
	v_mov_b32_e32 v94, v2
	v_mov_b32_e32 v95, v2
	v_mov_b32_e32 v96, v2
	v_mov_b32_e32 v97, v2
	v_mov_b32_e32 v102, v2
	v_mov_b32_e32 v103, v2
	v_mov_b32_e32 v104, v2
	v_mov_b32_e32 v105, v2
	v_mov_b32_e32 v110, v2
	v_mov_b32_e32 v111, v2
	v_mov_b32_e32 v112, v2
	v_mov_b32_e32 v113, v2
	v_mov_b32_e32 v118, v2
	v_mov_b32_e32 v119, v2
	v_mov_b32_e32 v120, v2
	v_mov_b32_e32 v121, v2
	v_mov_b32_e32 v74, v2
	v_mov_b32_e32 v75, v2
	v_mov_b32_e32 v76, v2
	v_mov_b32_e32 v77, v2
	v_mov_b32_e32 v82, v2
	v_mov_b32_e32 v83, v2
	v_mov_b32_e32 v84, v2
	v_mov_b32_e32 v85, v2
	v_mov_b32_e32 v90, v2
	v_mov_b32_e32 v91, v2
	v_mov_b32_e32 v92, v2
	v_mov_b32_e32 v93, v2
	v_mov_b32_e32 v98, v2
	v_mov_b32_e32 v99, v2
	v_mov_b32_e32 v100, v2
	v_mov_b32_e32 v101, v2
	v_mov_b32_e32 v106, v2
	v_mov_b32_e32 v107, v2
	v_mov_b32_e32 v108, v2
	v_mov_b32_e32 v109, v2
	v_mov_b32_e32 v114, v2
	v_mov_b32_e32 v115, v2
	v_mov_b32_e32 v116, v2
	v_mov_b32_e32 v117, v2
	v_mov_b32_e32 v122, v2
	v_mov_b32_e32 v123, v2
	v_mov_b32_e32 v124, v2
	v_mov_b32_e32 v125, v2
	v_mov_b32_e32 v126, v2
	v_mov_b32_e32 v127, v2
	v_mov_b32_e32 v128, v2
	v_mov_b32_e32 v129, v2
	s_and_b64 vcc, exec, s[18:19]
	s_cbranch_vccnz .Lsp_lead_2
	s_setprio 1
.Lsp_lead_2:
.LBB0_1521:
	ds_read_b128 v[130:133], v169
	ds_read_b128 v[134:137], v169 offset:1024
	ds_read_b128 v[138:141], v169 offset:2048
	ds_read_b128 v[142:145], v169 offset:3072
	ds_read_b128 v[162:165], v170
	ds_read_b128 v[172:175], v170 offset:1024
	ds_read_b128 v[176:179], v170 offset:2048
	ds_read_b128 v[180:183], v170 offset:3072
	s_add_u32 s38, s2, 0xfff00080
	s_addc_u32 s39, s3, -1
	s_cmp_eq_u32 s69, 60
	s_cselect_b32 s45, s29, s39
	s_cselect_b32 s44, s65, s38
	s_cselect_b32 s39, s27, s68
	s_cselect_b32 s38, s66, s67
	v_lshl_add_u64 v[216:217], s[2:3], 0, v[154:155]
	s_add_i32 m0, s37, 0xc000
	ds_read_b128 v[184:187], v171
	ds_read_b128 v[188:191], v171 offset:1024
	ds_read_b128 v[192:195], v171 offset:2048
	ds_read_b128 v[196:199], v171 offset:3072
	ds_read_b128 v[200:203], v171 offset:4096
	ds_read_b128 v[204:207], v171 offset:5120
	ds_read_b128 v[208:211], v171 offset:6144
	ds_read_b128 v[212:215], v171 offset:7168
	global_load_lds_dwordx4 v[216:217], off
	v_lshl_add_u64 v[216:217], s[2:3], 0, v[156:157]
	s_add_i32 m0, s37, 0xe000
	s_nop 0
	global_load_lds_dwordx4 v[216:217], off
	s_waitcnt vmcnt(8) lgkmcnt(0)
	s_barrier
	v_mfma_f32_16x16x32_bf16 v[126:129], v[130:133], v[184:187], v[126:129]
	v_mfma_f32_16x16x32_bf16 v[122:125], v[138:141], v[184:187], v[122:125]
	v_mfma_f32_16x16x32_bf16 v[114:117], v[130:133], v[192:195], v[114:117]
	v_mfma_f32_16x16x32_bf16 v[106:109], v[138:141], v[192:195], v[106:109]
	v_mfma_f32_16x16x32_bf16 v[98:101], v[130:133], v[200:203], v[98:101]
	v_mfma_f32_16x16x32_bf16 v[90:93], v[138:141], v[200:203], v[90:93]
	v_mfma_f32_16x16x32_bf16 v[82:85], v[130:133], v[208:211], v[82:85]
	v_mfma_f32_16x16x32_bf16 v[74:77], v[138:141], v[208:211], v[74:77]
	v_mfma_f32_16x16x32_bf16 v[126:129], v[134:137], v[188:191], v[126:129]
	v_mfma_f32_16x16x32_bf16 v[122:125], v[142:145], v[188:191], v[122:125]
	v_mfma_f32_16x16x32_bf16 v[114:117], v[134:137], v[196:199], v[114:117]
	v_mfma_f32_16x16x32_bf16 v[106:109], v[142:145], v[196:199], v[106:109]
	v_mfma_f32_16x16x32_bf16 v[98:101], v[134:137], v[204:207], v[98:101]
	v_mfma_f32_16x16x32_bf16 v[90:93], v[142:145], v[204:207], v[90:93]
	v_mfma_f32_16x16x32_bf16 v[82:85], v[134:137], v[212:215], v[82:85]
	v_mfma_f32_16x16x32_bf16 v[74:77], v[142:145], v[212:215], v[74:77]
	v_mfma_f32_16x16x32_bf16 v[118:121], v[162:165], v[184:187], v[118:121]
	v_mfma_f32_16x16x32_bf16 v[110:113], v[176:179], v[184:187], v[110:113]
	v_mfma_f32_16x16x32_bf16 v[102:105], v[162:165], v[192:195], v[102:105]
	v_mfma_f32_16x16x32_bf16 v[94:97], v[176:179], v[192:195], v[94:97]
	v_mfma_f32_16x16x32_bf16 v[86:89], v[162:165], v[200:203], v[86:89]
	v_mfma_f32_16x16x32_bf16 v[78:81], v[176:179], v[200:203], v[78:81]
	v_mfma_f32_16x16x32_bf16 v[70:73], v[162:165], v[208:211], v[70:73]
	v_mfma_f32_16x16x32_bf16 v[66:69], v[176:179], v[208:211], v[66:69]
	v_mfma_f32_16x16x32_bf16 v[118:121], v[172:175], v[188:191], v[118:121]
	v_mfma_f32_16x16x32_bf16 v[110:113], v[180:183], v[188:191], v[110:113]
	v_mfma_f32_16x16x32_bf16 v[102:105], v[172:175], v[196:199], v[102:105]
	v_mfma_f32_16x16x32_bf16 v[94:97], v[180:183], v[196:199], v[94:97]
	v_mfma_f32_16x16x32_bf16 v[86:89], v[172:175], v[204:207], v[86:89]
	v_mfma_f32_16x16x32_bf16 v[78:81], v[180:183], v[204:207], v[78:81]
	v_mfma_f32_16x16x32_bf16 v[70:73], v[172:175], v[212:215], v[70:73]
	v_mfma_f32_16x16x32_bf16 v[66:69], v[180:183], v[212:215], v[66:69]
	s_barrier
	s_add_i32 s43, s57, s50
	v_lshl_add_u64 v[216:217], s[38:39], 0, v[150:151]
	s_mov_b32 m0, s43
	ds_read_b128 v[184:187], v171 offset:16384
	ds_read_b128 v[188:191], v171 offset:17408
	ds_read_b128 v[192:195], v171 offset:18432
	ds_read_b128 v[196:199], v171 offset:19456
	ds_read_b128 v[200:203], v171 offset:20480
	ds_read_b128 v[204:207], v171 offset:21504
	ds_read_b128 v[208:211], v171 offset:22528
	ds_read_b128 v[212:215], v171 offset:23552
	global_load_lds_dwordx4 v[216:217], off
	s_add_i32 m0, s43, 0x2000
	s_add_u32 s70, s38, 0x100000
	v_lshl_add_u64 v[218:219], s[38:39], 0, v[146:147]
	s_addc_u32 s71, s39, 0
	s_add_i32 s43, s58, s50
	global_load_lds_dwordx4 v[218:219], off
	v_lshl_add_u64 v[220:221], s[70:71], 0, v[150:151]
	s_mov_b32 m0, s43
	v_lshl_add_u64 v[222:223], s[44:45], 0, v[148:149]
	global_load_lds_dwordx4 v[220:221], off
	v_lshl_add_u64 v[220:221], s[70:71], 0, v[146:147]
	s_add_i32 m0, s43, 0x2000
	s_nop 0
	global_load_lds_dwordx4 v[220:221], off
	v_lshl_add_u64 v[220:221], s[44:45], 0, v[152:153]
	s_mov_b32 m0, s37
	s_nop 0
	global_load_lds_dwordx4 v[220:221], off
	s_mov_b32 m0, s51
	s_nop 0
	global_load_lds_dwordx4 v[222:223], off
	s_waitcnt vmcnt(8) lgkmcnt(0)
	s_barrier
	v_mfma_f32_16x16x32_bf16 v[62:65], v[130:133], v[184:187], v[62:65]
	v_mfma_f32_16x16x32_bf16 v[58:61], v[138:141], v[184:187], v[58:61]
	v_mfma_f32_16x16x32_bf16 v[50:53], v[130:133], v[192:195], v[50:53]
	v_mfma_f32_16x16x32_bf16 v[42:45], v[138:141], v[192:195], v[42:45]
	v_mfma_f32_16x16x32_bf16 v[34:37], v[130:133], v[200:203], v[34:37]
	v_mfma_f32_16x16x32_bf16 v[26:29], v[138:141], v[200:203], v[26:29]
	v_mfma_f32_16x16x32_bf16 v[18:21], v[130:133], v[208:211], v[18:21]
	v_mfma_f32_16x16x32_bf16 v[10:13], v[138:141], v[208:211], v[10:13]
	v_mfma_f32_16x16x32_bf16 v[62:65], v[134:137], v[188:191], v[62:65]
	v_mfma_f32_16x16x32_bf16 v[58:61], v[142:145], v[188:191], v[58:61]
	v_mfma_f32_16x16x32_bf16 v[50:53], v[134:137], v[196:199], v[50:53]
	v_mfma_f32_16x16x32_bf16 v[42:45], v[142:145], v[196:199], v[42:45]
	v_mfma_f32_16x16x32_bf16 v[34:37], v[134:137], v[204:207], v[34:37]
	v_mfma_f32_16x16x32_bf16 v[26:29], v[142:145], v[204:207], v[26:29]
	v_mfma_f32_16x16x32_bf16 v[18:21], v[134:137], v[212:215], v[18:21]
	v_mfma_f32_16x16x32_bf16 v[10:13], v[142:145], v[212:215], v[10:13]
	v_mfma_f32_16x16x32_bf16 v[54:57], v[162:165], v[184:187], v[54:57]
	v_mfma_f32_16x16x32_bf16 v[46:49], v[176:179], v[184:187], v[46:49]
	v_mfma_f32_16x16x32_bf16 v[38:41], v[162:165], v[192:195], v[38:41]
	v_mfma_f32_16x16x32_bf16 v[30:33], v[176:179], v[192:195], v[30:33]
	v_mfma_f32_16x16x32_bf16 v[22:25], v[162:165], v[200:203], v[22:25]
	v_mfma_f32_16x16x32_bf16 v[14:17], v[176:179], v[200:203], v[14:17]
	v_mfma_f32_16x16x32_bf16 v[6:9], v[162:165], v[208:211], v[6:9]
	v_mfma_f32_16x16x32_bf16 v[2:5], v[176:179], v[208:211], v[2:5]
	v_mfma_f32_16x16x32_bf16 v[54:57], v[172:175], v[188:191], v[54:57]
	v_mfma_f32_16x16x32_bf16 v[46:49], v[180:183], v[188:191], v[46:49]
	v_mfma_f32_16x16x32_bf16 v[38:41], v[172:175], v[196:199], v[38:41]
	v_mfma_f32_16x16x32_bf16 v[30:33], v[180:183], v[196:199], v[30:33]
	v_mfma_f32_16x16x32_bf16 v[22:25], v[172:175], v[204:207], v[22:25]
	v_mfma_f32_16x16x32_bf16 v[14:17], v[180:183], v[204:207], v[14:17]
	v_mfma_f32_16x16x32_bf16 v[6:9], v[172:175], v[212:215], v[6:9]
	v_mfma_f32_16x16x32_bf16 v[2:5], v[180:183], v[212:215], v[2:5]
	s_barrier
	s_add_i32 s43, 0, 0x18000
	s_add_i32 s70, 0, 0x1c000
	v_add_u32_e32 v142, s43, v167
	v_add_u32_e32 v180, s70, v167
	ds_read_b128 v[130:133], v142
	ds_read_b128 v[134:137], v142 offset:1024
	ds_read_b128 v[138:141], v142 offset:2048
	ds_read_b128 v[142:145], v142 offset:3072
	ds_read_b128 v[162:165], v180
	ds_read_b128 v[172:175], v180 offset:1024
	ds_read_b128 v[176:179], v180 offset:2048
	ds_read_b128 v[180:183], v180 offset:3072
	s_add_u32 s44, s44, 0x100000
	s_addc_u32 s45, s45, 0
	s_mov_b32 m0, s52
	v_lshl_add_u64 v[224:225], s[44:45], 0, v[152:153]
	ds_read_b128 v[184:187], v171 offset:32768
	ds_read_b128 v[188:191], v171 offset:33792
	ds_read_b128 v[192:195], v171 offset:34816
	ds_read_b128 v[196:199], v171 offset:35840
	ds_read_b128 v[200:203], v171 offset:36864
	ds_read_b128 v[204:207], v171 offset:37888
	ds_read_b128 v[208:211], v171 offset:38912
	ds_read_b128 v[212:215], v171 offset:39936
	global_load_lds_dwordx4 v[224:225], off
	v_lshl_add_u64 v[224:225], s[44:45], 0, v[148:149]
	s_mov_b32 m0, s53
	s_nop 0
	global_load_lds_dwordx4 v[224:225], off
	s_waitcnt vmcnt(8) lgkmcnt(0)
	s_barrier
	v_mfma_f32_16x16x32_bf16 v[126:129], v[130:133], v[184:187], v[126:129]
	v_mfma_f32_16x16x32_bf16 v[122:125], v[138:141], v[184:187], v[122:125]
	v_mfma_f32_16x16x32_bf16 v[114:117], v[130:133], v[192:195], v[114:117]
	v_mfma_f32_16x16x32_bf16 v[106:109], v[138:141], v[192:195], v[106:109]
	v_mfma_f32_16x16x32_bf16 v[98:101], v[130:133], v[200:203], v[98:101]
	v_mfma_f32_16x16x32_bf16 v[90:93], v[138:141], v[200:203], v[90:93]
	v_mfma_f32_16x16x32_bf16 v[82:85], v[130:133], v[208:211], v[82:85]
	v_mfma_f32_16x16x32_bf16 v[74:77], v[138:141], v[208:211], v[74:77]
	v_mfma_f32_16x16x32_bf16 v[126:129], v[134:137], v[188:191], v[126:129]
	v_mfma_f32_16x16x32_bf16 v[122:125], v[142:145], v[188:191], v[122:125]
	v_mfma_f32_16x16x32_bf16 v[114:117], v[134:137], v[196:199], v[114:117]
	v_mfma_f32_16x16x32_bf16 v[106:109], v[142:145], v[196:199], v[106:109]
	v_mfma_f32_16x16x32_bf16 v[98:101], v[134:137], v[204:207], v[98:101]
	v_mfma_f32_16x16x32_bf16 v[90:93], v[142:145], v[204:207], v[90:93]
	v_mfma_f32_16x16x32_bf16 v[82:85], v[134:137], v[212:215], v[82:85]
	v_mfma_f32_16x16x32_bf16 v[74:77], v[142:145], v[212:215], v[74:77]
	v_mfma_f32_16x16x32_bf16 v[118:121], v[162:165], v[184:187], v[118:121]
	v_mfma_f32_16x16x32_bf16 v[110:113], v[176:179], v[184:187], v[110:113]
	v_mfma_f32_16x16x32_bf16 v[102:105], v[162:165], v[192:195], v[102:105]
	v_mfma_f32_16x16x32_bf16 v[94:97], v[176:179], v[192:195], v[94:97]
	v_mfma_f32_16x16x32_bf16 v[86:89], v[162:165], v[200:203], v[86:89]
	v_mfma_f32_16x16x32_bf16 v[78:81], v[176:179], v[200:203], v[78:81]
	v_mfma_f32_16x16x32_bf16 v[70:73], v[162:165], v[208:211], v[70:73]
	v_mfma_f32_16x16x32_bf16 v[66:69], v[176:179], v[208:211], v[66:69]
	v_mfma_f32_16x16x32_bf16 v[118:121], v[172:175], v[188:191], v[118:121]
	v_mfma_f32_16x16x32_bf16 v[110:113], v[180:183], v[188:191], v[110:113]
	v_mfma_f32_16x16x32_bf16 v[102:105], v[172:175], v[196:199], v[102:105]
	v_mfma_f32_16x16x32_bf16 v[94:97], v[180:183], v[196:199], v[94:97]
	v_mfma_f32_16x16x32_bf16 v[86:89], v[172:175], v[204:207], v[86:89]
	v_mfma_f32_16x16x32_bf16 v[78:81], v[180:183], v[204:207], v[78:81]
	v_mfma_f32_16x16x32_bf16 v[70:73], v[172:175], v[212:215], v[70:73]
	v_mfma_f32_16x16x32_bf16 v[66:69], v[180:183], v[212:215], v[66:69]
	s_barrier
	s_add_i32 s43, s43, s50
	v_lshl_add_u64 v[216:217], v[216:217], 0, s[16:17]
	s_mov_b32 m0, s43
	ds_read_b128 v[184:187], v171 offset:49152
	ds_read_b128 v[188:191], v171 offset:50176
	ds_read_b128 v[192:195], v171 offset:51200
	ds_read_b128 v[196:199], v171 offset:52224
	ds_read_b128 v[200:203], v171 offset:53248
	ds_read_b128 v[204:207], v171 offset:54272
	ds_read_b128 v[208:211], v171 offset:55296
	ds_read_b128 v[212:215], v171 offset:56320
	global_load_lds_dwordx4 v[216:217], off
	s_add_i32 m0, s43, 0x2000
	s_add_u32 s38, s38, 0x100080
	v_lshl_add_u64 v[216:217], v[218:219], 0, s[16:17]
	s_addc_u32 s39, s39, 0
	s_add_i32 s43, s70, s50
	global_load_lds_dwordx4 v[216:217], off
	v_lshl_add_u64 v[216:217], s[38:39], 0, v[150:151]
	s_mov_b32 m0, s43
	s_nop 0
	global_load_lds_dwordx4 v[216:217], off
	v_lshl_add_u64 v[216:217], s[38:39], 0, v[146:147]
	s_add_i32 m0, s43, 0x2000
	s_nop 0
	global_load_lds_dwordx4 v[216:217], off
	v_lshl_add_u64 v[216:217], v[220:221], 0, s[16:17]
	s_mov_b32 m0, s55
	s_nop 0
	global_load_lds_dwordx4 v[216:217], off
	v_lshl_add_u64 v[216:217], v[222:223], 0, s[16:17]
	s_mov_b32 m0, s56
	s_nop 0
	global_load_lds_dwordx4 v[216:217], off
	s_waitcnt vmcnt(8) lgkmcnt(0)
	s_barrier
	v_mfma_f32_16x16x32_bf16 v[62:65], v[130:133], v[184:187], v[62:65]
	v_mfma_f32_16x16x32_bf16 v[58:61], v[138:141], v[184:187], v[58:61]
	v_mfma_f32_16x16x32_bf16 v[50:53], v[130:133], v[192:195], v[50:53]
	v_mfma_f32_16x16x32_bf16 v[42:45], v[138:141], v[192:195], v[42:45]
	v_mfma_f32_16x16x32_bf16 v[34:37], v[130:133], v[200:203], v[34:37]
	v_mfma_f32_16x16x32_bf16 v[26:29], v[138:141], v[200:203], v[26:29]
	v_mfma_f32_16x16x32_bf16 v[18:21], v[130:133], v[208:211], v[18:21]
	v_mfma_f32_16x16x32_bf16 v[10:13], v[138:141], v[208:211], v[10:13]
	v_mfma_f32_16x16x32_bf16 v[62:65], v[134:137], v[188:191], v[62:65]
	v_mfma_f32_16x16x32_bf16 v[58:61], v[142:145], v[188:191], v[58:61]
	v_mfma_f32_16x16x32_bf16 v[50:53], v[134:137], v[196:199], v[50:53]
	v_mfma_f32_16x16x32_bf16 v[42:45], v[142:145], v[196:199], v[42:45]
	v_mfma_f32_16x16x32_bf16 v[34:37], v[134:137], v[204:207], v[34:37]
	v_mfma_f32_16x16x32_bf16 v[26:29], v[142:145], v[204:207], v[26:29]
	v_mfma_f32_16x16x32_bf16 v[18:21], v[134:137], v[212:215], v[18:21]
	v_mfma_f32_16x16x32_bf16 v[10:13], v[142:145], v[212:215], v[10:13]
	v_mfma_f32_16x16x32_bf16 v[54:57], v[162:165], v[184:187], v[54:57]
	v_mfma_f32_16x16x32_bf16 v[46:49], v[176:179], v[184:187], v[46:49]
	v_mfma_f32_16x16x32_bf16 v[38:41], v[162:165], v[192:195], v[38:41]
	v_mfma_f32_16x16x32_bf16 v[30:33], v[176:179], v[192:195], v[30:33]
	v_mfma_f32_16x16x32_bf16 v[22:25], v[162:165], v[200:203], v[22:25]
	v_mfma_f32_16x16x32_bf16 v[14:17], v[176:179], v[200:203], v[14:17]
	v_mfma_f32_16x16x32_bf16 v[6:9], v[162:165], v[208:211], v[6:9]
	v_mfma_f32_16x16x32_bf16 v[2:5], v[176:179], v[208:211], v[2:5]
	v_mfma_f32_16x16x32_bf16 v[54:57], v[172:175], v[188:191], v[54:57]
	v_mfma_f32_16x16x32_bf16 v[46:49], v[180:183], v[188:191], v[46:49]
	v_mfma_f32_16x16x32_bf16 v[38:41], v[172:175], v[196:199], v[38:41]
	v_mfma_f32_16x16x32_bf16 v[30:33], v[180:183], v[196:199], v[30:33]
	v_mfma_f32_16x16x32_bf16 v[22:25], v[172:175], v[204:207], v[22:25]
	v_mfma_f32_16x16x32_bf16 v[14:17], v[180:183], v[204:207], v[14:17]
	v_mfma_f32_16x16x32_bf16 v[6:9], v[172:175], v[212:215], v[6:9]
	v_mfma_f32_16x16x32_bf16 v[2:5], v[180:183], v[212:215], v[2:5]
	s_barrier
	s_add_i32 s69, s69, 2
	s_add_u32 s2, s2, 0x100
	s_addc_u32 s3, s3, 0
	s_add_u32 s67, s67, 0x100
	s_addc_u32 s68, s68, 0
	s_cmp_gt_u32 s69, 61
	s_cbranch_scc0 .LBB0_1521
	s_setprio 0
	s_and_b64 vcc, exec, s[18:19]
	s_cbranch_vccz .LBB0_1524
	s_barrier

.LBB0_1696:
	s_ashr_i32 s49, s48, 31
	s_lshl_b64 s[50:51], s[48:49], 20
	s_add_u32 s50, s62, s50
	s_addc_u32 s51, s63, s51
	s_and_b64 s[52:53], s[0:1], exec
	s_cselect_b32 s49, s51, s3
	s_cselect_b32 s87, s50, s2
	s_ashr_i32 s47, s46, 31
	s_lshl_b64 s[52:53], s[46:47], 20
	s_add_u32 s52, s8, s52
	s_addc_u32 s53, s9, s53
	s_and_b64 s[58:59], s[0:1], exec
	s_cselect_b32 s47, s53, s57
	s_cselect_b32 s88, s52, s56
	s_add_u32 s89, s56, 0x100
	v_mov_b32_e32 v34, 0
	s_addc_u32 s90, s57, 0
	s_mov_b32 s91, -2
	v_mov_b32_e32 v35, v34
	v_mov_b32_e32 v36, v34
	v_mov_b32_e32 v37, v34
	v_mov_b32_e32 v38, v34
	v_mov_b32_e32 v39, v34
	v_mov_b32_e32 v40, v34
	v_mov_b32_e32 v41, v34
	v_mov_b32_e32 v46, v34
	v_mov_b32_e32 v47, v34
	v_mov_b32_e32 v48, v34
	v_mov_b32_e32 v49, v34
	v_mov_b32_e32 v54, v34
	v_mov_b32_e32 v55, v34
	v_mov_b32_e32 v56, v34
	v_mov_b32_e32 v57, v34
	v_mov_b32_e32 v2, v34
	v_mov_b32_e32 v3, v34
	v_mov_b32_e32 v4, v34
	v_mov_b32_e32 v5, v34
	v_mov_b32_e32 v42, v34
	v_mov_b32_e32 v43, v34
	v_mov_b32_e32 v44, v34
	v_mov_b32_e32 v45, v34
	v_mov_b32_e32 v6, v34
	v_mov_b32_e32 v7, v34
	v_mov_b32_e32 v8, v34
	v_mov_b32_e32 v9, v34
	v_mov_b32_e32 v50, v34
	v_mov_b32_e32 v51, v34
	v_mov_b32_e32 v52, v34
	v_mov_b32_e32 v53, v34
	v_mov_b32_e32 v82, v34
	v_mov_b32_e32 v83, v34
	v_mov_b32_e32 v84, v34
	v_mov_b32_e32 v85, v34
	v_mov_b32_e32 v86, v34
	v_mov_b32_e32 v87, v34
	v_mov_b32_e32 v88, v34
	v_mov_b32_e32 v89, v34
	v_mov_b32_e32 v106, v34
	v_mov_b32_e32 v107, v34
	v_mov_b32_e32 v108, v34
	v_mov_b32_e32 v109, v34
	v_mov_b32_e32 v114, v34
	v_mov_b32_e32 v115, v34
	v_mov_b32_e32 v116, v34
	v_mov_b32_e32 v117, v34
	v_mov_b32_e32 v10, v34
	v_mov_b32_e32 v11, v34
	v_mov_b32_e32 v12, v34
	v_mov_b32_e32 v13, v34
	v_mov_b32_e32 v58, v34
	v_mov_b32_e32 v59, v34
	v_mov_b32_e32 v60, v34
	v_mov_b32_e32 v61, v34
	v_mov_b32_e32 v14, v34
	v_mov_b32_e32 v15, v34
	v_mov_b32_e32 v16, v34
	v_mov_b32_e32 v17, v34
	v_mov_b32_e32 v62, v34
	v_mov_b32_e32 v63, v34
	v_mov_b32_e32 v64, v34
	v_mov_b32_e32 v65, v34
	v_mov_b32_e32 v18, v34
	v_mov_b32_e32 v19, v34
	v_mov_b32_e32 v20, v34
	v_mov_b32_e32 v21, v34
	v_mov_b32_e32 v66, v34
	v_mov_b32_e32 v67, v34
	v_mov_b32_e32 v68, v34
	v_mov_b32_e32 v69, v34
	v_mov_b32_e32 v22, v34
	v_mov_b32_e32 v23, v34
	v_mov_b32_e32 v24, v34
	v_mov_b32_e32 v25, v34
	v_mov_b32_e32 v70, v34
	v_mov_b32_e32 v71, v34
	v_mov_b32_e32 v72, v34
	v_mov_b32_e32 v73, v34
	v_mov_b32_e32 v90, v34
	v_mov_b32_e32 v91, v34
	v_mov_b32_e32 v92, v34
	v_mov_b32_e32 v93, v34
	v_mov_b32_e32 v94, v34
	v_mov_b32_e32 v95, v34
	v_mov_b32_e32 v96, v34
	v_mov_b32_e32 v97, v34
	v_mov_b32_e32 v98, v34
	v_mov_b32_e32 v99, v34
	v_mov_b32_e32 v100, v34
	v_mov_b32_e32 v101, v34
	v_mov_b32_e32 v102, v34
	v_mov_b32_e32 v103, v34
	v_mov_b32_e32 v104, v34
	v_mov_b32_e32 v105, v34
	v_mov_b32_e32 v26, v34
	v_mov_b32_e32 v27, v34
	v_mov_b32_e32 v28, v34
	v_mov_b32_e32 v29, v34
	v_mov_b32_e32 v74, v34
	v_mov_b32_e32 v75, v34
	v_mov_b32_e32 v76, v34
	v_mov_b32_e32 v77, v34
	v_mov_b32_e32 v30, v34
	v_mov_b32_e32 v31, v34
	v_mov_b32_e32 v32, v34
	v_mov_b32_e32 v33, v34
	v_mov_b32_e32 v78, v34
	v_mov_b32_e32 v79, v34
	v_mov_b32_e32 v80, v34
	v_mov_b32_e32 v81, v34
	v_mov_b32_e32 v110, v34
	v_mov_b32_e32 v111, v34
	v_mov_b32_e32 v112, v34
	v_mov_b32_e32 v113, v34
	v_mov_b32_e32 v118, v34
	v_mov_b32_e32 v119, v34
	v_mov_b32_e32 v120, v34
	v_mov_b32_e32 v121, v34
	v_mov_b32_e32 v122, v34
	v_mov_b32_e32 v123, v34
	v_mov_b32_e32 v124, v34
	v_mov_b32_e32 v125, v34
	v_mov_b32_e32 v126, v34
	v_mov_b32_e32 v127, v34
	v_mov_b32_e32 v128, v34
	v_mov_b32_e32 v129, v34
	s_and_b64 vcc, exec, s[38:39]
	s_cbranch_vccnz .Lsp_lead_1
	s_setprio 1
.Lsp_lead_1:
.LBB0_1697:
	ds_read_b128 v[130:133], v238
	ds_read_b128 v[134:137], v238 offset:1024
	ds_read_b128 v[138:141], v238 offset:2048
	ds_read_b128 v[142:145], v238 offset:3072
	ds_read_b128 v[146:149], v239
	ds_read_b128 v[150:153], v239 offset:1024
	ds_read_b128 v[154:157], v239 offset:2048
	ds_read_b128 v[158:161], v239 offset:3072
	s_add_u32 s56, s2, 0x100
	s_addc_u32 s57, s3, 0
	s_cmp_eq_u32 s91, 28
	s_cselect_b32 s61, s49, s57
	s_cselect_b32 s60, s87, s56
	s_cselect_b32 s59, s47, s90
	s_cselect_b32 s58, s88, s89
	v_lshl_add_u64 v[194:195], s[2:3], 0, v[210:211]
	s_add_i32 m0, s55, 0xc000
	ds_read_b128 v[162:165], v240
	ds_read_b128 v[166:169], v240 offset:1024
	ds_read_b128 v[170:173], v240 offset:2048
	ds_read_b128 v[174:177], v240 offset:3072
	ds_read_b128 v[178:181], v240 offset:4096
	ds_read_b128 v[182:185], v240 offset:5120
	ds_read_b128 v[186:189], v240 offset:6144
	ds_read_b128 v[190:193], v240 offset:7168
	global_load_lds_dwordx4 v[194:195], off
	v_lshl_add_u64 v[194:195], s[2:3], 0, v[212:213]
	s_add_i32 m0, s55, 0xe000
	s_nop 0
	global_load_lds_dwordx4 v[194:195], off
	s_waitcnt vmcnt(8) lgkmcnt(0)
	s_barrier
	v_mfma_i32_16x16x64_i8 v[126:129], v[130:133], v[162:165], v[126:129]
	v_mfma_i32_16x16x64_i8 v[122:125], v[138:141], v[162:165], v[122:125]
	v_mfma_i32_16x16x64_i8 v[118:121], v[130:133], v[170:173], v[118:121]
	v_mfma_i32_16x16x64_i8 v[110:113], v[138:141], v[170:173], v[110:113]
	v_mfma_i32_16x16x64_i8 v[78:81], v[130:133], v[178:181], v[78:81]
	v_mfma_i32_16x16x64_i8 v[30:33], v[138:141], v[178:181], v[30:33]
	v_mfma_i32_16x16x64_i8 v[74:77], v[130:133], v[186:189], v[74:77]
	v_mfma_i32_16x16x64_i8 v[26:29], v[138:141], v[186:189], v[26:29]
	v_mfma_i32_16x16x64_i8 v[126:129], v[134:137], v[166:169], v[126:129]
	v_mfma_i32_16x16x64_i8 v[122:125], v[142:145], v[166:169], v[122:125]
	v_mfma_i32_16x16x64_i8 v[118:121], v[134:137], v[174:177], v[118:121]
	v_mfma_i32_16x16x64_i8 v[110:113], v[142:145], v[174:177], v[110:113]
	v_mfma_i32_16x16x64_i8 v[78:81], v[134:137], v[182:185], v[78:81]
	v_mfma_i32_16x16x64_i8 v[30:33], v[142:145], v[182:185], v[30:33]
	v_mfma_i32_16x16x64_i8 v[74:77], v[134:137], v[190:193], v[74:77]
	v_mfma_i32_16x16x64_i8 v[26:29], v[142:145], v[190:193], v[26:29]
	v_mfma_i32_16x16x64_i8 v[102:105], v[146:149], v[162:165], v[102:105]
	v_mfma_i32_16x16x64_i8 v[98:101], v[154:157], v[162:165], v[98:101]
	v_mfma_i32_16x16x64_i8 v[94:97], v[146:149], v[170:173], v[94:97]
	v_mfma_i32_16x16x64_i8 v[90:93], v[154:157], v[170:173], v[90:93]
	v_mfma_i32_16x16x64_i8 v[70:73], v[146:149], v[178:181], v[70:73]
	v_mfma_i32_16x16x64_i8 v[22:25], v[154:157], v[178:181], v[22:25]
	v_mfma_i32_16x16x64_i8 v[66:69], v[146:149], v[186:189], v[66:69]
	v_mfma_i32_16x16x64_i8 v[18:21], v[154:157], v[186:189], v[18:21]
	v_mfma_i32_16x16x64_i8 v[102:105], v[150:153], v[166:169], v[102:105]
	v_mfma_i32_16x16x64_i8 v[98:101], v[158:161], v[166:169], v[98:101]
	v_mfma_i32_16x16x64_i8 v[94:97], v[150:153], v[174:177], v[94:97]
	v_mfma_i32_16x16x64_i8 v[90:93], v[158:161], v[174:177], v[90:93]
	v_mfma_i32_16x16x64_i8 v[70:73], v[150:153], v[182:185], v[70:73]
	v_mfma_i32_16x16x64_i8 v[22:25], v[158:161], v[182:185], v[22:25]
	v_mfma_i32_16x16x64_i8 v[66:69], v[150:153], v[190:193], v[66:69]
	v_mfma_i32_16x16x64_i8 v[18:21], v[158:161], v[190:193], v[18:21]
	s_barrier
	s_add_i32 s2, s83, s66
	v_lshl_add_u64 v[194:195], s[58:59], 0, v[206:207]
	s_mov_b32 m0, s2
	ds_read_b128 v[162:165], v240 offset:16384
	ds_read_b128 v[166:169], v240 offset:17408
	ds_read_b128 v[170:173], v240 offset:18432
	ds_read_b128 v[174:177], v240 offset:19456
	ds_read_b128 v[178:181], v240 offset:20480
	ds_read_b128 v[182:185], v240 offset:21504
	ds_read_b128 v[186:189], v240 offset:22528
	ds_read_b128 v[190:193], v240 offset:23552
	global_load_lds_dwordx4 v[194:195], off
	s_add_i32 m0, s2, 0x2000
	s_add_u32 s2, s58, 0x80000
	v_lshl_add_u64 v[196:197], s[58:59], 0, v[202:203]
	s_addc_u32 s3, s59, 0
	s_add_i32 s43, s84, s66
	global_load_lds_dwordx4 v[196:197], off
	v_lshl_add_u64 v[198:199], s[2:3], 0, v[206:207]
	s_mov_b32 m0, s43
	v_lshl_add_u64 v[200:201], s[60:61], 0, v[204:205]
	global_load_lds_dwordx4 v[198:199], off
	v_lshl_add_u64 v[198:199], s[2:3], 0, v[202:203]
	s_add_i32 m0, s43, 0x2000
	s_nop 0
	global_load_lds_dwordx4 v[198:199], off
	v_lshl_add_u64 v[198:199], s[60:61], 0, v[208:209]
	s_mov_b32 m0, s55
	s_nop 0
	global_load_lds_dwordx4 v[198:199], off
	s_mov_b32 m0, s68
	s_nop 0
	global_load_lds_dwordx4 v[200:201], off
	s_waitcnt vmcnt(8) lgkmcnt(0)
	s_barrier
	v_mfma_i32_16x16x64_i8 v[62:65], v[130:133], v[162:165], v[62:65]
	v_mfma_i32_16x16x64_i8 v[14:17], v[138:141], v[162:165], v[14:17]
	v_mfma_i32_16x16x64_i8 v[58:61], v[130:133], v[170:173], v[58:61]
	v_mfma_i32_16x16x64_i8 v[10:13], v[138:141], v[170:173], v[10:13]
	v_mfma_i32_16x16x64_i8 v[114:117], v[130:133], v[178:181], v[114:117]
	v_mfma_i32_16x16x64_i8 v[106:109], v[138:141], v[178:181], v[106:109]
	v_mfma_i32_16x16x64_i8 v[86:89], v[130:133], v[186:189], v[86:89]
	v_mfma_i32_16x16x64_i8 v[82:85], v[138:141], v[186:189], v[82:85]
	v_mfma_i32_16x16x64_i8 v[62:65], v[134:137], v[166:169], v[62:65]
	v_mfma_i32_16x16x64_i8 v[14:17], v[142:145], v[166:169], v[14:17]
	v_mfma_i32_16x16x64_i8 v[58:61], v[134:137], v[174:177], v[58:61]
	v_mfma_i32_16x16x64_i8 v[10:13], v[142:145], v[174:177], v[10:13]
	v_mfma_i32_16x16x64_i8 v[114:117], v[134:137], v[182:185], v[114:117]
	v_mfma_i32_16x16x64_i8 v[106:109], v[142:145], v[182:185], v[106:109]
	v_mfma_i32_16x16x64_i8 v[86:89], v[134:137], v[190:193], v[86:89]
	v_mfma_i32_16x16x64_i8 v[82:85], v[142:145], v[190:193], v[82:85]
	v_mfma_i32_16x16x64_i8 v[50:53], v[146:149], v[162:165], v[50:53]
	v_mfma_i32_16x16x64_i8 v[6:9], v[154:157], v[162:165], v[6:9]
	v_mfma_i32_16x16x64_i8 v[42:45], v[146:149], v[170:173], v[42:45]
	v_mfma_i32_16x16x64_i8 v[2:5], v[154:157], v[170:173], v[2:5]
	v_mfma_i32_16x16x64_i8 v[54:57], v[146:149], v[178:181], v[54:57]
	v_mfma_i32_16x16x64_i8 v[46:49], v[154:157], v[178:181], v[46:49]
	v_mfma_i32_16x16x64_i8 v[38:41], v[146:149], v[186:189], v[38:41]
	v_mfma_i32_16x16x64_i8 v[34:37], v[154:157], v[186:189], v[34:37]
	v_mfma_i32_16x16x64_i8 v[50:53], v[150:153], v[166:169], v[50:53]
	v_mfma_i32_16x16x64_i8 v[6:9], v[158:161], v[166:169], v[6:9]
	v_mfma_i32_16x16x64_i8 v[42:45], v[150:153], v[174:177], v[42:45]
	v_mfma_i32_16x16x64_i8 v[2:5], v[158:161], v[174:177], v[2:5]
	v_mfma_i32_16x16x64_i8 v[54:57], v[150:153], v[182:185], v[54:57]
	v_mfma_i32_16x16x64_i8 v[46:49], v[158:161], v[182:185], v[46:49]
	v_mfma_i32_16x16x64_i8 v[38:41], v[150:153], v[190:193], v[38:41]
	v_mfma_i32_16x16x64_i8 v[34:37], v[158:161], v[190:193], v[34:37]
	s_barrier
	s_add_i32 s43, 0, 0x18000
	s_add_i32 s92, 0, 0x1c000
	v_add_u32_e32 v142, s43, v237
	v_add_u32_e32 v158, s92, v237
	ds_read_b128 v[130:133], v142
	ds_read_b128 v[134:137], v142 offset:1024
	ds_read_b128 v[138:141], v142 offset:2048
	ds_read_b128 v[142:145], v142 offset:3072
	ds_read_b128 v[146:149], v158
	ds_read_b128 v[150:153], v158 offset:1024
	ds_read_b128 v[154:157], v158 offset:2048
	ds_read_b128 v[158:161], v158 offset:3072
	s_add_u32 s2, s60, 0x4000
	s_addc_u32 s3, s61, 0
	s_mov_b32 m0, s69
	v_lshl_add_u64 v[220:221], s[2:3], 0, v[208:209]
	ds_read_b128 v[162:165], v240 offset:32768
	ds_read_b128 v[166:169], v240 offset:33792
	ds_read_b128 v[170:173], v240 offset:34816
	ds_read_b128 v[174:177], v240 offset:35840
	ds_read_b128 v[178:181], v240 offset:36864
	ds_read_b128 v[182:185], v240 offset:37888
	ds_read_b128 v[186:189], v240 offset:38912
	ds_read_b128 v[190:193], v240 offset:39936
	global_load_lds_dwordx4 v[220:221], off
	v_lshl_add_u64 v[220:221], s[2:3], 0, v[204:205]
	s_mov_b32 m0, s70
	s_nop 0
	global_load_lds_dwordx4 v[220:221], off
	s_waitcnt vmcnt(8) lgkmcnt(0)
	s_barrier
	v_mfma_i32_16x16x64_i8 v[126:129], v[130:133], v[162:165], v[126:129]
	v_mfma_i32_16x16x64_i8 v[122:125], v[138:141], v[162:165], v[122:125]
	v_mfma_i32_16x16x64_i8 v[118:121], v[130:133], v[170:173], v[118:121]
	v_mfma_i32_16x16x64_i8 v[110:113], v[138:141], v[170:173], v[110:113]
	v_mfma_i32_16x16x64_i8 v[78:81], v[130:133], v[178:181], v[78:81]
	v_mfma_i32_16x16x64_i8 v[30:33], v[138:141], v[178:181], v[30:33]
	v_mfma_i32_16x16x64_i8 v[74:77], v[130:133], v[186:189], v[74:77]
	v_mfma_i32_16x16x64_i8 v[26:29], v[138:141], v[186:189], v[26:29]
	v_mfma_i32_16x16x64_i8 v[126:129], v[134:137], v[166:169], v[126:129]
	v_mfma_i32_16x16x64_i8 v[122:125], v[142:145], v[166:169], v[122:125]
	v_mfma_i32_16x16x64_i8 v[118:121], v[134:137], v[174:177], v[118:121]
	v_mfma_i32_16x16x64_i8 v[110:113], v[142:145], v[174:177], v[110:113]
	v_mfma_i32_16x16x64_i8 v[78:81], v[134:137], v[182:185], v[78:81]
	v_mfma_i32_16x16x64_i8 v[30:33], v[142:145], v[182:185], v[30:33]
	v_mfma_i32_16x16x64_i8 v[74:77], v[134:137], v[190:193], v[74:77]
	v_mfma_i32_16x16x64_i8 v[26:29], v[142:145], v[190:193], v[26:29]
	v_mfma_i32_16x16x64_i8 v[102:105], v[146:149], v[162:165], v[102:105]
	v_mfma_i32_16x16x64_i8 v[98:101], v[154:157], v[162:165], v[98:101]
	v_mfma_i32_16x16x64_i8 v[94:97], v[146:149], v[170:173], v[94:97]
	v_mfma_i32_16x16x64_i8 v[90:93], v[154:157], v[170:173], v[90:93]
	v_mfma_i32_16x16x64_i8 v[70:73], v[146:149], v[178:181], v[70:73]
	v_mfma_i32_16x16x64_i8 v[22:25], v[154:157], v[178:181], v[22:25]
	v_mfma_i32_16x16x64_i8 v[66:69], v[146:149], v[186:189], v[66:69]
	v_mfma_i32_16x16x64_i8 v[18:21], v[154:157], v[186:189], v[18:21]
	v_mfma_i32_16x16x64_i8 v[102:105], v[150:153], v[166:169], v[102:105]
	v_mfma_i32_16x16x64_i8 v[98:101], v[158:161], v[166:169], v[98:101]
	v_mfma_i32_16x16x64_i8 v[94:97], v[150:153], v[174:177], v[94:97]
	v_mfma_i32_16x16x64_i8 v[90:93], v[158:161], v[174:177], v[90:93]
	v_mfma_i32_16x16x64_i8 v[70:73], v[150:153], v[182:185], v[70:73]
	v_mfma_i32_16x16x64_i8 v[22:25], v[158:161], v[182:185], v[22:25]
	v_mfma_i32_16x16x64_i8 v[66:69], v[150:153], v[190:193], v[66:69]
	v_mfma_i32_16x16x64_i8 v[18:21], v[158:161], v[190:193], v[18:21]
	s_barrier
	s_add_i32 s2, s43, s66
	v_lshl_add_u64 v[194:195], v[194:195], 0, s[36:37]
	s_mov_b32 m0, s2
	ds_read_b128 v[162:165], v240 offset:49152
	ds_read_b128 v[166:169], v240 offset:50176
	ds_read_b128 v[170:173], v240 offset:51200
	ds_read_b128 v[174:177], v240 offset:52224
	ds_read_b128 v[178:181], v240 offset:53248
	ds_read_b128 v[182:185], v240 offset:54272
	ds_read_b128 v[186:189], v240 offset:55296
	ds_read_b128 v[190:193], v240 offset:56320
	global_load_lds_dwordx4 v[194:195], off
	s_add_i32 m0, s2, 0x2000
	s_add_u32 s2, s58, 0x80080
	v_lshl_add_u64 v[194:195], v[196:197], 0, s[36:37]
	s_addc_u32 s3, s59, 0
	s_add_i32 s43, s92, s66
	global_load_lds_dwordx4 v[194:195], off
	v_lshl_add_u64 v[194:195], s[2:3], 0, v[206:207]
	s_mov_b32 m0, s43
	s_nop 0
	global_load_lds_dwordx4 v[194:195], off
	v_lshl_add_u64 v[194:195], s[2:3], 0, v[202:203]
	s_add_i32 m0, s43, 0x2000
	s_nop 0
	global_load_lds_dwordx4 v[194:195], off
	v_lshl_add_u64 v[194:195], v[198:199], 0, s[36:37]
	s_mov_b32 m0, s77
	s_nop 0
	global_load_lds_dwordx4 v[194:195], off
	v_lshl_add_u64 v[194:195], v[200:201], 0, s[36:37]
	s_mov_b32 m0, s78
	s_nop 0
	global_load_lds_dwordx4 v[194:195], off
	s_waitcnt vmcnt(8) lgkmcnt(0)
	s_barrier
	v_mfma_i32_16x16x64_i8 v[62:65], v[130:133], v[162:165], v[62:65]
	v_mfma_i32_16x16x64_i8 v[14:17], v[138:141], v[162:165], v[14:17]
	v_mfma_i32_16x16x64_i8 v[58:61], v[130:133], v[170:173], v[58:61]
	v_mfma_i32_16x16x64_i8 v[10:13], v[138:141], v[170:173], v[10:13]
	v_mfma_i32_16x16x64_i8 v[114:117], v[130:133], v[178:181], v[114:117]
	v_mfma_i32_16x16x64_i8 v[106:109], v[138:141], v[178:181], v[106:109]
	v_mfma_i32_16x16x64_i8 v[86:89], v[130:133], v[186:189], v[86:89]
	v_mfma_i32_16x16x64_i8 v[82:85], v[138:141], v[186:189], v[82:85]
	v_mfma_i32_16x16x64_i8 v[62:65], v[134:137], v[166:169], v[62:65]
	v_mfma_i32_16x16x64_i8 v[14:17], v[142:145], v[166:169], v[14:17]
	v_mfma_i32_16x16x64_i8 v[58:61], v[134:137], v[174:177], v[58:61]
	v_mfma_i32_16x16x64_i8 v[10:13], v[142:145], v[174:177], v[10:13]
	v_mfma_i32_16x16x64_i8 v[114:117], v[134:137], v[182:185], v[114:117]
	v_mfma_i32_16x16x64_i8 v[106:109], v[142:145], v[182:185], v[106:109]
	v_mfma_i32_16x16x64_i8 v[86:89], v[134:137], v[190:193], v[86:89]
	v_mfma_i32_16x16x64_i8 v[82:85], v[142:145], v[190:193], v[82:85]
	v_mfma_i32_16x16x64_i8 v[50:53], v[146:149], v[162:165], v[50:53]
	v_mfma_i32_16x16x64_i8 v[6:9], v[154:157], v[162:165], v[6:9]
	v_mfma_i32_16x16x64_i8 v[42:45], v[146:149], v[170:173], v[42:45]
	v_mfma_i32_16x16x64_i8 v[2:5], v[154:157], v[170:173], v[2:5]
	v_mfma_i32_16x16x64_i8 v[54:57], v[146:149], v[178:181], v[54:57]
	v_mfma_i32_16x16x64_i8 v[46:49], v[154:157], v[178:181], v[46:49]
	v_mfma_i32_16x16x64_i8 v[38:41], v[146:149], v[186:189], v[38:41]
	v_mfma_i32_16x16x64_i8 v[34:37], v[154:157], v[186:189], v[34:37]
	v_mfma_i32_16x16x64_i8 v[50:53], v[150:153], v[166:169], v[50:53]
	v_mfma_i32_16x16x64_i8 v[6:9], v[158:161], v[166:169], v[6:9]
	v_mfma_i32_16x16x64_i8 v[42:45], v[150:153], v[174:177], v[42:45]
	v_mfma_i32_16x16x64_i8 v[2:5], v[158:161], v[174:177], v[2:5]
	v_mfma_i32_16x16x64_i8 v[54:57], v[150:153], v[182:185], v[54:57]
	v_mfma_i32_16x16x64_i8 v[46:49], v[158:161], v[182:185], v[46:49]
	v_mfma_i32_16x16x64_i8 v[38:41], v[150:153], v[190:193], v[38:41]
	v_mfma_i32_16x16x64_i8 v[34:37], v[158:161], v[190:193], v[34:37]
	s_barrier
	s_add_i32 s91, s91, 2
	s_add_u32 s89, s89, 0x100
	s_addc_u32 s90, s90, 0
	s_cmp_gt_u32 s91, 29
	s_mov_b64 s[2:3], s[56:57]
	s_cbranch_scc0 .LBB0_1697
	s_setprio 0
	s_and_b64 vcc, exec, s[38:39]
	s_cbranch_vccz .LBB0_1700
	s_barrier

.LBB0_1950:
	s_add_u32 s75, s38, 0x100
	v_mov_b32_e32 v2, 0
	s_addc_u32 s76, s39, 0
	s_mov_b32 s77, -2
	v_mov_b32_e32 v3, v2
	v_mov_b32_e32 v4, v2
	v_mov_b32_e32 v5, v2
	v_mov_b32_e32 v6, v2
	v_mov_b32_e32 v7, v2
	v_mov_b32_e32 v8, v2
	v_mov_b32_e32 v9, v2
	v_mov_b32_e32 v18, v2
	v_mov_b32_e32 v19, v2
	v_mov_b32_e32 v20, v2
	v_mov_b32_e32 v21, v2
	v_mov_b32_e32 v22, v2
	v_mov_b32_e32 v23, v2
	v_mov_b32_e32 v24, v2
	v_mov_b32_e32 v25, v2
	v_mov_b32_e32 v34, v2
	v_mov_b32_e32 v35, v2
	v_mov_b32_e32 v36, v2
	v_mov_b32_e32 v37, v2
	v_mov_b32_e32 v38, v2
	v_mov_b32_e32 v39, v2
	v_mov_b32_e32 v40, v2
	v_mov_b32_e32 v41, v2
	v_mov_b32_e32 v50, v2
	v_mov_b32_e32 v51, v2
	v_mov_b32_e32 v52, v2
	v_mov_b32_e32 v53, v2
	v_mov_b32_e32 v54, v2
	v_mov_b32_e32 v55, v2
	v_mov_b32_e32 v56, v2
	v_mov_b32_e32 v57, v2
	v_mov_b32_e32 v10, v2
	v_mov_b32_e32 v11, v2
	v_mov_b32_e32 v12, v2
	v_mov_b32_e32 v13, v2
	v_mov_b32_e32 v14, v2
	v_mov_b32_e32 v15, v2
	v_mov_b32_e32 v16, v2
	v_mov_b32_e32 v17, v2
	v_mov_b32_e32 v26, v2
	v_mov_b32_e32 v27, v2
	v_mov_b32_e32 v28, v2
	v_mov_b32_e32 v29, v2
	v_mov_b32_e32 v30, v2
	v_mov_b32_e32 v31, v2
	v_mov_b32_e32 v32, v2
	v_mov_b32_e32 v33, v2
	v_mov_b32_e32 v42, v2
	v_mov_b32_e32 v43, v2
	v_mov_b32_e32 v44, v2
	v_mov_b32_e32 v45, v2
	v_mov_b32_e32 v46, v2
	v_mov_b32_e32 v47, v2
	v_mov_b32_e32 v48, v2
	v_mov_b32_e32 v49, v2
	v_mov_b32_e32 v58, v2
	v_mov_b32_e32 v59, v2
	v_mov_b32_e32 v60, v2
	v_mov_b32_e32 v61, v2
	v_mov_b32_e32 v62, v2
	v_mov_b32_e32 v63, v2
	v_mov_b32_e32 v64, v2
	v_mov_b32_e32 v65, v2
	v_mov_b32_e32 v66, v2
	v_mov_b32_e32 v67, v2
	v_mov_b32_e32 v68, v2
	v_mov_b32_e32 v69, v2
	v_mov_b32_e32 v70, v2
	v_mov_b32_e32 v71, v2
	v_mov_b32_e32 v72, v2
	v_mov_b32_e32 v73, v2
	v_mov_b32_e32 v82, v2
	v_mov_b32_e32 v83, v2
	v_mov_b32_e32 v84, v2
	v_mov_b32_e32 v85, v2
	v_mov_b32_e32 v86, v2
	v_mov_b32_e32 v87, v2
	v_mov_b32_e32 v88, v2
	v_mov_b32_e32 v89, v2
	v_mov_b32_e32 v98, v2
	v_mov_b32_e32 v99, v2
	v_mov_b32_e32 v100, v2
	v_mov_b32_e32 v101, v2
	v_mov_b32_e32 v102, v2
	v_mov_b32_e32 v103, v2
	v_mov_b32_e32 v104, v2
	v_mov_b32_e32 v105, v2
	v_mov_b32_e32 v114, v2
	v_mov_b32_e32 v115, v2
	v_mov_b32_e32 v116, v2
	v_mov_b32_e32 v117, v2
	v_mov_b32_e32 v118, v2
	v_mov_b32_e32 v119, v2
	v_mov_b32_e32 v120, v2
	v_mov_b32_e32 v121, v2
	v_mov_b32_e32 v74, v2
	v_mov_b32_e32 v75, v2
	v_mov_b32_e32 v76, v2
	v_mov_b32_e32 v77, v2
	v_mov_b32_e32 v78, v2
	v_mov_b32_e32 v79, v2
	v_mov_b32_e32 v80, v2
	v_mov_b32_e32 v81, v2
	v_mov_b32_e32 v90, v2
	v_mov_b32_e32 v91, v2
	v_mov_b32_e32 v92, v2
	v_mov_b32_e32 v93, v2
	v_mov_b32_e32 v94, v2
	v_mov_b32_e32 v95, v2
	v_mov_b32_e32 v96, v2
	v_mov_b32_e32 v97, v2
	v_mov_b32_e32 v106, v2
	v_mov_b32_e32 v107, v2
	v_mov_b32_e32 v108, v2
	v_mov_b32_e32 v109, v2
	v_mov_b32_e32 v110, v2
	v_mov_b32_e32 v111, v2
	v_mov_b32_e32 v112, v2
	v_mov_b32_e32 v113, v2
	v_mov_b32_e32 v122, v2
	v_mov_b32_e32 v123, v2
	v_mov_b32_e32 v124, v2
	v_mov_b32_e32 v125, v2
	v_mov_b32_e32 v126, v2
	v_mov_b32_e32 v127, v2
	v_mov_b32_e32 v128, v2
	v_mov_b32_e32 v129, v2
	s_and_b64 vcc, exec, s[16:17]
	s_cbranch_vccnz .Lsp_lead_0
	s_setprio 1
.Lsp_lead_0:
.LBB0_1951:
	ds_read_b128 v[130:133], v167
	ds_read_b128 v[134:137], v167 offset:1024
	ds_read_b128 v[138:141], v167 offset:2048
	ds_read_b128 v[142:145], v167 offset:3072
	ds_read_b128 v[170:173], v168
	ds_read_b128 v[174:177], v168 offset:1024
	ds_read_b128 v[178:181], v168 offset:2048
	ds_read_b128 v[182:185], v168 offset:3072
	s_add_u32 s38, s36, 0x100
	s_addc_u32 s39, s37, 0
	s_cmpk_eq_i32 s77, 0x52
	s_cselect_b32 s47, s3, s39
	s_cselect_b32 s46, s2, s38
	s_cselect_b32 s45, s35, s76
	s_cselect_b32 s44, s34, s75
	v_lshl_add_u64 v[162:163], s[36:37], 0, v[154:155]
	s_add_i32 m0, s52, 0xc000
	ds_read_b128 v[186:189], v169
	ds_read_b128 v[190:193], v169 offset:1024
	ds_read_b128 v[194:197], v169 offset:2048
	ds_read_b128 v[198:201], v169 offset:3072
	ds_read_b128 v[202:205], v169 offset:4096
	ds_read_b128 v[206:209], v169 offset:5120
	ds_read_b128 v[210:213], v169 offset:6144
	ds_read_b128 v[214:217], v169 offset:7168
	global_load_lds_dwordx4 v[162:163], off
	v_lshl_add_u64 v[162:163], s[36:37], 0, v[156:157]
	s_add_i32 m0, s52, 0xe000
	s_nop 0
	global_load_lds_dwordx4 v[162:163], off
	s_waitcnt vmcnt(8) lgkmcnt(0)
	s_barrier
	v_mfma_i32_16x16x64_i8 v[126:129], v[130:133], v[186:189], v[126:129]
	v_mfma_i32_16x16x64_i8 v[122:125], v[138:141], v[186:189], v[122:125]
	v_mfma_i32_16x16x64_i8 v[110:113], v[130:133], v[194:197], v[110:113]
	v_mfma_i32_16x16x64_i8 v[106:109], v[138:141], v[194:197], v[106:109]
	v_mfma_i32_16x16x64_i8 v[94:97], v[130:133], v[202:205], v[94:97]
	v_mfma_i32_16x16x64_i8 v[90:93], v[138:141], v[202:205], v[90:93]
	v_mfma_i32_16x16x64_i8 v[78:81], v[130:133], v[210:213], v[78:81]
	v_mfma_i32_16x16x64_i8 v[74:77], v[138:141], v[210:213], v[74:77]
	v_mfma_i32_16x16x64_i8 v[126:129], v[134:137], v[190:193], v[126:129]
	v_mfma_i32_16x16x64_i8 v[122:125], v[142:145], v[190:193], v[122:125]
	v_mfma_i32_16x16x64_i8 v[110:113], v[134:137], v[198:201], v[110:113]
	v_mfma_i32_16x16x64_i8 v[106:109], v[142:145], v[198:201], v[106:109]
	v_mfma_i32_16x16x64_i8 v[94:97], v[134:137], v[206:209], v[94:97]
	v_mfma_i32_16x16x64_i8 v[90:93], v[142:145], v[206:209], v[90:93]
	v_mfma_i32_16x16x64_i8 v[78:81], v[134:137], v[214:217], v[78:81]
	v_mfma_i32_16x16x64_i8 v[74:77], v[142:145], v[214:217], v[74:77]
	v_mfma_i32_16x16x64_i8 v[118:121], v[170:173], v[186:189], v[118:121]
	v_mfma_i32_16x16x64_i8 v[114:117], v[178:181], v[186:189], v[114:117]
	v_mfma_i32_16x16x64_i8 v[102:105], v[170:173], v[194:197], v[102:105]
	v_mfma_i32_16x16x64_i8 v[98:101], v[178:181], v[194:197], v[98:101]
	v_mfma_i32_16x16x64_i8 v[86:89], v[170:173], v[202:205], v[86:89]
	v_mfma_i32_16x16x64_i8 v[82:85], v[178:181], v[202:205], v[82:85]
	v_mfma_i32_16x16x64_i8 v[70:73], v[170:173], v[210:213], v[70:73]
	v_mfma_i32_16x16x64_i8 v[66:69], v[178:181], v[210:213], v[66:69]
	v_mfma_i32_16x16x64_i8 v[118:121], v[174:177], v[190:193], v[118:121]
	v_mfma_i32_16x16x64_i8 v[114:117], v[182:185], v[190:193], v[114:117]
	v_mfma_i32_16x16x64_i8 v[102:105], v[174:177], v[198:201], v[102:105]
	v_mfma_i32_16x16x64_i8 v[98:101], v[182:185], v[198:201], v[98:101]
	v_mfma_i32_16x16x64_i8 v[86:89], v[174:177], v[206:209], v[86:89]
	v_mfma_i32_16x16x64_i8 v[82:85], v[182:185], v[206:209], v[82:85]
	v_mfma_i32_16x16x64_i8 v[70:73], v[174:177], v[214:217], v[70:73]
	v_mfma_i32_16x16x64_i8 v[66:69], v[182:185], v[214:217], v[66:69]
	s_barrier
	s_add_i32 s36, s61, s51
	v_lshl_add_u64 v[162:163], s[44:45], 0, v[150:151]
	s_mov_b32 m0, s36
	ds_read_b128 v[186:189], v169 offset:16384
	ds_read_b128 v[190:193], v169 offset:17408
	ds_read_b128 v[194:197], v169 offset:18432
	ds_read_b128 v[198:201], v169 offset:19456
	ds_read_b128 v[202:205], v169 offset:20480
	ds_read_b128 v[206:209], v169 offset:21504
	ds_read_b128 v[210:213], v169 offset:22528
	ds_read_b128 v[214:217], v169 offset:23552
	global_load_lds_dwordx4 v[162:163], off
	s_add_i32 m0, s36, 0x2000
	s_add_u32 s36, s44, 0x158000
	v_lshl_add_u64 v[218:219], s[44:45], 0, v[146:147]
	s_addc_u32 s37, s45, 0
	s_add_i32 s78, s62, s51
	global_load_lds_dwordx4 v[218:219], off
	v_lshl_add_u64 v[220:221], s[36:37], 0, v[150:151]
	s_mov_b32 m0, s78
	v_lshl_add_u64 v[222:223], s[46:47], 0, v[148:149]
	global_load_lds_dwordx4 v[220:221], off
	v_lshl_add_u64 v[220:221], s[36:37], 0, v[146:147]
	s_add_i32 m0, s78, 0x2000
	s_nop 0
	global_load_lds_dwordx4 v[220:221], off
	v_lshl_add_u64 v[220:221], s[46:47], 0, v[152:153]
	s_mov_b32 m0, s52
	s_nop 0
	global_load_lds_dwordx4 v[220:221], off
	s_mov_b32 m0, s53
	s_nop 0
	global_load_lds_dwordx4 v[222:223], off
	s_waitcnt vmcnt(8) lgkmcnt(0)
	s_barrier
	v_mfma_i32_16x16x64_i8 v[62:65], v[130:133], v[186:189], v[62:65]
	v_mfma_i32_16x16x64_i8 v[58:61], v[138:141], v[186:189], v[58:61]
	v_mfma_i32_16x16x64_i8 v[46:49], v[130:133], v[194:197], v[46:49]
	v_mfma_i32_16x16x64_i8 v[42:45], v[138:141], v[194:197], v[42:45]
	v_mfma_i32_16x16x64_i8 v[30:33], v[130:133], v[202:205], v[30:33]
	v_mfma_i32_16x16x64_i8 v[26:29], v[138:141], v[202:205], v[26:29]
	v_mfma_i32_16x16x64_i8 v[14:17], v[130:133], v[210:213], v[14:17]
	v_mfma_i32_16x16x64_i8 v[10:13], v[138:141], v[210:213], v[10:13]
	v_mfma_i32_16x16x64_i8 v[62:65], v[134:137], v[190:193], v[62:65]
	v_mfma_i32_16x16x64_i8 v[58:61], v[142:145], v[190:193], v[58:61]
	v_mfma_i32_16x16x64_i8 v[46:49], v[134:137], v[198:201], v[46:49]
	v_mfma_i32_16x16x64_i8 v[42:45], v[142:145], v[198:201], v[42:45]
	v_mfma_i32_16x16x64_i8 v[30:33], v[134:137], v[206:209], v[30:33]
	v_mfma_i32_16x16x64_i8 v[26:29], v[142:145], v[206:209], v[26:29]
	v_mfma_i32_16x16x64_i8 v[14:17], v[134:137], v[214:217], v[14:17]
	v_mfma_i32_16x16x64_i8 v[10:13], v[142:145], v[214:217], v[10:13]
	v_mfma_i32_16x16x64_i8 v[54:57], v[170:173], v[186:189], v[54:57]
	v_mfma_i32_16x16x64_i8 v[50:53], v[178:181], v[186:189], v[50:53]
	v_mfma_i32_16x16x64_i8 v[38:41], v[170:173], v[194:197], v[38:41]
	v_mfma_i32_16x16x64_i8 v[34:37], v[178:181], v[194:197], v[34:37]
	v_mfma_i32_16x16x64_i8 v[22:25], v[170:173], v[202:205], v[22:25]
	v_mfma_i32_16x16x64_i8 v[18:21], v[178:181], v[202:205], v[18:21]
	v_mfma_i32_16x16x64_i8 v[6:9], v[170:173], v[210:213], v[6:9]
	v_mfma_i32_16x16x64_i8 v[2:5], v[178:181], v[210:213], v[2:5]
	v_mfma_i32_16x16x64_i8 v[54:57], v[174:177], v[190:193], v[54:57]
	v_mfma_i32_16x16x64_i8 v[50:53], v[182:185], v[190:193], v[50:53]
	v_mfma_i32_16x16x64_i8 v[38:41], v[174:177], v[198:201], v[38:41]
	v_mfma_i32_16x16x64_i8 v[34:37], v[182:185], v[198:201], v[34:37]
	v_mfma_i32_16x16x64_i8 v[22:25], v[174:177], v[206:209], v[22:25]
	v_mfma_i32_16x16x64_i8 v[18:21], v[182:185], v[206:209], v[18:21]
	v_mfma_i32_16x16x64_i8 v[6:9], v[174:177], v[214:217], v[6:9]
	v_mfma_i32_16x16x64_i8 v[2:5], v[182:185], v[214:217], v[2:5]
	s_barrier
	s_add_i32 s78, 0, 0x18000
	s_add_i32 s79, 0, 0x1c000
	v_add_u32_e32 v142, s78, v166
	v_add_u32_e32 v182, s79, v166
	ds_read_b128 v[130:133], v142
	ds_read_b128 v[134:137], v142 offset:1024
	ds_read_b128 v[138:141], v142 offset:2048
	ds_read_b128 v[142:145], v142 offset:3072
	ds_read_b128 v[170:173], v182
	ds_read_b128 v[174:177], v182 offset:1024
	ds_read_b128 v[178:181], v182 offset:2048
	ds_read_b128 v[182:185], v182 offset:3072
	s_add_u32 s36, s46, 0x158000
	s_addc_u32 s37, s47, 0
	s_mov_b32 m0, s54
	v_lshl_add_u64 v[224:225], s[36:37], 0, v[152:153]
	ds_read_b128 v[186:189], v169 offset:32768
	ds_read_b128 v[190:193], v169 offset:33792
	ds_read_b128 v[194:197], v169 offset:34816
	ds_read_b128 v[198:201], v169 offset:35840
	ds_read_b128 v[202:205], v169 offset:36864
	ds_read_b128 v[206:209], v169 offset:37888
	ds_read_b128 v[210:213], v169 offset:38912
	ds_read_b128 v[214:217], v169 offset:39936
	global_load_lds_dwordx4 v[224:225], off
	v_lshl_add_u64 v[224:225], s[36:37], 0, v[148:149]
	s_mov_b32 m0, s55
	s_nop 0
	global_load_lds_dwordx4 v[224:225], off
	s_waitcnt vmcnt(8) lgkmcnt(0)
	s_barrier
	v_mfma_i32_16x16x64_i8 v[126:129], v[130:133], v[186:189], v[126:129]
	v_mfma_i32_16x16x64_i8 v[122:125], v[138:141], v[186:189], v[122:125]
	v_mfma_i32_16x16x64_i8 v[110:113], v[130:133], v[194:197], v[110:113]
	v_mfma_i32_16x16x64_i8 v[106:109], v[138:141], v[194:197], v[106:109]
	v_mfma_i32_16x16x64_i8 v[94:97], v[130:133], v[202:205], v[94:97]
	v_mfma_i32_16x16x64_i8 v[90:93], v[138:141], v[202:205], v[90:93]
	v_mfma_i32_16x16x64_i8 v[78:81], v[130:133], v[210:213], v[78:81]
	v_mfma_i32_16x16x64_i8 v[74:77], v[138:141], v[210:213], v[74:77]
	v_mfma_i32_16x16x64_i8 v[126:129], v[134:137], v[190:193], v[126:129]
	v_mfma_i32_16x16x64_i8 v[122:125], v[142:145], v[190:193], v[122:125]
	v_mfma_i32_16x16x64_i8 v[110:113], v[134:137], v[198:201], v[110:113]
	v_mfma_i32_16x16x64_i8 v[106:109], v[142:145], v[198:201], v[106:109]
	v_mfma_i32_16x16x64_i8 v[94:97], v[134:137], v[206:209], v[94:97]
	v_mfma_i32_16x16x64_i8 v[90:93], v[142:145], v[206:209], v[90:93]
	v_mfma_i32_16x16x64_i8 v[78:81], v[134:137], v[214:217], v[78:81]
	v_mfma_i32_16x16x64_i8 v[74:77], v[142:145], v[214:217], v[74:77]
	v_mfma_i32_16x16x64_i8 v[118:121], v[170:173], v[186:189], v[118:121]
	v_mfma_i32_16x16x64_i8 v[114:117], v[178:181], v[186:189], v[114:117]
	v_mfma_i32_16x16x64_i8 v[102:105], v[170:173], v[194:197], v[102:105]
	v_mfma_i32_16x16x64_i8 v[98:101], v[178:181], v[194:197], v[98:101]
	v_mfma_i32_16x16x64_i8 v[86:89], v[170:173], v[202:205], v[86:89]
	v_mfma_i32_16x16x64_i8 v[82:85], v[178:181], v[202:205], v[82:85]
	v_mfma_i32_16x16x64_i8 v[70:73], v[170:173], v[210:213], v[70:73]
	v_mfma_i32_16x16x64_i8 v[66:69], v[178:181], v[210:213], v[66:69]
	v_mfma_i32_16x16x64_i8 v[118:121], v[174:177], v[190:193], v[118:121]
	v_mfma_i32_16x16x64_i8 v[114:117], v[182:185], v[190:193], v[114:117]
	v_mfma_i32_16x16x64_i8 v[102:105], v[174:177], v[198:201], v[102:105]
	v_mfma_i32_16x16x64_i8 v[98:101], v[182:185], v[198:201], v[98:101]
	v_mfma_i32_16x16x64_i8 v[86:89], v[174:177], v[206:209], v[86:89]
	v_mfma_i32_16x16x64_i8 v[82:85], v[182:185], v[206:209], v[82:85]
	v_mfma_i32_16x16x64_i8 v[70:73], v[174:177], v[214:217], v[70:73]
	v_mfma_i32_16x16x64_i8 v[66:69], v[182:185], v[214:217], v[66:69]
	s_barrier
	s_add_i32 s36, s78, s51
	v_lshl_add_u64 v[162:163], v[162:163], 0, s[14:15]
	s_mov_b32 m0, s36
	ds_read_b128 v[186:189], v169 offset:49152
	ds_read_b128 v[190:193], v169 offset:50176
	ds_read_b128 v[194:197], v169 offset:51200
	ds_read_b128 v[198:201], v169 offset:52224
	ds_read_b128 v[202:205], v169 offset:53248
	ds_read_b128 v[206:209], v169 offset:54272
	ds_read_b128 v[210:213], v169 offset:55296
	ds_read_b128 v[214:217], v169 offset:56320
	global_load_lds_dwordx4 v[162:163], off
	s_add_i32 m0, s36, 0x2000
	s_add_u32 s36, s44, 0x158080
	v_lshl_add_u64 v[162:163], v[218:219], 0, s[14:15]
	s_addc_u32 s37, s45, 0
	s_add_i32 s44, s79, s51
	global_load_lds_dwordx4 v[162:163], off
	v_lshl_add_u64 v[162:163], s[36:37], 0, v[150:151]
	s_mov_b32 m0, s44
	s_nop 0
	global_load_lds_dwordx4 v[162:163], off
	v_lshl_add_u64 v[162:163], s[36:37], 0, v[146:147]
	s_add_i32 m0, s44, 0x2000
	s_nop 0
	global_load_lds_dwordx4 v[162:163], off
	v_lshl_add_u64 v[162:163], v[220:221], 0, s[14:15]
	s_mov_b32 m0, s59
	s_nop 0
	global_load_lds_dwordx4 v[162:163], off
	v_lshl_add_u64 v[162:163], v[222:223], 0, s[14:15]
	s_mov_b32 m0, s60
	s_nop 0
	global_load_lds_dwordx4 v[162:163], off
	s_waitcnt vmcnt(8) lgkmcnt(0)
	s_barrier
	v_mfma_i32_16x16x64_i8 v[62:65], v[130:133], v[186:189], v[62:65]
	v_mfma_i32_16x16x64_i8 v[58:61], v[138:141], v[186:189], v[58:61]
	v_mfma_i32_16x16x64_i8 v[46:49], v[130:133], v[194:197], v[46:49]
	v_mfma_i32_16x16x64_i8 v[42:45], v[138:141], v[194:197], v[42:45]
	v_mfma_i32_16x16x64_i8 v[30:33], v[130:133], v[202:205], v[30:33]
	v_mfma_i32_16x16x64_i8 v[26:29], v[138:141], v[202:205], v[26:29]
	v_mfma_i32_16x16x64_i8 v[14:17], v[130:133], v[210:213], v[14:17]
	v_mfma_i32_16x16x64_i8 v[10:13], v[138:141], v[210:213], v[10:13]
	v_mfma_i32_16x16x64_i8 v[62:65], v[134:137], v[190:193], v[62:65]
	v_mfma_i32_16x16x64_i8 v[58:61], v[142:145], v[190:193], v[58:61]
	v_mfma_i32_16x16x64_i8 v[46:49], v[134:137], v[198:201], v[46:49]
	v_mfma_i32_16x16x64_i8 v[42:45], v[142:145], v[198:201], v[42:45]
	v_mfma_i32_16x16x64_i8 v[30:33], v[134:137], v[206:209], v[30:33]
	v_mfma_i32_16x16x64_i8 v[26:29], v[142:145], v[206:209], v[26:29]
	v_mfma_i32_16x16x64_i8 v[14:17], v[134:137], v[214:217], v[14:17]
	v_mfma_i32_16x16x64_i8 v[10:13], v[142:145], v[214:217], v[10:13]
	v_mfma_i32_16x16x64_i8 v[54:57], v[170:173], v[186:189], v[54:57]
	v_mfma_i32_16x16x64_i8 v[50:53], v[178:181], v[186:189], v[50:53]
	v_mfma_i32_16x16x64_i8 v[38:41], v[170:173], v[194:197], v[38:41]
	v_mfma_i32_16x16x64_i8 v[34:37], v[178:181], v[194:197], v[34:37]
	v_mfma_i32_16x16x64_i8 v[22:25], v[170:173], v[202:205], v[22:25]
	v_mfma_i32_16x16x64_i8 v[18:21], v[178:181], v[202:205], v[18:21]
	v_mfma_i32_16x16x64_i8 v[6:9], v[170:173], v[210:213], v[6:9]
	v_mfma_i32_16x16x64_i8 v[2:5], v[178:181], v[210:213], v[2:5]
	v_mfma_i32_16x16x64_i8 v[54:57], v[174:177], v[190:193], v[54:57]
	v_mfma_i32_16x16x64_i8 v[50:53], v[182:185], v[190:193], v[50:53]
	v_mfma_i32_16x16x64_i8 v[38:41], v[174:177], v[198:201], v[38:41]
	v_mfma_i32_16x16x64_i8 v[34:37], v[182:185], v[198:201], v[34:37]
	v_mfma_i32_16x16x64_i8 v[22:25], v[174:177], v[206:209], v[22:25]
	v_mfma_i32_16x16x64_i8 v[18:21], v[182:185], v[206:209], v[18:21]
	v_mfma_i32_16x16x64_i8 v[6:9], v[174:177], v[214:217], v[6:9]
	v_mfma_i32_16x16x64_i8 v[2:5], v[182:185], v[214:217], v[2:5]
	s_barrier
	s_add_i32 s77, s77, 2
	s_add_u32 s75, s75, 0x100
	s_addc_u32 s76, s76, 0
	s_cmpk_gt_u32 s77, 0x53
	s_mov_b64 s[36:37], s[38:39]
	s_cbranch_scc0 .LBB0_1951
	s_setprio 0
	s_and_b64 vcc, exec, s[16:17]
	s_cbranch_vccz .LBB0_1954
	s_barrier
